# GEMM loader: m0 wait states filled with the segment's own ds_reads instead of s_nop; merged/removed redundant waitcnts
# speedup vs baseline: 1.0047x; 1.0047x over previous
; #define PG8_STAGE(bufoff, gbase, voff) do { _Pragma("unroll") for (int _i = 0; _i < 2; ++_i) \
;         __builtin_amdgcn_global_load_lds((const unsigned*)((const char*)(gbase) + (voff)[_i]), (PG8_LAS unsigned*)(lds + (bufoff) + ldsw + _i * 8192), 16, 0, 0); } while (0)
; #define PG8_LDA(dst, b, h) do { _Pragma("unroll") for (int m = 0; m < 4; ++m) _Pragma("unroll") for (int k = 0; k < 2; ++k) dst[m][k] = *(const PG8_LAS bf16x8*)(lds + PG8_SA(b, h) + aoff + m * 2048 + k * 1024); } while (0)
; #define PG8_LDB(dst, b, h) do { _Pragma("unroll") for (int n = 0; n < 2; ++n) _Pragma("unroll") for (int k = 0; k < 2; ++k) dst[n][k] = *(const PG8_LAS bf16x8*)(lds + PG8_SB(b, h) + boff + n * 2048 + k * 1024); } while (0)
; #define PG8_MMA(ai, bj, At, Bt) do { __builtin_amdgcn_s_setprio(1); _Pragma("unroll") for (int m = 0; m < 4; ++m) _Pragma("unroll") for (int n = 0; n < 2; ++n) _Pragma("unroll") for (int k = 0; k < 2; ++k) \
;         acc[ai][bj][m][n] = __builtin_amdgcn_mfma_f32_16x16x32_bf16(Bt[n][k], At[m][k], acc[ai][bj][m][n], 0, 0, 0); __builtin_amdgcn_s_setprio(0); } while (0)
; #define PG8_WAIT_V(n) asm volatile("s_waitcnt vmcnt(" #n ")" ::: "memory")
; #define PG8_WAIT_L(n) asm volatile("s_waitcnt lgkmcnt(" #n ")" ::: "memory")
; #define PG8_BAR __builtin_amdgcn_s_barrier()
; #define PG8_SCHED __builtin_amdgcn_sched_barrier(0)
; template <class Epi, class Sched, bool ALIGN_EPI = false, bool SP2 = false>
; __device__ __forceinline__ void gemm_phase(PG8_LAS unsigned char* lds, const Gemm g, const Sched& S, const Epi& E) {
;     ...
;             PG8_LDB(B0, 0, 0); PG8_LDB(B1, 0, 1); PG8_SCHED; PG8_LDA(At, 0, 0); PG8_STAGE(PG8_SA(1, 1), a1 + hstep, voffA);
;             PG8_WAIT_V(8); PG8_WAIT_L(0); PG8_BAR; PG8_MMA(0, 0, At, B0); PG8_MMA(0, 1, At, B1); PG8_BAR; PG8_SCHED;
;             PG8_LDA(At, 0, 1); PG8_STAGE(PG8_SB(0, 0), b2, voffB); PG8_STAGE(PG8_SB(0, 1), b2 + hstep, voffB); PG8_STAGE(PG8_SA(0, 0), a2, voffA);
;             PG8_WAIT_V(8); PG8_WAIT_L(0); PG8_BAR; PG8_MMA(1, 0, At, B0); PG8_MMA(1, 1, At, B1); PG8_BAR; PG8_SCHED;
.LBB0_673:
	ds_read_b128 v[148:151], v241 offset:0
	ds_read_b128 v[156:159], v241 offset:1024
	ds_read_b128 v[166:169], v241 offset:2048
	ds_read_b128 v[170:173], v241 offset:3072
	ds_read_b128 v[174:177], v241 offset:16384
	ds_read_b128 v[178:181], v241 offset:17408
	ds_read_b128 v[182:185], v241 offset:18432
	ds_read_b128 v[186:189], v241 offset:19456
	s_add_u32 s20, s22, 0xfff00080
	s_addc_u32 s21, s23, -1
	s_cmp_eq_u32 s35, 60
	s_cselect_b32 s25, s11, s21
	s_cselect_b32 s24, s52, s20
	s_cselect_b32 s21, s13, s34
	s_cselect_b32 s20, s53, s62
	s_add_i32 m0, s19, 0xc000
	ds_read_b128 v[190:193], v161
	ds_read_b128 v[194:197], v161 offset:1024
	ds_read_b128 v[198:201], v161 offset:2048
	ds_read_b128 v[202:205], v161 offset:3072
	ds_read_b128 v[206:209], v161 offset:4096
	ds_read_b128 v[210:213], v161 offset:5120
	ds_read_b128 v[214:217], v161 offset:6144
	global_load_lds_dwordx4 v138, s[22:23]
	s_add_i32 m0, s19, 0xe000
	ds_read_b128 v[218:221], v161 offset:7168
	global_load_lds_dwordx4 v140, s[22:23]
	s_waitcnt vmcnt(8) lgkmcnt(0)
	s_barrier
	v_mfma_f32_16x16x32_bf16 v[118:121], v[148:151], v[190:193], v[118:121]
	v_mfma_f32_16x16x32_bf16 v[114:117], v[166:169], v[190:193], v[114:117]
	v_mfma_f32_16x16x32_bf16 v[102:105], v[148:151], v[198:201], v[102:105]
	v_mfma_f32_16x16x32_bf16 v[98:101], v[166:169], v[198:201], v[98:101]
	v_mfma_f32_16x16x32_bf16 v[86:89], v[148:151], v[206:209], v[86:89]
	v_mfma_f32_16x16x32_bf16 v[82:85], v[166:169], v[206:209], v[82:85]
	v_mfma_f32_16x16x32_bf16 v[70:73], v[148:151], v[214:217], v[70:73]
	v_mfma_f32_16x16x32_bf16 v[66:69], v[166:169], v[214:217], v[66:69]
	v_mfma_f32_16x16x32_bf16 v[118:121], v[156:159], v[194:197], v[118:121]
	v_mfma_f32_16x16x32_bf16 v[114:117], v[170:173], v[194:197], v[114:117]
	v_mfma_f32_16x16x32_bf16 v[102:105], v[156:159], v[202:205], v[102:105]
	v_mfma_f32_16x16x32_bf16 v[98:101], v[170:173], v[202:205], v[98:101]
	v_mfma_f32_16x16x32_bf16 v[86:89], v[156:159], v[210:213], v[86:89]
	v_mfma_f32_16x16x32_bf16 v[82:85], v[170:173], v[210:213], v[82:85]
	v_mfma_f32_16x16x32_bf16 v[70:73], v[156:159], v[218:221], v[70:73]
	v_mfma_f32_16x16x32_bf16 v[66:69], v[170:173], v[218:221], v[66:69]
	v_mfma_f32_16x16x32_bf16 v[126:129], v[174:177], v[190:193], v[126:129]
	v_mfma_f32_16x16x32_bf16 v[122:125], v[182:185], v[190:193], v[122:125]
	v_mfma_f32_16x16x32_bf16 v[110:113], v[174:177], v[198:201], v[110:113]
	v_mfma_f32_16x16x32_bf16 v[106:109], v[182:185], v[198:201], v[106:109]
	v_mfma_f32_16x16x32_bf16 v[94:97], v[174:177], v[206:209], v[94:97]
	v_mfma_f32_16x16x32_bf16 v[90:93], v[182:185], v[206:209], v[90:93]
	v_mfma_f32_16x16x32_bf16 v[78:81], v[174:177], v[214:217], v[78:81]
	v_mfma_f32_16x16x32_bf16 v[74:77], v[182:185], v[214:217], v[74:77]
	v_mfma_f32_16x16x32_bf16 v[126:129], v[178:181], v[194:197], v[126:129]
	v_mfma_f32_16x16x32_bf16 v[122:125], v[186:189], v[194:197], v[122:125]
	v_mfma_f32_16x16x32_bf16 v[110:113], v[178:181], v[202:205], v[110:113]
	v_mfma_f32_16x16x32_bf16 v[106:109], v[186:189], v[202:205], v[106:109]
	v_mfma_f32_16x16x32_bf16 v[94:97], v[178:181], v[210:213], v[94:97]
	v_mfma_f32_16x16x32_bf16 v[90:93], v[186:189], v[210:213], v[90:93]
	v_mfma_f32_16x16x32_bf16 v[78:81], v[178:181], v[218:221], v[78:81]
	v_mfma_f32_16x16x32_bf16 v[74:77], v[186:189], v[218:221], v[74:77]
	s_barrier
	s_add_i32 s63, s43, s26
	s_mov_b32 m0, s63
	ds_read_b128 v[190:193], v161 offset:16384
	ds_read_b128 v[194:197], v161 offset:17408
	ds_read_b128 v[198:201], v161 offset:18432
	ds_read_b128 v[202:205], v161 offset:19456
	ds_read_b128 v[206:209], v161 offset:20480
	global_load_lds_dwordx4 v132, s[20:21]
	s_add_i32 m0, s63, 0x2000
	s_add_u32 s64, s20, 0x100000
	s_addc_u32 s65, s21, 0
	s_add_i32 s63, s46, s26
	global_load_lds_dwordx4 v136, s[20:21]
	s_mov_b32 m0, s63
	s_add_u32 s100, s24, 0x80
	s_addc_u32 s101, s25, 0
	global_load_lds_dwordx4 v132, s[64:65]
	s_add_i32 m0, s63, 0x2000
	ds_read_b128 v[218:221], v161 offset:23552
	global_load_lds_dwordx4 v136, s[64:65]
	s_mov_b32 m0, s19
	ds_read_b128 v[214:217], v161 offset:22528
	global_load_lds_dwordx4 v130, s[24:25]
	s_mov_b32 m0, s29
	ds_read_b128 v[210:213], v161 offset:21504
	global_load_lds_dwordx4 v134, s[24:25]
	s_waitcnt vmcnt(8) lgkmcnt(0)
	s_barrier
	v_mfma_f32_16x16x32_bf16 v[54:57], v[148:151], v[190:193], v[54:57]
	v_mfma_f32_16x16x32_bf16 v[50:53], v[166:169], v[190:193], v[50:53]
	v_mfma_f32_16x16x32_bf16 v[38:41], v[148:151], v[198:201], v[38:41]
	v_mfma_f32_16x16x32_bf16 v[34:37], v[166:169], v[198:201], v[34:37]
	v_mfma_f32_16x16x32_bf16 v[22:25], v[148:151], v[206:209], v[22:25]
	v_mfma_f32_16x16x32_bf16 v[18:21], v[166:169], v[206:209], v[18:21]
	v_mfma_f32_16x16x32_bf16 v[6:9], v[148:151], v[214:217], v[6:9]
	v_mfma_f32_16x16x32_bf16 v[2:5], v[166:169], v[214:217], v[2:5]
	v_mfma_f32_16x16x32_bf16 v[54:57], v[156:159], v[194:197], v[54:57]
	v_mfma_f32_16x16x32_bf16 v[50:53], v[170:173], v[194:197], v[50:53]
	v_mfma_f32_16x16x32_bf16 v[38:41], v[156:159], v[202:205], v[38:41]
	v_mfma_f32_16x16x32_bf16 v[34:37], v[170:173], v[202:205], v[34:37]
	v_mfma_f32_16x16x32_bf16 v[22:25], v[156:159], v[210:213], v[22:25]
	v_mfma_f32_16x16x32_bf16 v[18:21], v[170:173], v[210:213], v[18:21]
	v_mfma_f32_16x16x32_bf16 v[6:9], v[156:159], v[218:221], v[6:9]
	v_mfma_f32_16x16x32_bf16 v[2:5], v[170:173], v[218:221], v[2:5]
	v_mfma_f32_16x16x32_bf16 v[62:65], v[174:177], v[190:193], v[62:65]
	v_mfma_f32_16x16x32_bf16 v[58:61], v[182:185], v[190:193], v[58:61]
	v_mfma_f32_16x16x32_bf16 v[46:49], v[174:177], v[198:201], v[46:49]
	v_mfma_f32_16x16x32_bf16 v[42:45], v[182:185], v[198:201], v[42:45]
	v_mfma_f32_16x16x32_bf16 v[30:33], v[174:177], v[206:209], v[30:33]
	v_mfma_f32_16x16x32_bf16 v[26:29], v[182:185], v[206:209], v[26:29]
	v_mfma_f32_16x16x32_bf16 v[10:13], v[174:177], v[214:217], v[10:13]
	v_mfma_f32_16x16x32_bf16 v[14:17], v[182:185], v[214:217], v[14:17]
	v_mfma_f32_16x16x32_bf16 v[62:65], v[178:181], v[194:197], v[62:65]
	v_mfma_f32_16x16x32_bf16 v[58:61], v[186:189], v[194:197], v[58:61]
	v_mfma_f32_16x16x32_bf16 v[46:49], v[178:181], v[202:205], v[46:49]
	v_mfma_f32_16x16x32_bf16 v[42:45], v[186:189], v[202:205], v[42:45]
	v_mfma_f32_16x16x32_bf16 v[30:33], v[178:181], v[210:213], v[30:33]
	v_mfma_f32_16x16x32_bf16 v[26:29], v[186:189], v[210:213], v[26:29]
	v_mfma_f32_16x16x32_bf16 v[10:13], v[178:181], v[218:221], v[10:13]
	v_mfma_f32_16x16x32_bf16 v[14:17], v[186:189], v[218:221], v[14:17]
	s_barrier
; #define PG8_STAGE(bufoff, gbase, voff) do { _Pragma("unroll") for (int _i = 0; _i < 2; ++_i) \
;         __builtin_amdgcn_global_load_lds((const unsigned*)((const char*)(gbase) + (voff)[_i]), (PG8_LAS unsigned*)(lds + (bufoff) + ldsw + _i * 8192), 16, 0, 0); } while (0)
; #define PG8_LDA(dst, b, h) do { _Pragma("unroll") for (int m = 0; m < 4; ++m) _Pragma("unroll") for (int k = 0; k < 2; ++k) dst[m][k] = *(const PG8_LAS bf16x8*)(lds + PG8_SA(b, h) + aoff + m * 2048 + k * 1024); } while (0)
; #define PG8_LDB(dst, b, h) do { _Pragma("unroll") for (int n = 0; n < 2; ++n) _Pragma("unroll") for (int k = 0; k < 2; ++k) dst[n][k] = *(const PG8_LAS bf16x8*)(lds + PG8_SB(b, h) + boff + n * 2048 + k * 1024); } while (0)
; #define PG8_MMA(ai, bj, At, Bt) do { __builtin_amdgcn_s_setprio(1); _Pragma("unroll") for (int m = 0; m < 4; ++m) _Pragma("unroll") for (int n = 0; n < 2; ++n) _Pragma("unroll") for (int k = 0; k < 2; ++k) \
;         acc[ai][bj][m][n] = __builtin_amdgcn_mfma_f32_16x16x32_bf16(Bt[n][k], At[m][k], acc[ai][bj][m][n], 0, 0, 0); __builtin_amdgcn_s_setprio(0); } while (0)
; #define PG8_WAIT_V(n) asm volatile("s_waitcnt vmcnt(" #n ")" ::: "memory")
; #define PG8_WAIT_L(n) asm volatile("s_waitcnt lgkmcnt(" #n ")" ::: "memory")
; #define PG8_BAR __builtin_amdgcn_s_barrier()
; #define PG8_SCHED __builtin_amdgcn_sched_barrier(0)
; template <class Epi, class Sched, bool ALIGN_EPI = false, bool SP2 = false>
; __device__ __forceinline__ void gemm_phase(PG8_LAS unsigned char* lds, const Gemm g, const Sched& S, const Epi& E) {
;     ...
;             PG8_LDB(B0, 1, 0); PG8_LDB(B1, 1, 1); PG8_SCHED; PG8_LDA(At, 1, 0); PG8_STAGE(PG8_SA(0, 1), a2 + hstep, voffA);
;             PG8_WAIT_V(8); PG8_WAIT_L(0); PG8_BAR; PG8_MMA(0, 0, At, B0); PG8_MMA(0, 1, At, B1); PG8_BAR; PG8_SCHED;
;             PG8_LDA(At, 1, 1); PG8_STAGE(PG8_SB(1, 0), b3, voffB); PG8_STAGE(PG8_SB(1, 1), b3 + hstep, voffB); PG8_STAGE(PG8_SA(1, 0), a3, voffA);
;             PG8_WAIT_V(8); PG8_WAIT_L(0); PG8_BAR; PG8_MMA(1, 0, At, B0); PG8_MMA(1, 1, At, B1); PG8_BAR; PG8_SCHED;
	s_add_i32 s63, 0, 0x18000
	s_add_i32 s64, 0, 0x1c000
	ds_read_b128 v[148:151], v241 offset:32768
	ds_read_b128 v[156:159], v241 offset:33792
	ds_read_b128 v[166:169], v241 offset:34816
	ds_read_b128 v[170:173], v241 offset:35840
	ds_read_b128 v[174:177], v241 offset:49152
	ds_read_b128 v[178:181], v241 offset:50176
	ds_read_b128 v[182:185], v241 offset:51200
	ds_read_b128 v[186:189], v241 offset:52224
	s_add_u32 s24, s24, 0x100000
	s_addc_u32 s25, s25, 0
	s_mov_b32 m0, s30
	ds_read_b128 v[190:193], v161 offset:32768
	ds_read_b128 v[194:197], v161 offset:33792
	ds_read_b128 v[198:201], v161 offset:34816
	ds_read_b128 v[202:205], v161 offset:35840
	ds_read_b128 v[206:209], v161 offset:36864
	ds_read_b128 v[210:213], v161 offset:37888
	ds_read_b128 v[214:217], v161 offset:38912
	global_load_lds_dwordx4 v130, s[24:25]
	s_mov_b32 m0, s31
	ds_read_b128 v[218:221], v161 offset:39936
	global_load_lds_dwordx4 v134, s[24:25]
	s_waitcnt vmcnt(8) lgkmcnt(0)
	s_barrier
	v_mfma_f32_16x16x32_bf16 v[118:121], v[148:151], v[190:193], v[118:121]
	v_mfma_f32_16x16x32_bf16 v[114:117], v[166:169], v[190:193], v[114:117]
	v_mfma_f32_16x16x32_bf16 v[102:105], v[148:151], v[198:201], v[102:105]
	v_mfma_f32_16x16x32_bf16 v[98:101], v[166:169], v[198:201], v[98:101]
	v_mfma_f32_16x16x32_bf16 v[86:89], v[148:151], v[206:209], v[86:89]
	v_mfma_f32_16x16x32_bf16 v[82:85], v[166:169], v[206:209], v[82:85]
	v_mfma_f32_16x16x32_bf16 v[70:73], v[148:151], v[214:217], v[70:73]
	v_mfma_f32_16x16x32_bf16 v[66:69], v[166:169], v[214:217], v[66:69]
	v_mfma_f32_16x16x32_bf16 v[118:121], v[156:159], v[194:197], v[118:121]
	v_mfma_f32_16x16x32_bf16 v[114:117], v[170:173], v[194:197], v[114:117]
	v_mfma_f32_16x16x32_bf16 v[102:105], v[156:159], v[202:205], v[102:105]
	v_mfma_f32_16x16x32_bf16 v[98:101], v[170:173], v[202:205], v[98:101]
	v_mfma_f32_16x16x32_bf16 v[86:89], v[156:159], v[210:213], v[86:89]
	v_mfma_f32_16x16x32_bf16 v[82:85], v[170:173], v[210:213], v[82:85]
	v_mfma_f32_16x16x32_bf16 v[70:73], v[156:159], v[218:221], v[70:73]
	v_mfma_f32_16x16x32_bf16 v[66:69], v[170:173], v[218:221], v[66:69]
	v_mfma_f32_16x16x32_bf16 v[126:129], v[174:177], v[190:193], v[126:129]
	v_mfma_f32_16x16x32_bf16 v[122:125], v[182:185], v[190:193], v[122:125]
	v_mfma_f32_16x16x32_bf16 v[110:113], v[174:177], v[198:201], v[110:113]
	v_mfma_f32_16x16x32_bf16 v[106:109], v[182:185], v[198:201], v[106:109]
	v_mfma_f32_16x16x32_bf16 v[94:97], v[174:177], v[206:209], v[94:97]
	v_mfma_f32_16x16x32_bf16 v[90:93], v[182:185], v[206:209], v[90:93]
	v_mfma_f32_16x16x32_bf16 v[78:81], v[174:177], v[214:217], v[78:81]
	v_mfma_f32_16x16x32_bf16 v[74:77], v[182:185], v[214:217], v[74:77]
	v_mfma_f32_16x16x32_bf16 v[126:129], v[178:181], v[194:197], v[126:129]
	v_mfma_f32_16x16x32_bf16 v[122:125], v[186:189], v[194:197], v[122:125]
	v_mfma_f32_16x16x32_bf16 v[110:113], v[178:181], v[202:205], v[110:113]
	v_mfma_f32_16x16x32_bf16 v[106:109], v[186:189], v[202:205], v[106:109]
	v_mfma_f32_16x16x32_bf16 v[94:97], v[178:181], v[210:213], v[94:97]
	v_mfma_f32_16x16x32_bf16 v[90:93], v[186:189], v[210:213], v[90:93]
	v_mfma_f32_16x16x32_bf16 v[78:81], v[178:181], v[218:221], v[78:81]
	v_mfma_f32_16x16x32_bf16 v[74:77], v[186:189], v[218:221], v[74:77]
	s_barrier
	s_add_i32 s24, s63, s26
	s_add_i32 m0, s24, 0xffffff80
	ds_read_b128 v[190:193], v161 offset:49152
	ds_read_b128 v[194:197], v161 offset:50176
	ds_read_b128 v[198:201], v161 offset:51200
	ds_read_b128 v[202:205], v161 offset:52224
	global_load_lds_dwordx4 v132, s[20:21] offset:128
	s_add_i32 m0, s24, 0x1f80
	s_add_i32 s24, s64, s26
	global_load_lds_dwordx4 v136, s[20:21] offset:128
	s_add_u32 s20, s20, 0x100080
	s_addc_u32 s21, s21, 0
	s_mov_b32 m0, s24
	ds_read_b128 v[218:221], v161 offset:56320
	global_load_lds_dwordx4 v132, s[20:21]
	s_add_i32 m0, s24, 0x2000
	ds_read_b128 v[214:217], v161 offset:55296
	global_load_lds_dwordx4 v136, s[20:21]
	s_mov_b32 m0, s40
	ds_read_b128 v[210:213], v161 offset:54272
	global_load_lds_dwordx4 v130, s[100:101]
	s_mov_b32 m0, s41
	ds_read_b128 v[206:209], v161 offset:53248
	global_load_lds_dwordx4 v134, s[100:101]
	s_waitcnt vmcnt(8) lgkmcnt(0)
	s_barrier
	v_mfma_f32_16x16x32_bf16 v[54:57], v[148:151], v[190:193], v[54:57]
	v_mfma_f32_16x16x32_bf16 v[50:53], v[166:169], v[190:193], v[50:53]
	v_mfma_f32_16x16x32_bf16 v[38:41], v[148:151], v[198:201], v[38:41]
	v_mfma_f32_16x16x32_bf16 v[34:37], v[166:169], v[198:201], v[34:37]
	v_mfma_f32_16x16x32_bf16 v[22:25], v[148:151], v[206:209], v[22:25]
	v_mfma_f32_16x16x32_bf16 v[18:21], v[166:169], v[206:209], v[18:21]
	v_mfma_f32_16x16x32_bf16 v[6:9], v[148:151], v[214:217], v[6:9]
	v_mfma_f32_16x16x32_bf16 v[2:5], v[166:169], v[214:217], v[2:5]
	v_mfma_f32_16x16x32_bf16 v[54:57], v[156:159], v[194:197], v[54:57]
	v_mfma_f32_16x16x32_bf16 v[50:53], v[170:173], v[194:197], v[50:53]
	v_mfma_f32_16x16x32_bf16 v[38:41], v[156:159], v[202:205], v[38:41]
	v_mfma_f32_16x16x32_bf16 v[34:37], v[170:173], v[202:205], v[34:37]
	v_mfma_f32_16x16x32_bf16 v[22:25], v[156:159], v[210:213], v[22:25]
	v_mfma_f32_16x16x32_bf16 v[18:21], v[170:173], v[210:213], v[18:21]
	v_mfma_f32_16x16x32_bf16 v[6:9], v[156:159], v[218:221], v[6:9]
	v_mfma_f32_16x16x32_bf16 v[2:5], v[170:173], v[218:221], v[2:5]
	v_mfma_f32_16x16x32_bf16 v[62:65], v[174:177], v[190:193], v[62:65]
	v_mfma_f32_16x16x32_bf16 v[58:61], v[182:185], v[190:193], v[58:61]
	v_mfma_f32_16x16x32_bf16 v[46:49], v[174:177], v[198:201], v[46:49]
	v_mfma_f32_16x16x32_bf16 v[42:45], v[182:185], v[198:201], v[42:45]
	v_mfma_f32_16x16x32_bf16 v[30:33], v[174:177], v[206:209], v[30:33]
	v_mfma_f32_16x16x32_bf16 v[26:29], v[182:185], v[206:209], v[26:29]
	v_mfma_f32_16x16x32_bf16 v[10:13], v[174:177], v[214:217], v[10:13]
	v_mfma_f32_16x16x32_bf16 v[14:17], v[182:185], v[214:217], v[14:17]
	v_mfma_f32_16x16x32_bf16 v[62:65], v[178:181], v[194:197], v[62:65]
	v_mfma_f32_16x16x32_bf16 v[58:61], v[186:189], v[194:197], v[58:61]
	v_mfma_f32_16x16x32_bf16 v[46:49], v[178:181], v[202:205], v[46:49]
	v_mfma_f32_16x16x32_bf16 v[42:45], v[186:189], v[202:205], v[42:45]
	v_mfma_f32_16x16x32_bf16 v[30:33], v[178:181], v[210:213], v[30:33]
	v_mfma_f32_16x16x32_bf16 v[26:29], v[186:189], v[210:213], v[26:29]
	v_mfma_f32_16x16x32_bf16 v[10:13], v[178:181], v[218:221], v[10:13]
	v_mfma_f32_16x16x32_bf16 v[14:17], v[186:189], v[218:221], v[14:17]
	s_barrier
	s_add_i32 s35, s35, 2
	s_add_u32 s22, s22, 0x100
	s_addc_u32 s23, s23, 0
	s_add_u32 s62, s62, 0x100
	s_addc_u32 s34, s34, 0
	s_cmp_gt_u32 s35, 61
	s_cbranch_scc0 .LBB0_673


; #define PG8_BAR __builtin_amdgcn_s_barrier()
; template <class Epi, class Sched, bool ALIGN_EPI = false, bool SP2 = false>
; __device__ __forceinline__ void gemm_phase(PG8_LAS unsigned char* lds, const Gemm g, const Sched& S, const Epi& E) {
;     ...
;         if constexpr (ALIGN_EPI) { if (wr == 0) PG8_BAR; }
	s_and_b64 vcc, exec, s[8:9]
	s_cbranch_vccz .LBB0_676
	s_barrier

; #define PG8_STAGE(bufoff, gbase, voff) do { _Pragma("unroll") for (int _i = 0; _i < 2; ++_i) \
;         __builtin_amdgcn_global_load_lds((const unsigned*)((const char*)(gbase) + (voff)[_i]), (PG8_LAS unsigned*)(lds + (bufoff) + ldsw + _i * 8192), 16, 0, 0); } while (0)
; #define PG8_LDA(dst, b, h) do { _Pragma("unroll") for (int m = 0; m < 4; ++m) _Pragma("unroll") for (int k = 0; k < 2; ++k) dst[m][k] = *(const PG8_LAS bf16x8*)(lds + PG8_SA(b, h) + aoff + m * 2048 + k * 1024); } while (0)
; #define PG8_LDB(dst, b, h) do { _Pragma("unroll") for (int n = 0; n < 2; ++n) _Pragma("unroll") for (int k = 0; k < 2; ++k) dst[n][k] = *(const PG8_LAS bf16x8*)(lds + PG8_SB(b, h) + boff + n * 2048 + k * 1024); } while (0)
; #define PG8_MMA(ai, bj, At, Bt) do { __builtin_amdgcn_s_setprio(1); _Pragma("unroll") for (int m = 0; m < 4; ++m) _Pragma("unroll") for (int n = 0; n < 2; ++n) _Pragma("unroll") for (int k = 0; k < 2; ++k) \
;         acc[ai][bj][m][n] = __builtin_amdgcn_mfma_f32_16x16x32_bf16(Bt[n][k], At[m][k], acc[ai][bj][m][n], 0, 0, 0); __builtin_amdgcn_s_setprio(0); } while (0)
; #define PG8_WAIT_V(n) asm volatile("s_waitcnt vmcnt(" #n ")" ::: "memory")
; #define PG8_WAIT_L(n) asm volatile("s_waitcnt lgkmcnt(" #n ")" ::: "memory")
; #define PG8_BAR __builtin_amdgcn_s_barrier()
; #define PG8_SCHED __builtin_amdgcn_sched_barrier(0)
; template <class Epi, class Sched, bool ALIGN_EPI = false, bool SP2 = false>
; __device__ __forceinline__ void gemm_phase(PG8_LAS unsigned char* lds, const Gemm g, const Sched& S, const Epi& E) {
;     ...
;             PG8_LDB(B0, 0, 0); PG8_LDB(B1, 0, 1); PG8_SCHED; PG8_LDA(At, 0, 0); PG8_STAGE(PG8_SA(1, 1), a1 + hstep, voffA);
;             PG8_WAIT_V(8); PG8_WAIT_L(0); PG8_BAR; PG8_MMA(0, 0, At, B0); PG8_MMA(0, 1, At, B1); PG8_BAR; PG8_SCHED;
;             PG8_LDA(At, 0, 1); PG8_STAGE(PG8_SB(0, 0), b2, voffB); PG8_STAGE(PG8_SB(0, 1), b2 + hstep, voffB); PG8_STAGE(PG8_SA(0, 0), a2, voffA);
;             PG8_WAIT_V(8); PG8_WAIT_L(0); PG8_BAR; PG8_MMA(1, 0, At, B0); PG8_MMA(1, 1, At, B1); PG8_BAR; PG8_SCHED;
.LBB0_1039:
	ds_read_b128 v[130:133], v241 offset:0
	ds_read_b128 v[134:137], v241 offset:1024
	ds_read_b128 v[138:141], v241 offset:2048
	ds_read_b128 v[142:145], v241 offset:3072
	ds_read_b128 v[146:149], v241 offset:16384
	ds_read_b128 v[150:153], v241 offset:17408
	ds_read_b128 v[172:175], v241 offset:18432
	ds_read_b128 v[176:179], v241 offset:19456
	s_add_u32 s24, s26, 0xfff00080
	s_addc_u32 s25, s27, -1
	s_cmp_eq_u32 s68, 60
	s_cselect_b32 s29, s15, s25
	s_cselect_b32 s28, s21, s24
	s_cselect_b32 s25, s13, s67
	s_cselect_b32 s24, s65, s66
	s_add_i32 m0, s23, 0xc000
	ds_read_b128 v[180:183], v185
	ds_read_b128 v[188:191], v185 offset:1024
	ds_read_b128 v[192:195], v185 offset:2048
	ds_read_b128 v[196:199], v185 offset:3072
	ds_read_b128 v[200:203], v185 offset:4096
	ds_read_b128 v[204:207], v185 offset:5120
	ds_read_b128 v[208:211], v185 offset:6144
	global_load_lds_dwordx4 v162, s[26:27]
	s_add_i32 m0, s23, 0xe000
	ds_read_b128 v[212:215], v185 offset:7168
	global_load_lds_dwordx4 v166, s[26:27]
	s_waitcnt vmcnt(8) lgkmcnt(0)
	s_barrier
	v_mfma_f32_16x16x32_bf16 v[114:117], v[130:133], v[180:183], v[114:117]
	v_mfma_f32_16x16x32_bf16 v[118:121], v[138:141], v[180:183], v[118:121]
	v_mfma_f32_16x16x32_bf16 v[106:109], v[130:133], v[192:195], v[106:109]
	v_mfma_f32_16x16x32_bf16 v[98:101], v[138:141], v[192:195], v[98:101]
	v_mfma_f32_16x16x32_bf16 v[90:93], v[130:133], v[200:203], v[90:93]
	v_mfma_f32_16x16x32_bf16 v[82:85], v[138:141], v[200:203], v[82:85]
	v_mfma_f32_16x16x32_bf16 v[74:77], v[130:133], v[208:211], v[74:77]
	v_mfma_f32_16x16x32_bf16 v[66:69], v[138:141], v[208:211], v[66:69]
	v_mfma_f32_16x16x32_bf16 v[114:117], v[134:137], v[188:191], v[114:117]
	v_mfma_f32_16x16x32_bf16 v[118:121], v[142:145], v[188:191], v[118:121]
	v_mfma_f32_16x16x32_bf16 v[106:109], v[134:137], v[196:199], v[106:109]
	v_mfma_f32_16x16x32_bf16 v[98:101], v[142:145], v[196:199], v[98:101]
	v_mfma_f32_16x16x32_bf16 v[90:93], v[134:137], v[204:207], v[90:93]
	v_mfma_f32_16x16x32_bf16 v[82:85], v[142:145], v[204:207], v[82:85]
	v_mfma_f32_16x16x32_bf16 v[74:77], v[134:137], v[212:215], v[74:77]
	v_mfma_f32_16x16x32_bf16 v[66:69], v[142:145], v[212:215], v[66:69]
	v_mfma_f32_16x16x32_bf16 v[122:125], v[146:149], v[180:183], v[122:125]
	v_mfma_f32_16x16x32_bf16 v[126:129], v[172:175], v[180:183], v[126:129]
	v_mfma_f32_16x16x32_bf16 v[110:113], v[146:149], v[192:195], v[110:113]
	v_mfma_f32_16x16x32_bf16 v[102:105], v[172:175], v[192:195], v[102:105]
	v_mfma_f32_16x16x32_bf16 v[94:97], v[146:149], v[200:203], v[94:97]
	v_mfma_f32_16x16x32_bf16 v[86:89], v[172:175], v[200:203], v[86:89]
	v_mfma_f32_16x16x32_bf16 v[78:81], v[146:149], v[208:211], v[78:81]
	v_mfma_f32_16x16x32_bf16 v[70:73], v[172:175], v[208:211], v[70:73]
	v_mfma_f32_16x16x32_bf16 v[122:125], v[150:153], v[188:191], v[122:125]
	v_mfma_f32_16x16x32_bf16 v[126:129], v[176:179], v[188:191], v[126:129]
	v_mfma_f32_16x16x32_bf16 v[110:113], v[150:153], v[196:199], v[110:113]
	v_mfma_f32_16x16x32_bf16 v[102:105], v[176:179], v[196:199], v[102:105]
	v_mfma_f32_16x16x32_bf16 v[94:97], v[150:153], v[204:207], v[94:97]
	v_mfma_f32_16x16x32_bf16 v[86:89], v[176:179], v[204:207], v[86:89]
	v_mfma_f32_16x16x32_bf16 v[78:81], v[150:153], v[212:215], v[78:81]
	v_mfma_f32_16x16x32_bf16 v[70:73], v[176:179], v[212:215], v[70:73]
	s_barrier
	s_add_i32 s33, s62, s36
	s_mov_b32 m0, s33
	ds_read_b128 v[180:183], v185 offset:16384
	ds_read_b128 v[188:191], v185 offset:17408
	ds_read_b128 v[192:195], v185 offset:18432
	ds_read_b128 v[196:199], v185 offset:19456
	ds_read_b128 v[200:203], v185 offset:20480
	global_load_lds_dwordx4 v156, s[24:25]
	s_add_i32 m0, s33, 0x2000
	s_add_u32 s72, s24, 0x100000
	s_addc_u32 s73, s25, 0
	s_add_i32 s33, s63, s36
	global_load_lds_dwordx4 v160, s[24:25]
	s_mov_b32 m0, s33
	s_add_u32 s100, s28, 0x80
	s_addc_u32 s101, s29, 0
	global_load_lds_dwordx4 v156, s[72:73]
	s_add_i32 m0, s33, 0x2000
	ds_read_b128 v[212:215], v185 offset:23552
	global_load_lds_dwordx4 v160, s[72:73]
	s_mov_b32 m0, s23
	ds_read_b128 v[208:211], v185 offset:22528
	global_load_lds_dwordx4 v154, s[28:29]
	s_mov_b32 m0, s37
	ds_read_b128 v[204:207], v185 offset:21504
	global_load_lds_dwordx4 v158, s[28:29]
	s_waitcnt vmcnt(8) lgkmcnt(0)
	s_barrier
	v_mfma_f32_16x16x32_bf16 v[58:61], v[130:133], v[180:183], v[58:61]
	v_mfma_f32_16x16x32_bf16 v[54:57], v[138:141], v[180:183], v[54:57]
	v_mfma_f32_16x16x32_bf16 v[42:45], v[130:133], v[192:195], v[42:45]
	v_mfma_f32_16x16x32_bf16 v[34:37], v[138:141], v[192:195], v[34:37]
	v_mfma_f32_16x16x32_bf16 v[26:29], v[130:133], v[200:203], v[26:29]
	v_mfma_f32_16x16x32_bf16 v[18:21], v[138:141], v[200:203], v[18:21]
	v_mfma_f32_16x16x32_bf16 v[6:9], v[130:133], v[208:211], v[6:9]
	v_mfma_f32_16x16x32_bf16 v[2:5], v[138:141], v[208:211], v[2:5]
	v_mfma_f32_16x16x32_bf16 v[58:61], v[134:137], v[188:191], v[58:61]
	v_mfma_f32_16x16x32_bf16 v[54:57], v[142:145], v[188:191], v[54:57]
	v_mfma_f32_16x16x32_bf16 v[42:45], v[134:137], v[196:199], v[42:45]
	v_mfma_f32_16x16x32_bf16 v[34:37], v[142:145], v[196:199], v[34:37]
	v_mfma_f32_16x16x32_bf16 v[26:29], v[134:137], v[204:207], v[26:29]
	v_mfma_f32_16x16x32_bf16 v[18:21], v[142:145], v[204:207], v[18:21]
	v_mfma_f32_16x16x32_bf16 v[6:9], v[134:137], v[212:215], v[6:9]
	v_mfma_f32_16x16x32_bf16 v[2:5], v[142:145], v[212:215], v[2:5]
	v_mfma_f32_16x16x32_bf16 v[62:65], v[146:149], v[180:183], v[62:65]
	v_mfma_f32_16x16x32_bf16 v[50:53], v[172:175], v[180:183], v[50:53]
	v_mfma_f32_16x16x32_bf16 v[46:49], v[146:149], v[192:195], v[46:49]
	v_mfma_f32_16x16x32_bf16 v[38:41], v[172:175], v[192:195], v[38:41]
	v_mfma_f32_16x16x32_bf16 v[30:33], v[146:149], v[200:203], v[30:33]
	v_mfma_f32_16x16x32_bf16 v[22:25], v[172:175], v[200:203], v[22:25]
	v_mfma_f32_16x16x32_bf16 v[10:13], v[146:149], v[208:211], v[10:13]
	v_mfma_f32_16x16x32_bf16 v[14:17], v[172:175], v[208:211], v[14:17]
	v_mfma_f32_16x16x32_bf16 v[62:65], v[150:153], v[188:191], v[62:65]
	v_mfma_f32_16x16x32_bf16 v[50:53], v[176:179], v[188:191], v[50:53]
	v_mfma_f32_16x16x32_bf16 v[46:49], v[150:153], v[196:199], v[46:49]
	v_mfma_f32_16x16x32_bf16 v[38:41], v[176:179], v[196:199], v[38:41]
	v_mfma_f32_16x16x32_bf16 v[30:33], v[150:153], v[204:207], v[30:33]
	v_mfma_f32_16x16x32_bf16 v[22:25], v[176:179], v[204:207], v[22:25]
	v_mfma_f32_16x16x32_bf16 v[10:13], v[150:153], v[212:215], v[10:13]
	v_mfma_f32_16x16x32_bf16 v[14:17], v[176:179], v[212:215], v[14:17]
	s_barrier
; #define PG8_STAGE(bufoff, gbase, voff) do { _Pragma("unroll") for (int _i = 0; _i < 2; ++_i) \
;         __builtin_amdgcn_global_load_lds((const unsigned*)((const char*)(gbase) + (voff)[_i]), (PG8_LAS unsigned*)(lds + (bufoff) + ldsw + _i * 8192), 16, 0, 0); } while (0)
; #define PG8_LDA(dst, b, h) do { _Pragma("unroll") for (int m = 0; m < 4; ++m) _Pragma("unroll") for (int k = 0; k < 2; ++k) dst[m][k] = *(const PG8_LAS bf16x8*)(lds + PG8_SA(b, h) + aoff + m * 2048 + k * 1024); } while (0)
; #define PG8_LDB(dst, b, h) do { _Pragma("unroll") for (int n = 0; n < 2; ++n) _Pragma("unroll") for (int k = 0; k < 2; ++k) dst[n][k] = *(const PG8_LAS bf16x8*)(lds + PG8_SB(b, h) + boff + n * 2048 + k * 1024); } while (0)
; #define PG8_MMA(ai, bj, At, Bt) do { __builtin_amdgcn_s_setprio(1); _Pragma("unroll") for (int m = 0; m < 4; ++m) _Pragma("unroll") for (int n = 0; n < 2; ++n) _Pragma("unroll") for (int k = 0; k < 2; ++k) \
;         acc[ai][bj][m][n] = __builtin_amdgcn_mfma_f32_16x16x32_bf16(Bt[n][k], At[m][k], acc[ai][bj][m][n], 0, 0, 0); __builtin_amdgcn_s_setprio(0); } while (0)
; #define PG8_WAIT_V(n) asm volatile("s_waitcnt vmcnt(" #n ")" ::: "memory")
; #define PG8_WAIT_L(n) asm volatile("s_waitcnt lgkmcnt(" #n ")" ::: "memory")
; #define PG8_BAR __builtin_amdgcn_s_barrier()
; #define PG8_SCHED __builtin_amdgcn_sched_barrier(0)
; template <class Epi, class Sched, bool ALIGN_EPI = false, bool SP2 = false>
; __device__ __forceinline__ void gemm_phase(PG8_LAS unsigned char* lds, const Gemm g, const Sched& S, const Epi& E) {
;     ...
;             PG8_LDB(B0, 1, 0); PG8_LDB(B1, 1, 1); PG8_SCHED; PG8_LDA(At, 1, 0); PG8_STAGE(PG8_SA(0, 1), a2 + hstep, voffA);
;             PG8_WAIT_V(8); PG8_WAIT_L(0); PG8_BAR; PG8_MMA(0, 0, At, B0); PG8_MMA(0, 1, At, B1); PG8_BAR; PG8_SCHED;
;             PG8_LDA(At, 1, 1); PG8_STAGE(PG8_SB(1, 0), b3, voffB); PG8_STAGE(PG8_SB(1, 1), b3 + hstep, voffB); PG8_STAGE(PG8_SA(1, 0), a3, voffA);
;             PG8_WAIT_V(8); PG8_WAIT_L(0); PG8_BAR; PG8_MMA(1, 0, At, B0); PG8_MMA(1, 1, At, B1); PG8_BAR; PG8_SCHED;
	s_add_i32 s33, 0, 0x18000
	s_add_i32 s42, 0, 0x1c000
	ds_read_b128 v[130:133], v241 offset:32768
	ds_read_b128 v[134:137], v241 offset:33792
	ds_read_b128 v[138:141], v241 offset:34816
	ds_read_b128 v[142:145], v241 offset:35840
	ds_read_b128 v[146:149], v241 offset:49152
	ds_read_b128 v[150:153], v241 offset:50176
	ds_read_b128 v[172:175], v241 offset:51200
	ds_read_b128 v[176:179], v241 offset:52224
	s_add_u32 s28, s28, 0x100000
	s_addc_u32 s29, s29, 0
	s_mov_b32 m0, s40
	ds_read_b128 v[180:183], v185 offset:32768
	ds_read_b128 v[188:191], v185 offset:33792
	ds_read_b128 v[192:195], v185 offset:34816
	ds_read_b128 v[196:199], v185 offset:35840
	ds_read_b128 v[200:203], v185 offset:36864
	ds_read_b128 v[204:207], v185 offset:37888
	ds_read_b128 v[208:211], v185 offset:38912
	global_load_lds_dwordx4 v154, s[28:29]
	s_mov_b32 m0, s41
	ds_read_b128 v[212:215], v185 offset:39936
	global_load_lds_dwordx4 v158, s[28:29]
	s_waitcnt vmcnt(8) lgkmcnt(0)
	s_barrier
	v_mfma_f32_16x16x32_bf16 v[114:117], v[130:133], v[180:183], v[114:117]
	v_mfma_f32_16x16x32_bf16 v[118:121], v[138:141], v[180:183], v[118:121]
	v_mfma_f32_16x16x32_bf16 v[106:109], v[130:133], v[192:195], v[106:109]
	v_mfma_f32_16x16x32_bf16 v[98:101], v[138:141], v[192:195], v[98:101]
	v_mfma_f32_16x16x32_bf16 v[90:93], v[130:133], v[200:203], v[90:93]
	v_mfma_f32_16x16x32_bf16 v[82:85], v[138:141], v[200:203], v[82:85]
	v_mfma_f32_16x16x32_bf16 v[74:77], v[130:133], v[208:211], v[74:77]
	v_mfma_f32_16x16x32_bf16 v[66:69], v[138:141], v[208:211], v[66:69]
	v_mfma_f32_16x16x32_bf16 v[114:117], v[134:137], v[188:191], v[114:117]
	v_mfma_f32_16x16x32_bf16 v[118:121], v[142:145], v[188:191], v[118:121]
	v_mfma_f32_16x16x32_bf16 v[106:109], v[134:137], v[196:199], v[106:109]
	v_mfma_f32_16x16x32_bf16 v[98:101], v[142:145], v[196:199], v[98:101]
	v_mfma_f32_16x16x32_bf16 v[90:93], v[134:137], v[204:207], v[90:93]
	v_mfma_f32_16x16x32_bf16 v[82:85], v[142:145], v[204:207], v[82:85]
	v_mfma_f32_16x16x32_bf16 v[74:77], v[134:137], v[212:215], v[74:77]
	v_mfma_f32_16x16x32_bf16 v[66:69], v[142:145], v[212:215], v[66:69]
	v_mfma_f32_16x16x32_bf16 v[122:125], v[146:149], v[180:183], v[122:125]
	v_mfma_f32_16x16x32_bf16 v[126:129], v[172:175], v[180:183], v[126:129]
	v_mfma_f32_16x16x32_bf16 v[110:113], v[146:149], v[192:195], v[110:113]
	v_mfma_f32_16x16x32_bf16 v[102:105], v[172:175], v[192:195], v[102:105]
	v_mfma_f32_16x16x32_bf16 v[94:97], v[146:149], v[200:203], v[94:97]
	v_mfma_f32_16x16x32_bf16 v[86:89], v[172:175], v[200:203], v[86:89]
	v_mfma_f32_16x16x32_bf16 v[78:81], v[146:149], v[208:211], v[78:81]
	v_mfma_f32_16x16x32_bf16 v[70:73], v[172:175], v[208:211], v[70:73]
	v_mfma_f32_16x16x32_bf16 v[122:125], v[150:153], v[188:191], v[122:125]
	v_mfma_f32_16x16x32_bf16 v[126:129], v[176:179], v[188:191], v[126:129]
	v_mfma_f32_16x16x32_bf16 v[110:113], v[150:153], v[196:199], v[110:113]
	v_mfma_f32_16x16x32_bf16 v[102:105], v[176:179], v[196:199], v[102:105]
	v_mfma_f32_16x16x32_bf16 v[94:97], v[150:153], v[204:207], v[94:97]
	v_mfma_f32_16x16x32_bf16 v[86:89], v[176:179], v[204:207], v[86:89]
	v_mfma_f32_16x16x32_bf16 v[78:81], v[150:153], v[212:215], v[78:81]
	v_mfma_f32_16x16x32_bf16 v[70:73], v[176:179], v[212:215], v[70:73]
	s_barrier
	s_add_i32 s28, s33, s36
	s_add_i32 m0, s28, 0xffffff80
	ds_read_b128 v[180:183], v185 offset:49152
	ds_read_b128 v[188:191], v185 offset:50176
	ds_read_b128 v[192:195], v185 offset:51200
	ds_read_b128 v[196:199], v185 offset:52224
	global_load_lds_dwordx4 v156, s[24:25] offset:128
	s_add_i32 m0, s28, 0x1f80
	s_add_i32 s28, s42, s36
	global_load_lds_dwordx4 v160, s[24:25] offset:128
	s_add_u32 s24, s24, 0x100080
	s_addc_u32 s25, s25, 0
	s_mov_b32 m0, s28
	ds_read_b128 v[212:215], v185 offset:56320
	global_load_lds_dwordx4 v156, s[24:25]
	s_add_i32 m0, s28, 0x2000
	ds_read_b128 v[208:211], v185 offset:55296
	global_load_lds_dwordx4 v160, s[24:25]
	s_mov_b32 m0, s46
	ds_read_b128 v[204:207], v185 offset:54272
	global_load_lds_dwordx4 v154, s[100:101]
	s_mov_b32 m0, s47
	ds_read_b128 v[200:203], v185 offset:53248
	global_load_lds_dwordx4 v158, s[100:101]
	s_waitcnt vmcnt(8) lgkmcnt(0)
	s_barrier
	v_mfma_f32_16x16x32_bf16 v[58:61], v[130:133], v[180:183], v[58:61]
	v_mfma_f32_16x16x32_bf16 v[54:57], v[138:141], v[180:183], v[54:57]
	v_mfma_f32_16x16x32_bf16 v[42:45], v[130:133], v[192:195], v[42:45]
	v_mfma_f32_16x16x32_bf16 v[34:37], v[138:141], v[192:195], v[34:37]
	v_mfma_f32_16x16x32_bf16 v[26:29], v[130:133], v[200:203], v[26:29]
	v_mfma_f32_16x16x32_bf16 v[18:21], v[138:141], v[200:203], v[18:21]
	v_mfma_f32_16x16x32_bf16 v[6:9], v[130:133], v[208:211], v[6:9]
	v_mfma_f32_16x16x32_bf16 v[2:5], v[138:141], v[208:211], v[2:5]
	v_mfma_f32_16x16x32_bf16 v[58:61], v[134:137], v[188:191], v[58:61]
	v_mfma_f32_16x16x32_bf16 v[54:57], v[142:145], v[188:191], v[54:57]
	v_mfma_f32_16x16x32_bf16 v[42:45], v[134:137], v[196:199], v[42:45]
	v_mfma_f32_16x16x32_bf16 v[34:37], v[142:145], v[196:199], v[34:37]
	v_mfma_f32_16x16x32_bf16 v[26:29], v[134:137], v[204:207], v[26:29]
	v_mfma_f32_16x16x32_bf16 v[18:21], v[142:145], v[204:207], v[18:21]
	v_mfma_f32_16x16x32_bf16 v[6:9], v[134:137], v[212:215], v[6:9]
	v_mfma_f32_16x16x32_bf16 v[2:5], v[142:145], v[212:215], v[2:5]
	v_mfma_f32_16x16x32_bf16 v[62:65], v[146:149], v[180:183], v[62:65]
	v_mfma_f32_16x16x32_bf16 v[50:53], v[172:175], v[180:183], v[50:53]
	v_mfma_f32_16x16x32_bf16 v[46:49], v[146:149], v[192:195], v[46:49]
	v_mfma_f32_16x16x32_bf16 v[38:41], v[172:175], v[192:195], v[38:41]
	v_mfma_f32_16x16x32_bf16 v[30:33], v[146:149], v[200:203], v[30:33]
	v_mfma_f32_16x16x32_bf16 v[22:25], v[172:175], v[200:203], v[22:25]
	v_mfma_f32_16x16x32_bf16 v[10:13], v[146:149], v[208:211], v[10:13]
	v_mfma_f32_16x16x32_bf16 v[14:17], v[172:175], v[208:211], v[14:17]
	v_mfma_f32_16x16x32_bf16 v[62:65], v[150:153], v[188:191], v[62:65]
	v_mfma_f32_16x16x32_bf16 v[50:53], v[176:179], v[188:191], v[50:53]
	v_mfma_f32_16x16x32_bf16 v[46:49], v[150:153], v[196:199], v[46:49]
	v_mfma_f32_16x16x32_bf16 v[38:41], v[176:179], v[196:199], v[38:41]
	v_mfma_f32_16x16x32_bf16 v[30:33], v[150:153], v[204:207], v[30:33]
	v_mfma_f32_16x16x32_bf16 v[22:25], v[176:179], v[204:207], v[22:25]
	v_mfma_f32_16x16x32_bf16 v[10:13], v[150:153], v[212:215], v[10:13]
	v_mfma_f32_16x16x32_bf16 v[14:17], v[176:179], v[212:215], v[14:17]
	s_barrier
	s_add_i32 s68, s68, 2
	s_add_u32 s26, s26, 0x100
	s_addc_u32 s27, s27, 0
	s_add_u32 s66, s66, 0x100
	s_addc_u32 s67, s67, 0
	s_cmp_gt_u32 s68, 61
	s_cbranch_scc0 .LBB0_1039


; #define PG8_BAR __builtin_amdgcn_s_barrier()
; template <class Epi, class Sched, bool ALIGN_EPI = false, bool SP2 = false>
; __device__ __forceinline__ void gemm_phase(PG8_LAS unsigned char* lds, const Gemm g, const Sched& S, const Epi& E) {
;     ...
;         if constexpr (ALIGN_EPI) { if (wr == 0) PG8_BAR; }
	s_and_b64 vcc, exec, s[10:11]
	s_cbranch_vccz .LBB0_1042
	s_barrier

; #define PG8_STAGE(bufoff, gbase, voff) do { _Pragma("unroll") for (int _i = 0; _i < 2; ++_i) \
;         __builtin_amdgcn_global_load_lds((const unsigned*)((const char*)(gbase) + (voff)[_i]), (PG8_LAS unsigned*)(lds + (bufoff) + ldsw + _i * 8192), 16, 0, 0); } while (0)
; #define PG8_LDA(dst, b, h) do { _Pragma("unroll") for (int m = 0; m < 4; ++m) _Pragma("unroll") for (int k = 0; k < 2; ++k) dst[m][k] = *(const PG8_LAS bf16x8*)(lds + PG8_SA(b, h) + aoff + m * 2048 + k * 1024); } while (0)
; #define PG8_LDB(dst, b, h) do { _Pragma("unroll") for (int n = 0; n < 2; ++n) _Pragma("unroll") for (int k = 0; k < 2; ++k) dst[n][k] = *(const PG8_LAS bf16x8*)(lds + PG8_SB(b, h) + boff + n * 2048 + k * 1024); } while (0)
; #define PG8_MMA(ai, bj, At, Bt) do { __builtin_amdgcn_s_setprio(1); _Pragma("unroll") for (int m = 0; m < 4; ++m) _Pragma("unroll") for (int n = 0; n < 2; ++n) _Pragma("unroll") for (int k = 0; k < 2; ++k) \
;         acc[ai][bj][m][n] = __builtin_amdgcn_mfma_f32_16x16x32_bf16(Bt[n][k], At[m][k], acc[ai][bj][m][n], 0, 0, 0); __builtin_amdgcn_s_setprio(0); } while (0)
; #define PG8_WAIT_V(n) asm volatile("s_waitcnt vmcnt(" #n ")" ::: "memory")
; #define PG8_WAIT_L(n) asm volatile("s_waitcnt lgkmcnt(" #n ")" ::: "memory")
; #define PG8_BAR __builtin_amdgcn_s_barrier()
; #define PG8_SCHED __builtin_amdgcn_sched_barrier(0)
; template <class Epi, class Sched, bool ALIGN_EPI = false, bool SP2 = false>
; __device__ __forceinline__ void gemm_phase(PG8_LAS unsigned char* lds, const Gemm g, const Sched& S, const Epi& E) {
;     ...
;             PG8_LDB(B0, 0, 0); PG8_LDB(B1, 0, 1); PG8_SCHED; PG8_LDA(At, 0, 0); PG8_STAGE(PG8_SA(1, 1), a1 + hstep, voffA);
;             PG8_WAIT_V(8); PG8_WAIT_L(0); PG8_BAR; PG8_MMA(0, 0, At, B0); PG8_MMA(0, 1, At, B1); PG8_BAR; PG8_SCHED;
;             PG8_LDA(At, 0, 1); PG8_STAGE(PG8_SB(0, 0), b2, voffB); PG8_STAGE(PG8_SB(0, 1), b2 + hstep, voffB); PG8_STAGE(PG8_SA(0, 0), a2, voffA);
;             PG8_WAIT_V(8); PG8_WAIT_L(0); PG8_BAR; PG8_MMA(1, 0, At, B0); PG8_MMA(1, 1, At, B1); PG8_BAR; PG8_SCHED;
.LBB0_1126:
	ds_read_b128 v[160:163], v241 offset:0
	ds_read_b128 v[166:169], v241 offset:1024
	ds_read_b128 v[170:173], v241 offset:2048
	ds_read_b128 v[174:177], v241 offset:3072
	ds_read_b128 v[178:181], v241 offset:16384
	ds_read_b128 v[182:185], v241 offset:17408
	ds_read_b128 v[186:189], v241 offset:18432
	ds_read_b128 v[190:193], v241 offset:19456
	s_add_u32 s22, s24, 0xfff00080
	s_addc_u32 s23, s25, -1
	s_cmp_eq_u32 s68, 60
	s_cselect_b32 s27, s15, s23
	s_cselect_b32 s26, s64, s22
	s_cselect_b32 s23, s13, s67
	s_cselect_b32 s22, s65, s66
	s_add_i32 m0, s21, 0xc000
	ds_read_b128 v[194:197], v155
	ds_read_b128 v[198:201], v155 offset:1024
	ds_read_b128 v[202:205], v155 offset:2048
	ds_read_b128 v[206:209], v155 offset:3072
	ds_read_b128 v[210:213], v155 offset:4096
	ds_read_b128 v[214:217], v155 offset:5120
	ds_read_b128 v[218:221], v155 offset:6144
	global_load_lds_dwordx4 v138, s[24:25]
	s_add_i32 m0, s21, 0xe000
	ds_read_b128 v[222:225], v155 offset:7168
	global_load_lds_dwordx4 v140, s[24:25]
	s_waitcnt vmcnt(8) lgkmcnt(0)
	s_barrier
	v_mfma_f32_16x16x32_bf16 v[122:125], v[160:163], v[194:197], v[122:125]
	v_mfma_f32_16x16x32_bf16 v[114:117], v[170:173], v[194:197], v[114:117]
	v_mfma_f32_16x16x32_bf16 v[106:109], v[160:163], v[202:205], v[106:109]
	v_mfma_f32_16x16x32_bf16 v[98:101], v[170:173], v[202:205], v[98:101]
	v_mfma_f32_16x16x32_bf16 v[90:93], v[160:163], v[210:213], v[90:93]
	v_mfma_f32_16x16x32_bf16 v[82:85], v[170:173], v[210:213], v[82:85]
	v_mfma_f32_16x16x32_bf16 v[74:77], v[160:163], v[218:221], v[74:77]
	v_mfma_f32_16x16x32_bf16 v[62:65], v[170:173], v[218:221], v[62:65]
	v_mfma_f32_16x16x32_bf16 v[122:125], v[166:169], v[198:201], v[122:125]
	v_mfma_f32_16x16x32_bf16 v[114:117], v[174:177], v[198:201], v[114:117]
	v_mfma_f32_16x16x32_bf16 v[106:109], v[166:169], v[206:209], v[106:109]
	v_mfma_f32_16x16x32_bf16 v[98:101], v[174:177], v[206:209], v[98:101]
	v_mfma_f32_16x16x32_bf16 v[90:93], v[166:169], v[214:217], v[90:93]
	v_mfma_f32_16x16x32_bf16 v[82:85], v[174:177], v[214:217], v[82:85]
	v_mfma_f32_16x16x32_bf16 v[74:77], v[166:169], v[222:225], v[74:77]
	v_mfma_f32_16x16x32_bf16 v[62:65], v[174:177], v[222:225], v[62:65]
	v_mfma_f32_16x16x32_bf16 v[126:129], v[178:181], v[194:197], v[126:129]
	v_mfma_f32_16x16x32_bf16 v[118:121], v[186:189], v[194:197], v[118:121]
	v_mfma_f32_16x16x32_bf16 v[110:113], v[178:181], v[202:205], v[110:113]
	v_mfma_f32_16x16x32_bf16 v[102:105], v[186:189], v[202:205], v[102:105]
	v_mfma_f32_16x16x32_bf16 v[94:97], v[178:181], v[210:213], v[94:97]
	v_mfma_f32_16x16x32_bf16 v[86:89], v[186:189], v[210:213], v[86:89]
	v_mfma_f32_16x16x32_bf16 v[78:81], v[178:181], v[218:221], v[78:81]
	v_mfma_f32_16x16x32_bf16 v[70:73], v[186:189], v[218:221], v[70:73]
	v_mfma_f32_16x16x32_bf16 v[126:129], v[182:185], v[198:201], v[126:129]
	v_mfma_f32_16x16x32_bf16 v[118:121], v[190:193], v[198:201], v[118:121]
	v_mfma_f32_16x16x32_bf16 v[110:113], v[182:185], v[206:209], v[110:113]
	v_mfma_f32_16x16x32_bf16 v[102:105], v[190:193], v[206:209], v[102:105]
	v_mfma_f32_16x16x32_bf16 v[94:97], v[182:185], v[214:217], v[94:97]
	v_mfma_f32_16x16x32_bf16 v[86:89], v[190:193], v[214:217], v[86:89]
	v_mfma_f32_16x16x32_bf16 v[78:81], v[182:185], v[222:225], v[78:81]
	v_mfma_f32_16x16x32_bf16 v[70:73], v[190:193], v[222:225], v[70:73]
	s_barrier
	s_add_i32 s33, s52, s29
	s_mov_b32 m0, s33
	ds_read_b128 v[194:197], v155 offset:16384
	ds_read_b128 v[198:201], v155 offset:17408
	ds_read_b128 v[202:205], v155 offset:18432
	ds_read_b128 v[206:209], v155 offset:19456
	ds_read_b128 v[210:213], v155 offset:20480
	global_load_lds_dwordx4 v132, s[22:23]
	s_add_i32 m0, s33, 0x2000
	s_add_u32 s72, s22, 0x100000
	s_addc_u32 s73, s23, 0
	s_add_i32 s33, s53, s29
	global_load_lds_dwordx4 v136, s[22:23]
	s_mov_b32 m0, s33
	s_add_u32 s100, s26, 0x80
	s_addc_u32 s101, s27, 0
	global_load_lds_dwordx4 v132, s[72:73]
	s_add_i32 m0, s33, 0x2000
	ds_read_b128 v[222:225], v155 offset:23552
	global_load_lds_dwordx4 v136, s[72:73]
	s_mov_b32 m0, s21
	ds_read_b128 v[218:221], v155 offset:22528
	global_load_lds_dwordx4 v130, s[26:27]
	s_mov_b32 m0, s36
	ds_read_b128 v[214:217], v155 offset:21504
	global_load_lds_dwordx4 v134, s[26:27]
	s_waitcnt vmcnt(8) lgkmcnt(0)
	s_barrier
	v_mfma_f32_16x16x32_bf16 v[58:61], v[160:163], v[194:197], v[58:61]
	v_mfma_f32_16x16x32_bf16 v[50:53], v[170:173], v[194:197], v[50:53]
	v_mfma_f32_16x16x32_bf16 v[42:45], v[160:163], v[202:205], v[42:45]
	v_mfma_f32_16x16x32_bf16 v[34:37], v[170:173], v[202:205], v[34:37]
	v_mfma_f32_16x16x32_bf16 v[26:29], v[160:163], v[210:213], v[26:29]
	v_mfma_f32_16x16x32_bf16 v[18:21], v[170:173], v[210:213], v[18:21]
	v_mfma_f32_16x16x32_bf16 v[10:13], v[160:163], v[218:221], v[10:13]
	v_mfma_f32_16x16x32_bf16 v[2:5], v[170:173], v[218:221], v[2:5]
	v_mfma_f32_16x16x32_bf16 v[58:61], v[166:169], v[198:201], v[58:61]
	v_mfma_f32_16x16x32_bf16 v[50:53], v[174:177], v[198:201], v[50:53]
	v_mfma_f32_16x16x32_bf16 v[42:45], v[166:169], v[206:209], v[42:45]
	v_mfma_f32_16x16x32_bf16 v[34:37], v[174:177], v[206:209], v[34:37]
	v_mfma_f32_16x16x32_bf16 v[26:29], v[166:169], v[214:217], v[26:29]
	v_mfma_f32_16x16x32_bf16 v[18:21], v[174:177], v[214:217], v[18:21]
	v_mfma_f32_16x16x32_bf16 v[10:13], v[166:169], v[222:225], v[10:13]
	v_mfma_f32_16x16x32_bf16 v[2:5], v[174:177], v[222:225], v[2:5]
	v_mfma_f32_16x16x32_bf16 v[66:69], v[178:181], v[194:197], v[66:69]
	v_mfma_f32_16x16x32_bf16 v[54:57], v[186:189], v[194:197], v[54:57]
	v_mfma_f32_16x16x32_bf16 v[46:49], v[178:181], v[202:205], v[46:49]
	v_mfma_f32_16x16x32_bf16 v[38:41], v[186:189], v[202:205], v[38:41]
	v_mfma_f32_16x16x32_bf16 v[30:33], v[178:181], v[210:213], v[30:33]
	v_mfma_f32_16x16x32_bf16 v[22:25], v[186:189], v[210:213], v[22:25]
	v_mfma_f32_16x16x32_bf16 v[14:17], v[178:181], v[218:221], v[14:17]
	v_mfma_f32_16x16x32_bf16 v[6:9], v[186:189], v[218:221], v[6:9]
	v_mfma_f32_16x16x32_bf16 v[66:69], v[182:185], v[198:201], v[66:69]
	v_mfma_f32_16x16x32_bf16 v[54:57], v[190:193], v[198:201], v[54:57]
	v_mfma_f32_16x16x32_bf16 v[46:49], v[182:185], v[206:209], v[46:49]
	v_mfma_f32_16x16x32_bf16 v[38:41], v[190:193], v[206:209], v[38:41]
	v_mfma_f32_16x16x32_bf16 v[30:33], v[182:185], v[214:217], v[30:33]
	v_mfma_f32_16x16x32_bf16 v[22:25], v[190:193], v[214:217], v[22:25]
	v_mfma_f32_16x16x32_bf16 v[14:17], v[182:185], v[222:225], v[14:17]
	v_mfma_f32_16x16x32_bf16 v[6:9], v[190:193], v[222:225], v[6:9]
	s_barrier
; #define PG8_STAGE(bufoff, gbase, voff) do { _Pragma("unroll") for (int _i = 0; _i < 2; ++_i) \
;         __builtin_amdgcn_global_load_lds((const unsigned*)((const char*)(gbase) + (voff)[_i]), (PG8_LAS unsigned*)(lds + (bufoff) + ldsw + _i * 8192), 16, 0, 0); } while (0)
; #define PG8_LDA(dst, b, h) do { _Pragma("unroll") for (int m = 0; m < 4; ++m) _Pragma("unroll") for (int k = 0; k < 2; ++k) dst[m][k] = *(const PG8_LAS bf16x8*)(lds + PG8_SA(b, h) + aoff + m * 2048 + k * 1024); } while (0)
; #define PG8_LDB(dst, b, h) do { _Pragma("unroll") for (int n = 0; n < 2; ++n) _Pragma("unroll") for (int k = 0; k < 2; ++k) dst[n][k] = *(const PG8_LAS bf16x8*)(lds + PG8_SB(b, h) + boff + n * 2048 + k * 1024); } while (0)
; #define PG8_MMA(ai, bj, At, Bt) do { __builtin_amdgcn_s_setprio(1); _Pragma("unroll") for (int m = 0; m < 4; ++m) _Pragma("unroll") for (int n = 0; n < 2; ++n) _Pragma("unroll") for (int k = 0; k < 2; ++k) \
;         acc[ai][bj][m][n] = __builtin_amdgcn_mfma_f32_16x16x32_bf16(Bt[n][k], At[m][k], acc[ai][bj][m][n], 0, 0, 0); __builtin_amdgcn_s_setprio(0); } while (0)
; #define PG8_WAIT_V(n) asm volatile("s_waitcnt vmcnt(" #n ")" ::: "memory")
; #define PG8_WAIT_L(n) asm volatile("s_waitcnt lgkmcnt(" #n ")" ::: "memory")
; #define PG8_BAR __builtin_amdgcn_s_barrier()
; #define PG8_SCHED __builtin_amdgcn_sched_barrier(0)
; template <class Epi, class Sched, bool ALIGN_EPI = false, bool SP2 = false>
; __device__ __forceinline__ void gemm_phase(PG8_LAS unsigned char* lds, const Gemm g, const Sched& S, const Epi& E) {
;     ...
;             PG8_LDB(B0, 1, 0); PG8_LDB(B1, 1, 1); PG8_SCHED; PG8_LDA(At, 1, 0); PG8_STAGE(PG8_SA(0, 1), a2 + hstep, voffA);
;             PG8_WAIT_V(8); PG8_WAIT_L(0); PG8_BAR; PG8_MMA(0, 0, At, B0); PG8_MMA(0, 1, At, B1); PG8_BAR; PG8_SCHED;
;             PG8_LDA(At, 1, 1); PG8_STAGE(PG8_SB(1, 0), b3, voffB); PG8_STAGE(PG8_SB(1, 1), b3 + hstep, voffB); PG8_STAGE(PG8_SA(1, 0), a3, voffA);
;             PG8_WAIT_V(8); PG8_WAIT_L(0); PG8_BAR; PG8_MMA(1, 0, At, B0); PG8_MMA(1, 1, At, B1); PG8_BAR; PG8_SCHED;
	s_add_i32 s33, 0, 0x18000
	s_add_i32 s42, 0, 0x1c000
	ds_read_b128 v[160:163], v241 offset:32768
	ds_read_b128 v[166:169], v241 offset:33792
	ds_read_b128 v[170:173], v241 offset:34816
	ds_read_b128 v[174:177], v241 offset:35840
	ds_read_b128 v[178:181], v241 offset:49152
	ds_read_b128 v[182:185], v241 offset:50176
	ds_read_b128 v[186:189], v241 offset:51200
	ds_read_b128 v[190:193], v241 offset:52224
	s_add_u32 s26, s26, 0x100000
	s_addc_u32 s27, s27, 0
	s_mov_b32 m0, s37
	ds_read_b128 v[194:197], v155 offset:32768
	ds_read_b128 v[198:201], v155 offset:33792
	ds_read_b128 v[202:205], v155 offset:34816
	ds_read_b128 v[206:209], v155 offset:35840
	ds_read_b128 v[210:213], v155 offset:36864
	ds_read_b128 v[214:217], v155 offset:37888
	ds_read_b128 v[218:221], v155 offset:38912
	global_load_lds_dwordx4 v130, s[26:27]
	s_mov_b32 m0, s40
	ds_read_b128 v[222:225], v155 offset:39936
	global_load_lds_dwordx4 v134, s[26:27]
	s_waitcnt vmcnt(8) lgkmcnt(0)
	s_barrier
	v_mfma_f32_16x16x32_bf16 v[122:125], v[160:163], v[194:197], v[122:125]
	v_mfma_f32_16x16x32_bf16 v[114:117], v[170:173], v[194:197], v[114:117]
	v_mfma_f32_16x16x32_bf16 v[106:109], v[160:163], v[202:205], v[106:109]
	v_mfma_f32_16x16x32_bf16 v[98:101], v[170:173], v[202:205], v[98:101]
	v_mfma_f32_16x16x32_bf16 v[90:93], v[160:163], v[210:213], v[90:93]
	v_mfma_f32_16x16x32_bf16 v[82:85], v[170:173], v[210:213], v[82:85]
	v_mfma_f32_16x16x32_bf16 v[74:77], v[160:163], v[218:221], v[74:77]
	v_mfma_f32_16x16x32_bf16 v[62:65], v[170:173], v[218:221], v[62:65]
	v_mfma_f32_16x16x32_bf16 v[122:125], v[166:169], v[198:201], v[122:125]
	v_mfma_f32_16x16x32_bf16 v[114:117], v[174:177], v[198:201], v[114:117]
	v_mfma_f32_16x16x32_bf16 v[106:109], v[166:169], v[206:209], v[106:109]
	v_mfma_f32_16x16x32_bf16 v[98:101], v[174:177], v[206:209], v[98:101]
	v_mfma_f32_16x16x32_bf16 v[90:93], v[166:169], v[214:217], v[90:93]
	v_mfma_f32_16x16x32_bf16 v[82:85], v[174:177], v[214:217], v[82:85]
	v_mfma_f32_16x16x32_bf16 v[74:77], v[166:169], v[222:225], v[74:77]
	v_mfma_f32_16x16x32_bf16 v[62:65], v[174:177], v[222:225], v[62:65]
	v_mfma_f32_16x16x32_bf16 v[126:129], v[178:181], v[194:197], v[126:129]
	v_mfma_f32_16x16x32_bf16 v[118:121], v[186:189], v[194:197], v[118:121]
	v_mfma_f32_16x16x32_bf16 v[110:113], v[178:181], v[202:205], v[110:113]
	v_mfma_f32_16x16x32_bf16 v[102:105], v[186:189], v[202:205], v[102:105]
	v_mfma_f32_16x16x32_bf16 v[94:97], v[178:181], v[210:213], v[94:97]
	v_mfma_f32_16x16x32_bf16 v[86:89], v[186:189], v[210:213], v[86:89]
	v_mfma_f32_16x16x32_bf16 v[78:81], v[178:181], v[218:221], v[78:81]
	v_mfma_f32_16x16x32_bf16 v[70:73], v[186:189], v[218:221], v[70:73]
	v_mfma_f32_16x16x32_bf16 v[126:129], v[182:185], v[198:201], v[126:129]
	v_mfma_f32_16x16x32_bf16 v[118:121], v[190:193], v[198:201], v[118:121]
	v_mfma_f32_16x16x32_bf16 v[110:113], v[182:185], v[206:209], v[110:113]
	v_mfma_f32_16x16x32_bf16 v[102:105], v[190:193], v[206:209], v[102:105]
	v_mfma_f32_16x16x32_bf16 v[94:97], v[182:185], v[214:217], v[94:97]
	v_mfma_f32_16x16x32_bf16 v[86:89], v[190:193], v[214:217], v[86:89]
	v_mfma_f32_16x16x32_bf16 v[78:81], v[182:185], v[222:225], v[78:81]
	v_mfma_f32_16x16x32_bf16 v[70:73], v[190:193], v[222:225], v[70:73]
	s_barrier
	s_add_i32 s26, s33, s29
	s_add_i32 m0, s26, 0xffffff80
	ds_read_b128 v[194:197], v155 offset:49152
	ds_read_b128 v[198:201], v155 offset:50176
	ds_read_b128 v[202:205], v155 offset:51200
	ds_read_b128 v[206:209], v155 offset:52224
	global_load_lds_dwordx4 v132, s[22:23] offset:128
	s_add_i32 m0, s26, 0x1f80
	s_add_i32 s26, s42, s29
	global_load_lds_dwordx4 v136, s[22:23] offset:128
	s_add_u32 s22, s22, 0x100080
	s_addc_u32 s23, s23, 0
	s_mov_b32 m0, s26
	ds_read_b128 v[222:225], v155 offset:56320
	global_load_lds_dwordx4 v132, s[22:23]
	s_add_i32 m0, s26, 0x2000
	ds_read_b128 v[218:221], v155 offset:55296
	global_load_lds_dwordx4 v136, s[22:23]
	s_mov_b32 m0, s46
	ds_read_b128 v[214:217], v155 offset:54272
	global_load_lds_dwordx4 v130, s[100:101]
	s_mov_b32 m0, s47
	ds_read_b128 v[210:213], v155 offset:53248
	global_load_lds_dwordx4 v134, s[100:101]
	s_waitcnt vmcnt(8) lgkmcnt(0)
	s_barrier
	v_mfma_f32_16x16x32_bf16 v[58:61], v[160:163], v[194:197], v[58:61]
	v_mfma_f32_16x16x32_bf16 v[50:53], v[170:173], v[194:197], v[50:53]
	v_mfma_f32_16x16x32_bf16 v[42:45], v[160:163], v[202:205], v[42:45]
	v_mfma_f32_16x16x32_bf16 v[34:37], v[170:173], v[202:205], v[34:37]
	v_mfma_f32_16x16x32_bf16 v[26:29], v[160:163], v[210:213], v[26:29]
	v_mfma_f32_16x16x32_bf16 v[18:21], v[170:173], v[210:213], v[18:21]
	v_mfma_f32_16x16x32_bf16 v[10:13], v[160:163], v[218:221], v[10:13]
	v_mfma_f32_16x16x32_bf16 v[2:5], v[170:173], v[218:221], v[2:5]
	v_mfma_f32_16x16x32_bf16 v[58:61], v[166:169], v[198:201], v[58:61]
	v_mfma_f32_16x16x32_bf16 v[50:53], v[174:177], v[198:201], v[50:53]
	v_mfma_f32_16x16x32_bf16 v[42:45], v[166:169], v[206:209], v[42:45]
	v_mfma_f32_16x16x32_bf16 v[34:37], v[174:177], v[206:209], v[34:37]
	v_mfma_f32_16x16x32_bf16 v[26:29], v[166:169], v[214:217], v[26:29]
	v_mfma_f32_16x16x32_bf16 v[18:21], v[174:177], v[214:217], v[18:21]
	v_mfma_f32_16x16x32_bf16 v[10:13], v[166:169], v[222:225], v[10:13]
	v_mfma_f32_16x16x32_bf16 v[2:5], v[174:177], v[222:225], v[2:5]
	v_mfma_f32_16x16x32_bf16 v[66:69], v[178:181], v[194:197], v[66:69]
	v_mfma_f32_16x16x32_bf16 v[54:57], v[186:189], v[194:197], v[54:57]
	v_mfma_f32_16x16x32_bf16 v[46:49], v[178:181], v[202:205], v[46:49]
	v_mfma_f32_16x16x32_bf16 v[38:41], v[186:189], v[202:205], v[38:41]
	v_mfma_f32_16x16x32_bf16 v[30:33], v[178:181], v[210:213], v[30:33]
	v_mfma_f32_16x16x32_bf16 v[22:25], v[186:189], v[210:213], v[22:25]
	v_mfma_f32_16x16x32_bf16 v[14:17], v[178:181], v[218:221], v[14:17]
	v_mfma_f32_16x16x32_bf16 v[6:9], v[186:189], v[218:221], v[6:9]
	v_mfma_f32_16x16x32_bf16 v[66:69], v[182:185], v[198:201], v[66:69]
	v_mfma_f32_16x16x32_bf16 v[54:57], v[190:193], v[198:201], v[54:57]
	v_mfma_f32_16x16x32_bf16 v[46:49], v[182:185], v[206:209], v[46:49]
	v_mfma_f32_16x16x32_bf16 v[38:41], v[190:193], v[206:209], v[38:41]
	v_mfma_f32_16x16x32_bf16 v[30:33], v[182:185], v[214:217], v[30:33]
	v_mfma_f32_16x16x32_bf16 v[22:25], v[190:193], v[214:217], v[22:25]
	v_mfma_f32_16x16x32_bf16 v[14:17], v[182:185], v[222:225], v[14:17]
	v_mfma_f32_16x16x32_bf16 v[6:9], v[190:193], v[222:225], v[6:9]
	s_barrier
	s_add_i32 s68, s68, 2
	s_add_u32 s24, s24, 0x100
	s_addc_u32 s25, s25, 0
	s_add_u32 s66, s66, 0x100
	s_addc_u32 s67, s67, 0
	s_cmp_gt_u32 s68, 61
	s_cbranch_scc0 .LBB0_1126


; #define PG8_BAR __builtin_amdgcn_s_barrier()
; template <class Epi, class Sched, bool ALIGN_EPI = false, bool SP2 = false>
; __device__ __forceinline__ void gemm_phase(PG8_LAS unsigned char* lds, const Gemm g, const Sched& S, const Epi& E) {
;     ...
;         if constexpr (ALIGN_EPI) { if (wr == 0) PG8_BAR; }
	s_and_b64 vcc, exec, s[8:9]
	s_cbranch_vccz .LBB0_1129
	s_barrier

; #define PG8_STAGE(bufoff, gbase, voff) do { _Pragma("unroll") for (int _i = 0; _i < 2; ++_i) \
;         __builtin_amdgcn_global_load_lds((const unsigned*)((const char*)(gbase) + (voff)[_i]), (PG8_LAS unsigned*)(lds + (bufoff) + ldsw + _i * 8192), 16, 0, 0); } while (0)
; #define PG8_LDA(dst, b, h) do { _Pragma("unroll") for (int m = 0; m < 4; ++m) _Pragma("unroll") for (int k = 0; k < 2; ++k) dst[m][k] = *(const PG8_LAS bf16x8*)(lds + PG8_SA(b, h) + aoff + m * 2048 + k * 1024); } while (0)
; #define PG8_LDB(dst, b, h) do { _Pragma("unroll") for (int n = 0; n < 2; ++n) _Pragma("unroll") for (int k = 0; k < 2; ++k) dst[n][k] = *(const PG8_LAS bf16x8*)(lds + PG8_SB(b, h) + boff + n * 2048 + k * 1024); } while (0)
; #define PG8_MMA(ai, bj, At, Bt) do { __builtin_amdgcn_s_setprio(1); _Pragma("unroll") for (int m = 0; m < 4; ++m) _Pragma("unroll") for (int n = 0; n < 2; ++n) _Pragma("unroll") for (int k = 0; k < 2; ++k) \
;         acc[ai][bj][m][n] = __builtin_amdgcn_mfma_f32_16x16x32_bf16(Bt[n][k], At[m][k], acc[ai][bj][m][n], 0, 0, 0); __builtin_amdgcn_s_setprio(0); } while (0)
; #define PG8_WAIT_V(n) asm volatile("s_waitcnt vmcnt(" #n ")" ::: "memory")
; #define PG8_WAIT_L(n) asm volatile("s_waitcnt lgkmcnt(" #n ")" ::: "memory")
; #define PG8_BAR __builtin_amdgcn_s_barrier()
; #define PG8_SCHED __builtin_amdgcn_sched_barrier(0)
; template <class Epi, class Sched, bool ALIGN_EPI = false, bool SP2 = false>
; __device__ __forceinline__ void gemm_phase(PG8_LAS unsigned char* lds, const Gemm g, const Sched& S, const Epi& E) {
;     ...
;             PG8_LDB(B0, 0, 0); PG8_LDB(B1, 0, 1); PG8_SCHED; PG8_LDA(At, 0, 0); PG8_STAGE(PG8_SA(1, 1), a1 + hstep, voffA);
;             PG8_WAIT_V(8); PG8_WAIT_L(0); PG8_BAR; PG8_MMA(0, 0, At, B0); PG8_MMA(0, 1, At, B1); PG8_BAR; PG8_SCHED;
;             PG8_LDA(At, 0, 1); PG8_STAGE(PG8_SB(0, 0), b2, voffB); PG8_STAGE(PG8_SB(0, 1), b2 + hstep, voffB); PG8_STAGE(PG8_SA(0, 0), a2, voffA);
;             PG8_WAIT_V(8); PG8_WAIT_L(0); PG8_BAR; PG8_MMA(1, 0, At, B0); PG8_MMA(1, 1, At, B1); PG8_BAR; PG8_SCHED;
.LBB0_1245:
	ds_read_b128 v[130:133], v241 offset:0
	ds_read_b128 v[134:137], v241 offset:1024
	ds_read_b128 v[138:141], v241 offset:2048
	ds_read_b128 v[142:145], v241 offset:3072
	ds_read_b128 v[146:149], v241 offset:16384
	ds_read_b128 v[150:153], v241 offset:17408
	ds_read_b128 v[172:175], v241 offset:18432
	ds_read_b128 v[176:179], v241 offset:19456
	s_add_u32 s16, s18, 0xffd50080
	s_addc_u32 s17, s19, -1
	s_cmpk_eq_i32 s64, 0xa8
	s_cselect_b32 s21, s5, s17
	s_cselect_b32 s20, s4, s16
	s_cselect_b32 s17, s15, s63
	s_cselect_b32 s16, s14, s62
	s_add_i32 m0, s25, 0xc000
	ds_read_b128 v[180:183], v185
	ds_read_b128 v[188:191], v185 offset:1024
	ds_read_b128 v[192:195], v185 offset:2048
	ds_read_b128 v[196:199], v185 offset:3072
	ds_read_b128 v[200:203], v185 offset:4096
	ds_read_b128 v[204:207], v185 offset:5120
	ds_read_b128 v[208:211], v185 offset:6144
	global_load_lds_dwordx4 v162, s[18:19]
	s_add_i32 m0, s25, 0xe000
	ds_read_b128 v[212:215], v185 offset:7168
	global_load_lds_dwordx4 v166, s[18:19]
	s_waitcnt vmcnt(8) lgkmcnt(0)
	s_barrier
	v_mfma_f32_16x16x32_bf16 v[114:117], v[130:133], v[180:183], v[114:117]
	v_mfma_f32_16x16x32_bf16 v[118:121], v[138:141], v[180:183], v[118:121]
	v_mfma_f32_16x16x32_bf16 v[106:109], v[130:133], v[192:195], v[106:109]
	v_mfma_f32_16x16x32_bf16 v[98:101], v[138:141], v[192:195], v[98:101]
	v_mfma_f32_16x16x32_bf16 v[90:93], v[130:133], v[200:203], v[90:93]
	v_mfma_f32_16x16x32_bf16 v[82:85], v[138:141], v[200:203], v[82:85]
	v_mfma_f32_16x16x32_bf16 v[74:77], v[130:133], v[208:211], v[74:77]
	v_mfma_f32_16x16x32_bf16 v[66:69], v[138:141], v[208:211], v[66:69]
	v_mfma_f32_16x16x32_bf16 v[114:117], v[134:137], v[188:191], v[114:117]
	v_mfma_f32_16x16x32_bf16 v[118:121], v[142:145], v[188:191], v[118:121]
	v_mfma_f32_16x16x32_bf16 v[106:109], v[134:137], v[196:199], v[106:109]
	v_mfma_f32_16x16x32_bf16 v[98:101], v[142:145], v[196:199], v[98:101]
	v_mfma_f32_16x16x32_bf16 v[90:93], v[134:137], v[204:207], v[90:93]
	v_mfma_f32_16x16x32_bf16 v[82:85], v[142:145], v[204:207], v[82:85]
	v_mfma_f32_16x16x32_bf16 v[74:77], v[134:137], v[212:215], v[74:77]
	v_mfma_f32_16x16x32_bf16 v[66:69], v[142:145], v[212:215], v[66:69]
	v_mfma_f32_16x16x32_bf16 v[122:125], v[146:149], v[180:183], v[122:125]
	v_mfma_f32_16x16x32_bf16 v[126:129], v[172:175], v[180:183], v[126:129]
	v_mfma_f32_16x16x32_bf16 v[110:113], v[146:149], v[192:195], v[110:113]
	v_mfma_f32_16x16x32_bf16 v[102:105], v[172:175], v[192:195], v[102:105]
	v_mfma_f32_16x16x32_bf16 v[94:97], v[146:149], v[200:203], v[94:97]
	v_mfma_f32_16x16x32_bf16 v[86:89], v[172:175], v[200:203], v[86:89]
	v_mfma_f32_16x16x32_bf16 v[78:81], v[146:149], v[208:211], v[78:81]
	v_mfma_f32_16x16x32_bf16 v[70:73], v[172:175], v[208:211], v[70:73]
	v_mfma_f32_16x16x32_bf16 v[122:125], v[150:153], v[188:191], v[122:125]
	v_mfma_f32_16x16x32_bf16 v[126:129], v[176:179], v[188:191], v[126:129]
	v_mfma_f32_16x16x32_bf16 v[110:113], v[150:153], v[196:199], v[110:113]
	v_mfma_f32_16x16x32_bf16 v[102:105], v[176:179], v[196:199], v[102:105]
	v_mfma_f32_16x16x32_bf16 v[94:97], v[150:153], v[204:207], v[94:97]
	v_mfma_f32_16x16x32_bf16 v[86:89], v[176:179], v[204:207], v[86:89]
	v_mfma_f32_16x16x32_bf16 v[78:81], v[150:153], v[212:215], v[78:81]
	v_mfma_f32_16x16x32_bf16 v[70:73], v[176:179], v[212:215], v[70:73]
	s_barrier
	s_add_i32 s33, s40, s24
	s_mov_b32 m0, s33
	ds_read_b128 v[180:183], v185 offset:16384
	ds_read_b128 v[188:191], v185 offset:17408
	ds_read_b128 v[192:195], v185 offset:18432
	ds_read_b128 v[196:199], v185 offset:19456
	ds_read_b128 v[200:203], v185 offset:20480
	global_load_lds_dwordx4 v156, s[16:17]
	s_add_i32 m0, s33, 0x2000
	s_add_u32 s66, s16, 0x2b0000
	s_addc_u32 s67, s17, 0
	s_add_i32 s33, s41, s24
	global_load_lds_dwordx4 v160, s[16:17]
	s_mov_b32 m0, s33
	s_add_u32 s100, s20, 0x80
	s_addc_u32 s101, s21, 0
	global_load_lds_dwordx4 v156, s[66:67]
	s_add_i32 m0, s33, 0x2000
	ds_read_b128 v[212:215], v185 offset:23552
	global_load_lds_dwordx4 v160, s[66:67]
	s_mov_b32 m0, s25
	ds_read_b128 v[208:211], v185 offset:22528
	global_load_lds_dwordx4 v154, s[20:21]
	s_mov_b32 m0, s26
	ds_read_b128 v[204:207], v185 offset:21504
	global_load_lds_dwordx4 v158, s[20:21]
	s_waitcnt vmcnt(8) lgkmcnt(0)
	s_barrier
	v_mfma_f32_16x16x32_bf16 v[58:61], v[130:133], v[180:183], v[58:61]
	v_mfma_f32_16x16x32_bf16 v[54:57], v[138:141], v[180:183], v[54:57]
	v_mfma_f32_16x16x32_bf16 v[42:45], v[130:133], v[192:195], v[42:45]
	v_mfma_f32_16x16x32_bf16 v[34:37], v[138:141], v[192:195], v[34:37]
	v_mfma_f32_16x16x32_bf16 v[26:29], v[130:133], v[200:203], v[26:29]
	v_mfma_f32_16x16x32_bf16 v[18:21], v[138:141], v[200:203], v[18:21]
	v_mfma_f32_16x16x32_bf16 v[6:9], v[130:133], v[208:211], v[6:9]
	v_mfma_f32_16x16x32_bf16 v[2:5], v[138:141], v[208:211], v[2:5]
	v_mfma_f32_16x16x32_bf16 v[58:61], v[134:137], v[188:191], v[58:61]
	v_mfma_f32_16x16x32_bf16 v[54:57], v[142:145], v[188:191], v[54:57]
	v_mfma_f32_16x16x32_bf16 v[42:45], v[134:137], v[196:199], v[42:45]
	v_mfma_f32_16x16x32_bf16 v[34:37], v[142:145], v[196:199], v[34:37]
	v_mfma_f32_16x16x32_bf16 v[26:29], v[134:137], v[204:207], v[26:29]
	v_mfma_f32_16x16x32_bf16 v[18:21], v[142:145], v[204:207], v[18:21]
	v_mfma_f32_16x16x32_bf16 v[6:9], v[134:137], v[212:215], v[6:9]
	v_mfma_f32_16x16x32_bf16 v[2:5], v[142:145], v[212:215], v[2:5]
	v_mfma_f32_16x16x32_bf16 v[62:65], v[146:149], v[180:183], v[62:65]
	v_mfma_f32_16x16x32_bf16 v[50:53], v[172:175], v[180:183], v[50:53]
	v_mfma_f32_16x16x32_bf16 v[46:49], v[146:149], v[192:195], v[46:49]
	v_mfma_f32_16x16x32_bf16 v[38:41], v[172:175], v[192:195], v[38:41]
	v_mfma_f32_16x16x32_bf16 v[30:33], v[146:149], v[200:203], v[30:33]
	v_mfma_f32_16x16x32_bf16 v[22:25], v[172:175], v[200:203], v[22:25]
	v_mfma_f32_16x16x32_bf16 v[10:13], v[146:149], v[208:211], v[10:13]
	v_mfma_f32_16x16x32_bf16 v[14:17], v[172:175], v[208:211], v[14:17]
	v_mfma_f32_16x16x32_bf16 v[62:65], v[150:153], v[188:191], v[62:65]
	v_mfma_f32_16x16x32_bf16 v[50:53], v[176:179], v[188:191], v[50:53]
	v_mfma_f32_16x16x32_bf16 v[46:49], v[150:153], v[196:199], v[46:49]
	v_mfma_f32_16x16x32_bf16 v[38:41], v[176:179], v[196:199], v[38:41]
	v_mfma_f32_16x16x32_bf16 v[30:33], v[150:153], v[204:207], v[30:33]
	v_mfma_f32_16x16x32_bf16 v[22:25], v[176:179], v[204:207], v[22:25]
	v_mfma_f32_16x16x32_bf16 v[10:13], v[150:153], v[212:215], v[10:13]
	v_mfma_f32_16x16x32_bf16 v[14:17], v[176:179], v[212:215], v[14:17]
	s_barrier
; #define PG8_STAGE(bufoff, gbase, voff) do { _Pragma("unroll") for (int _i = 0; _i < 2; ++_i) \
;         __builtin_amdgcn_global_load_lds((const unsigned*)((const char*)(gbase) + (voff)[_i]), (PG8_LAS unsigned*)(lds + (bufoff) + ldsw + _i * 8192), 16, 0, 0); } while (0)
; #define PG8_LDA(dst, b, h) do { _Pragma("unroll") for (int m = 0; m < 4; ++m) _Pragma("unroll") for (int k = 0; k < 2; ++k) dst[m][k] = *(const PG8_LAS bf16x8*)(lds + PG8_SA(b, h) + aoff + m * 2048 + k * 1024); } while (0)
; #define PG8_LDB(dst, b, h) do { _Pragma("unroll") for (int n = 0; n < 2; ++n) _Pragma("unroll") for (int k = 0; k < 2; ++k) dst[n][k] = *(const PG8_LAS bf16x8*)(lds + PG8_SB(b, h) + boff + n * 2048 + k * 1024); } while (0)
; #define PG8_MMA(ai, bj, At, Bt) do { __builtin_amdgcn_s_setprio(1); _Pragma("unroll") for (int m = 0; m < 4; ++m) _Pragma("unroll") for (int n = 0; n < 2; ++n) _Pragma("unroll") for (int k = 0; k < 2; ++k) \
;         acc[ai][bj][m][n] = __builtin_amdgcn_mfma_f32_16x16x32_bf16(Bt[n][k], At[m][k], acc[ai][bj][m][n], 0, 0, 0); __builtin_amdgcn_s_setprio(0); } while (0)
; #define PG8_WAIT_V(n) asm volatile("s_waitcnt vmcnt(" #n ")" ::: "memory")
; #define PG8_WAIT_L(n) asm volatile("s_waitcnt lgkmcnt(" #n ")" ::: "memory")
; #define PG8_BAR __builtin_amdgcn_s_barrier()
; #define PG8_SCHED __builtin_amdgcn_sched_barrier(0)
; template <class Epi, class Sched, bool ALIGN_EPI = false, bool SP2 = false>
; __device__ __forceinline__ void gemm_phase(PG8_LAS unsigned char* lds, const Gemm g, const Sched& S, const Epi& E) {
;     ...
;             PG8_LDB(B0, 1, 0); PG8_LDB(B1, 1, 1); PG8_SCHED; PG8_LDA(At, 1, 0); PG8_STAGE(PG8_SA(0, 1), a2 + hstep, voffA);
;             PG8_WAIT_V(8); PG8_WAIT_L(0); PG8_BAR; PG8_MMA(0, 0, At, B0); PG8_MMA(0, 1, At, B1); PG8_BAR; PG8_SCHED;
;             PG8_LDA(At, 1, 1); PG8_STAGE(PG8_SB(1, 0), b3, voffB); PG8_STAGE(PG8_SB(1, 1), b3 + hstep, voffB); PG8_STAGE(PG8_SA(1, 0), a3, voffA);
;             PG8_WAIT_V(8); PG8_WAIT_L(0); PG8_BAR; PG8_MMA(1, 0, At, B0); PG8_MMA(1, 1, At, B1); PG8_BAR; PG8_SCHED;
	s_add_i32 s33, 0, 0x18000
	s_add_i32 s42, 0, 0x1c000
	ds_read_b128 v[130:133], v241 offset:32768
	ds_read_b128 v[134:137], v241 offset:33792
	ds_read_b128 v[138:141], v241 offset:34816
	ds_read_b128 v[142:145], v241 offset:35840
	ds_read_b128 v[146:149], v241 offset:49152
	ds_read_b128 v[150:153], v241 offset:50176
	ds_read_b128 v[172:175], v241 offset:51200
	ds_read_b128 v[176:179], v241 offset:52224
	s_add_u32 s20, s20, 0x2b0000
	s_addc_u32 s21, s21, 0
	s_mov_b32 m0, s27
	ds_read_b128 v[180:183], v185 offset:32768
	ds_read_b128 v[188:191], v185 offset:33792
	ds_read_b128 v[192:195], v185 offset:34816
	ds_read_b128 v[196:199], v185 offset:35840
	ds_read_b128 v[200:203], v185 offset:36864
	ds_read_b128 v[204:207], v185 offset:37888
	ds_read_b128 v[208:211], v185 offset:38912
	global_load_lds_dwordx4 v154, s[20:21]
	s_mov_b32 m0, s28
	ds_read_b128 v[212:215], v185 offset:39936
	global_load_lds_dwordx4 v158, s[20:21]
	s_waitcnt vmcnt(8) lgkmcnt(0)
	s_barrier
	v_mfma_f32_16x16x32_bf16 v[114:117], v[130:133], v[180:183], v[114:117]
	v_mfma_f32_16x16x32_bf16 v[118:121], v[138:141], v[180:183], v[118:121]
	v_mfma_f32_16x16x32_bf16 v[106:109], v[130:133], v[192:195], v[106:109]
	v_mfma_f32_16x16x32_bf16 v[98:101], v[138:141], v[192:195], v[98:101]
	v_mfma_f32_16x16x32_bf16 v[90:93], v[130:133], v[200:203], v[90:93]
	v_mfma_f32_16x16x32_bf16 v[82:85], v[138:141], v[200:203], v[82:85]
	v_mfma_f32_16x16x32_bf16 v[74:77], v[130:133], v[208:211], v[74:77]
	v_mfma_f32_16x16x32_bf16 v[66:69], v[138:141], v[208:211], v[66:69]
	v_mfma_f32_16x16x32_bf16 v[114:117], v[134:137], v[188:191], v[114:117]
	v_mfma_f32_16x16x32_bf16 v[118:121], v[142:145], v[188:191], v[118:121]
	v_mfma_f32_16x16x32_bf16 v[106:109], v[134:137], v[196:199], v[106:109]
	v_mfma_f32_16x16x32_bf16 v[98:101], v[142:145], v[196:199], v[98:101]
	v_mfma_f32_16x16x32_bf16 v[90:93], v[134:137], v[204:207], v[90:93]
	v_mfma_f32_16x16x32_bf16 v[82:85], v[142:145], v[204:207], v[82:85]
	v_mfma_f32_16x16x32_bf16 v[74:77], v[134:137], v[212:215], v[74:77]
	v_mfma_f32_16x16x32_bf16 v[66:69], v[142:145], v[212:215], v[66:69]
	v_mfma_f32_16x16x32_bf16 v[122:125], v[146:149], v[180:183], v[122:125]
	v_mfma_f32_16x16x32_bf16 v[126:129], v[172:175], v[180:183], v[126:129]
	v_mfma_f32_16x16x32_bf16 v[110:113], v[146:149], v[192:195], v[110:113]
	v_mfma_f32_16x16x32_bf16 v[102:105], v[172:175], v[192:195], v[102:105]
	v_mfma_f32_16x16x32_bf16 v[94:97], v[146:149], v[200:203], v[94:97]
	v_mfma_f32_16x16x32_bf16 v[86:89], v[172:175], v[200:203], v[86:89]
	v_mfma_f32_16x16x32_bf16 v[78:81], v[146:149], v[208:211], v[78:81]
	v_mfma_f32_16x16x32_bf16 v[70:73], v[172:175], v[208:211], v[70:73]
	v_mfma_f32_16x16x32_bf16 v[122:125], v[150:153], v[188:191], v[122:125]
	v_mfma_f32_16x16x32_bf16 v[126:129], v[176:179], v[188:191], v[126:129]
	v_mfma_f32_16x16x32_bf16 v[110:113], v[150:153], v[196:199], v[110:113]
	v_mfma_f32_16x16x32_bf16 v[102:105], v[176:179], v[196:199], v[102:105]
	v_mfma_f32_16x16x32_bf16 v[94:97], v[150:153], v[204:207], v[94:97]
	v_mfma_f32_16x16x32_bf16 v[86:89], v[176:179], v[204:207], v[86:89]
	v_mfma_f32_16x16x32_bf16 v[78:81], v[150:153], v[212:215], v[78:81]
	v_mfma_f32_16x16x32_bf16 v[70:73], v[176:179], v[212:215], v[70:73]
	s_barrier
	s_add_i32 s20, s33, s24
	s_add_i32 m0, s20, 0xffffff80
	ds_read_b128 v[180:183], v185 offset:49152
	ds_read_b128 v[188:191], v185 offset:50176
	ds_read_b128 v[192:195], v185 offset:51200
	ds_read_b128 v[196:199], v185 offset:52224
	global_load_lds_dwordx4 v156, s[16:17] offset:128
	s_add_i32 m0, s20, 0x1f80
	s_add_i32 s20, s42, s24
	global_load_lds_dwordx4 v160, s[16:17] offset:128
	s_add_u32 s16, s16, 0x2b0080
	s_addc_u32 s17, s17, 0
	s_mov_b32 m0, s20
	ds_read_b128 v[212:215], v185 offset:56320
	global_load_lds_dwordx4 v156, s[16:17]
	s_add_i32 m0, s20, 0x2000
	ds_read_b128 v[208:211], v185 offset:55296
	global_load_lds_dwordx4 v160, s[16:17]
	s_mov_b32 m0, s34
	ds_read_b128 v[204:207], v185 offset:54272
	global_load_lds_dwordx4 v154, s[100:101]
	s_mov_b32 m0, s35
	ds_read_b128 v[200:203], v185 offset:53248
	global_load_lds_dwordx4 v158, s[100:101]
	s_waitcnt vmcnt(8) lgkmcnt(0)
	s_barrier
	v_mfma_f32_16x16x32_bf16 v[58:61], v[130:133], v[180:183], v[58:61]
	v_mfma_f32_16x16x32_bf16 v[54:57], v[138:141], v[180:183], v[54:57]
	v_mfma_f32_16x16x32_bf16 v[42:45], v[130:133], v[192:195], v[42:45]
	v_mfma_f32_16x16x32_bf16 v[34:37], v[138:141], v[192:195], v[34:37]
	v_mfma_f32_16x16x32_bf16 v[26:29], v[130:133], v[200:203], v[26:29]
	v_mfma_f32_16x16x32_bf16 v[18:21], v[138:141], v[200:203], v[18:21]
	v_mfma_f32_16x16x32_bf16 v[6:9], v[130:133], v[208:211], v[6:9]
	v_mfma_f32_16x16x32_bf16 v[2:5], v[138:141], v[208:211], v[2:5]
	v_mfma_f32_16x16x32_bf16 v[58:61], v[134:137], v[188:191], v[58:61]
	v_mfma_f32_16x16x32_bf16 v[54:57], v[142:145], v[188:191], v[54:57]
	v_mfma_f32_16x16x32_bf16 v[42:45], v[134:137], v[196:199], v[42:45]
	v_mfma_f32_16x16x32_bf16 v[34:37], v[142:145], v[196:199], v[34:37]
	v_mfma_f32_16x16x32_bf16 v[26:29], v[134:137], v[204:207], v[26:29]
	v_mfma_f32_16x16x32_bf16 v[18:21], v[142:145], v[204:207], v[18:21]
	v_mfma_f32_16x16x32_bf16 v[6:9], v[134:137], v[212:215], v[6:9]
	v_mfma_f32_16x16x32_bf16 v[2:5], v[142:145], v[212:215], v[2:5]
	v_mfma_f32_16x16x32_bf16 v[62:65], v[146:149], v[180:183], v[62:65]
	v_mfma_f32_16x16x32_bf16 v[50:53], v[172:175], v[180:183], v[50:53]
	v_mfma_f32_16x16x32_bf16 v[46:49], v[146:149], v[192:195], v[46:49]
	v_mfma_f32_16x16x32_bf16 v[38:41], v[172:175], v[192:195], v[38:41]
	v_mfma_f32_16x16x32_bf16 v[30:33], v[146:149], v[200:203], v[30:33]
	v_mfma_f32_16x16x32_bf16 v[22:25], v[172:175], v[200:203], v[22:25]
	v_mfma_f32_16x16x32_bf16 v[10:13], v[146:149], v[208:211], v[10:13]
	v_mfma_f32_16x16x32_bf16 v[14:17], v[172:175], v[208:211], v[14:17]
	v_mfma_f32_16x16x32_bf16 v[62:65], v[150:153], v[188:191], v[62:65]
	v_mfma_f32_16x16x32_bf16 v[50:53], v[176:179], v[188:191], v[50:53]
	v_mfma_f32_16x16x32_bf16 v[46:49], v[150:153], v[196:199], v[46:49]
	v_mfma_f32_16x16x32_bf16 v[38:41], v[176:179], v[196:199], v[38:41]
	v_mfma_f32_16x16x32_bf16 v[30:33], v[150:153], v[204:207], v[30:33]
	v_mfma_f32_16x16x32_bf16 v[22:25], v[176:179], v[204:207], v[22:25]
	v_mfma_f32_16x16x32_bf16 v[10:13], v[150:153], v[212:215], v[10:13]
	v_mfma_f32_16x16x32_bf16 v[14:17], v[176:179], v[212:215], v[14:17]
	s_barrier
	s_add_i32 s64, s64, 2
	s_add_u32 s18, s18, 0x100
	s_addc_u32 s19, s19, 0
	s_add_u32 s62, s62, 0x100
	s_addc_u32 s63, s63, 0
	s_cmpk_gt_u32 s64, 0xa9
	s_cbranch_scc0 .LBB0_1245


; #define PG8_BAR __builtin_amdgcn_s_barrier()
; template <class Epi, class Sched, bool ALIGN_EPI = false, bool SP2 = false>
; __device__ __forceinline__ void gemm_phase(PG8_LAS unsigned char* lds, const Gemm g, const Sched& S, const Epi& E) {
;     ...
;         if constexpr (ALIGN_EPI) { if (wr == 0) PG8_BAR; }
	s_and_b64 vcc, exec, s[12:13]
	s_cbranch_vccz .LBB0_1248
	s_barrier

; #define PG8_STAGE(bufoff, gbase, voff) do { _Pragma("unroll") for (int _i = 0; _i < 2; ++_i) \
;         __builtin_amdgcn_global_load_lds((const unsigned*)((const char*)(gbase) + (voff)[_i]), (PG8_LAS unsigned*)(lds + (bufoff) + ldsw + _i * 8192), 16, 0, 0); } while (0)
; #define PG8_LDA(dst, b, h) do { _Pragma("unroll") for (int m = 0; m < 4; ++m) _Pragma("unroll") for (int k = 0; k < 2; ++k) dst[m][k] = *(const PG8_LAS bf16x8*)(lds + PG8_SA(b, h) + aoff + m * 2048 + k * 1024); } while (0)
; #define PG8_LDB(dst, b, h) do { _Pragma("unroll") for (int n = 0; n < 2; ++n) _Pragma("unroll") for (int k = 0; k < 2; ++k) dst[n][k] = *(const PG8_LAS bf16x8*)(lds + PG8_SB(b, h) + boff + n * 2048 + k * 1024); } while (0)
; #define PG8_MMA(ai, bj, At, Bt) do { __builtin_amdgcn_s_setprio(1); _Pragma("unroll") for (int m = 0; m < 4; ++m) _Pragma("unroll") for (int n = 0; n < 2; ++n) _Pragma("unroll") for (int k = 0; k < 2; ++k) \
;         acc[ai][bj][m][n] = __builtin_amdgcn_mfma_f32_16x16x32_bf16(Bt[n][k], At[m][k], acc[ai][bj][m][n], 0, 0, 0); __builtin_amdgcn_s_setprio(0); } while (0)
; #define PG8_WAIT_V(n) asm volatile("s_waitcnt vmcnt(" #n ")" ::: "memory")
; #define PG8_WAIT_L(n) asm volatile("s_waitcnt lgkmcnt(" #n ")" ::: "memory")
; #define PG8_BAR __builtin_amdgcn_s_barrier()
; #define PG8_SCHED __builtin_amdgcn_sched_barrier(0)
; template <class Epi, class Sched, bool ALIGN_EPI = false, bool SP2 = false>
; __device__ __forceinline__ void gemm_phase(PG8_LAS unsigned char* lds, const Gemm g, const Sched& S, const Epi& E) {
;     ...
;             PG8_LDB(B0, 0, 0); PG8_LDB(B1, 0, 1); PG8_SCHED; PG8_LDA(At, 0, 0); PG8_STAGE(PG8_SA(1, 1), a1 + hstep, voffA);
;             PG8_WAIT_V(8); PG8_WAIT_L(0); PG8_BAR; PG8_MMA(0, 0, At, B0); PG8_MMA(0, 1, At, B1); PG8_BAR; PG8_SCHED;
;             PG8_LDA(At, 0, 1); PG8_STAGE(PG8_SB(0, 0), b2, voffB); PG8_STAGE(PG8_SB(0, 1), b2 + hstep, voffB); PG8_STAGE(PG8_SA(0, 0), a2, voffA);
;             PG8_WAIT_V(8); PG8_WAIT_L(0); PG8_BAR; PG8_MMA(1, 0, At, B0); PG8_MMA(1, 1, At, B1); PG8_BAR; PG8_SCHED;
.LBB0_1332:
	ds_read_b128 v[148:151], v241 offset:0
	ds_read_b128 v[156:159], v241 offset:1024
	ds_read_b128 v[166:169], v241 offset:2048
	ds_read_b128 v[170:173], v241 offset:3072
	ds_read_b128 v[174:177], v241 offset:16384
	ds_read_b128 v[178:181], v241 offset:17408
	ds_read_b128 v[182:185], v241 offset:18432
	ds_read_b128 v[186:189], v241 offset:19456
	s_add_u32 s20, s22, 0xfff00080
	s_addc_u32 s21, s23, -1
	s_cmp_eq_u32 s67, 60
	s_cselect_b32 s25, s13, s21
	s_cselect_b32 s24, s63, s20
	s_cselect_b32 s21, s11, s66
	s_cselect_b32 s20, s64, s65
	s_add_i32 m0, s19, 0xc000
	ds_read_b128 v[190:193], v155
	ds_read_b128 v[194:197], v155 offset:1024
	ds_read_b128 v[198:201], v155 offset:2048
	ds_read_b128 v[202:205], v155 offset:3072
	ds_read_b128 v[206:209], v155 offset:4096
	ds_read_b128 v[210:213], v155 offset:5120
	ds_read_b128 v[214:217], v155 offset:6144
	global_load_lds_dwordx4 v138, s[22:23]
	s_add_i32 m0, s19, 0xe000
	ds_read_b128 v[218:221], v155 offset:7168
	global_load_lds_dwordx4 v140, s[22:23]
	s_waitcnt vmcnt(8) lgkmcnt(0)
	s_barrier
	v_mfma_f32_16x16x32_bf16 v[118:121], v[148:151], v[190:193], v[118:121]
	v_mfma_f32_16x16x32_bf16 v[114:117], v[166:169], v[190:193], v[114:117]
	v_mfma_f32_16x16x32_bf16 v[102:105], v[148:151], v[198:201], v[102:105]
	v_mfma_f32_16x16x32_bf16 v[98:101], v[166:169], v[198:201], v[98:101]
	v_mfma_f32_16x16x32_bf16 v[86:89], v[148:151], v[206:209], v[86:89]
	v_mfma_f32_16x16x32_bf16 v[82:85], v[166:169], v[206:209], v[82:85]
	v_mfma_f32_16x16x32_bf16 v[70:73], v[148:151], v[214:217], v[70:73]
	v_mfma_f32_16x16x32_bf16 v[66:69], v[166:169], v[214:217], v[66:69]
	v_mfma_f32_16x16x32_bf16 v[118:121], v[156:159], v[194:197], v[118:121]
	v_mfma_f32_16x16x32_bf16 v[114:117], v[170:173], v[194:197], v[114:117]
	v_mfma_f32_16x16x32_bf16 v[102:105], v[156:159], v[202:205], v[102:105]
	v_mfma_f32_16x16x32_bf16 v[98:101], v[170:173], v[202:205], v[98:101]
	v_mfma_f32_16x16x32_bf16 v[86:89], v[156:159], v[210:213], v[86:89]
	v_mfma_f32_16x16x32_bf16 v[82:85], v[170:173], v[210:213], v[82:85]
	v_mfma_f32_16x16x32_bf16 v[70:73], v[156:159], v[218:221], v[70:73]
	v_mfma_f32_16x16x32_bf16 v[66:69], v[170:173], v[218:221], v[66:69]
	v_mfma_f32_16x16x32_bf16 v[126:129], v[174:177], v[190:193], v[126:129]
	v_mfma_f32_16x16x32_bf16 v[122:125], v[182:185], v[190:193], v[122:125]
	v_mfma_f32_16x16x32_bf16 v[110:113], v[174:177], v[198:201], v[110:113]
	v_mfma_f32_16x16x32_bf16 v[106:109], v[182:185], v[198:201], v[106:109]
	v_mfma_f32_16x16x32_bf16 v[94:97], v[174:177], v[206:209], v[94:97]
	v_mfma_f32_16x16x32_bf16 v[90:93], v[182:185], v[206:209], v[90:93]
	v_mfma_f32_16x16x32_bf16 v[78:81], v[174:177], v[214:217], v[78:81]
	v_mfma_f32_16x16x32_bf16 v[74:77], v[182:185], v[214:217], v[74:77]
	v_mfma_f32_16x16x32_bf16 v[126:129], v[178:181], v[194:197], v[126:129]
	v_mfma_f32_16x16x32_bf16 v[122:125], v[186:189], v[194:197], v[122:125]
	v_mfma_f32_16x16x32_bf16 v[110:113], v[178:181], v[202:205], v[110:113]
	v_mfma_f32_16x16x32_bf16 v[106:109], v[186:189], v[202:205], v[106:109]
	v_mfma_f32_16x16x32_bf16 v[94:97], v[178:181], v[210:213], v[94:97]
	v_mfma_f32_16x16x32_bf16 v[90:93], v[186:189], v[210:213], v[90:93]
	v_mfma_f32_16x16x32_bf16 v[78:81], v[178:181], v[218:221], v[78:81]
	v_mfma_f32_16x16x32_bf16 v[74:77], v[186:189], v[218:221], v[74:77]
	s_barrier
	s_add_i32 s33, s47, s28
	s_mov_b32 m0, s33
	ds_read_b128 v[190:193], v155 offset:16384
	ds_read_b128 v[194:197], v155 offset:17408
	ds_read_b128 v[198:201], v155 offset:18432
	ds_read_b128 v[202:205], v155 offset:19456
	ds_read_b128 v[206:209], v155 offset:20480
	global_load_lds_dwordx4 v132, s[20:21]
	s_add_i32 m0, s33, 0x2000
	s_add_u32 s68, s20, 0x100000
	s_addc_u32 s69, s21, 0
	s_add_i32 s33, s52, s28
	global_load_lds_dwordx4 v136, s[20:21]
	s_mov_b32 m0, s33
	s_add_u32 s100, s24, 0x80
	s_addc_u32 s101, s25, 0
	global_load_lds_dwordx4 v132, s[68:69]
	s_add_i32 m0, s33, 0x2000
	ds_read_b128 v[218:221], v155 offset:23552
	global_load_lds_dwordx4 v136, s[68:69]
	s_mov_b32 m0, s19
	ds_read_b128 v[214:217], v155 offset:22528
	global_load_lds_dwordx4 v130, s[24:25]
	s_mov_b32 m0, s35
	ds_read_b128 v[210:213], v155 offset:21504
	global_load_lds_dwordx4 v134, s[24:25]
	s_waitcnt vmcnt(8) lgkmcnt(0)
	s_barrier
	v_mfma_f32_16x16x32_bf16 v[54:57], v[148:151], v[190:193], v[54:57]
	v_mfma_f32_16x16x32_bf16 v[50:53], v[166:169], v[190:193], v[50:53]
	v_mfma_f32_16x16x32_bf16 v[38:41], v[148:151], v[198:201], v[38:41]
	v_mfma_f32_16x16x32_bf16 v[34:37], v[166:169], v[198:201], v[34:37]
	v_mfma_f32_16x16x32_bf16 v[22:25], v[148:151], v[206:209], v[22:25]
	v_mfma_f32_16x16x32_bf16 v[18:21], v[166:169], v[206:209], v[18:21]
	v_mfma_f32_16x16x32_bf16 v[6:9], v[148:151], v[214:217], v[6:9]
	v_mfma_f32_16x16x32_bf16 v[2:5], v[166:169], v[214:217], v[2:5]
	v_mfma_f32_16x16x32_bf16 v[54:57], v[156:159], v[194:197], v[54:57]
	v_mfma_f32_16x16x32_bf16 v[50:53], v[170:173], v[194:197], v[50:53]
	v_mfma_f32_16x16x32_bf16 v[38:41], v[156:159], v[202:205], v[38:41]
	v_mfma_f32_16x16x32_bf16 v[34:37], v[170:173], v[202:205], v[34:37]
	v_mfma_f32_16x16x32_bf16 v[22:25], v[156:159], v[210:213], v[22:25]
	v_mfma_f32_16x16x32_bf16 v[18:21], v[170:173], v[210:213], v[18:21]
	v_mfma_f32_16x16x32_bf16 v[6:9], v[156:159], v[218:221], v[6:9]
	v_mfma_f32_16x16x32_bf16 v[2:5], v[170:173], v[218:221], v[2:5]
	v_mfma_f32_16x16x32_bf16 v[62:65], v[174:177], v[190:193], v[62:65]
	v_mfma_f32_16x16x32_bf16 v[58:61], v[182:185], v[190:193], v[58:61]
	v_mfma_f32_16x16x32_bf16 v[46:49], v[174:177], v[198:201], v[46:49]
	v_mfma_f32_16x16x32_bf16 v[42:45], v[182:185], v[198:201], v[42:45]
	v_mfma_f32_16x16x32_bf16 v[30:33], v[174:177], v[206:209], v[30:33]
	v_mfma_f32_16x16x32_bf16 v[26:29], v[182:185], v[206:209], v[26:29]
	v_mfma_f32_16x16x32_bf16 v[10:13], v[174:177], v[214:217], v[10:13]
	v_mfma_f32_16x16x32_bf16 v[14:17], v[182:185], v[214:217], v[14:17]
	v_mfma_f32_16x16x32_bf16 v[62:65], v[178:181], v[194:197], v[62:65]
	v_mfma_f32_16x16x32_bf16 v[58:61], v[186:189], v[194:197], v[58:61]
	v_mfma_f32_16x16x32_bf16 v[46:49], v[178:181], v[202:205], v[46:49]
	v_mfma_f32_16x16x32_bf16 v[42:45], v[186:189], v[202:205], v[42:45]
	v_mfma_f32_16x16x32_bf16 v[30:33], v[178:181], v[210:213], v[30:33]
	v_mfma_f32_16x16x32_bf16 v[26:29], v[186:189], v[210:213], v[26:29]
	v_mfma_f32_16x16x32_bf16 v[10:13], v[178:181], v[218:221], v[10:13]
	v_mfma_f32_16x16x32_bf16 v[14:17], v[186:189], v[218:221], v[14:17]
	s_barrier
; #define PG8_STAGE(bufoff, gbase, voff) do { _Pragma("unroll") for (int _i = 0; _i < 2; ++_i) \
;         __builtin_amdgcn_global_load_lds((const unsigned*)((const char*)(gbase) + (voff)[_i]), (PG8_LAS unsigned*)(lds + (bufoff) + ldsw + _i * 8192), 16, 0, 0); } while (0)
; #define PG8_LDA(dst, b, h) do { _Pragma("unroll") for (int m = 0; m < 4; ++m) _Pragma("unroll") for (int k = 0; k < 2; ++k) dst[m][k] = *(const PG8_LAS bf16x8*)(lds + PG8_SA(b, h) + aoff + m * 2048 + k * 1024); } while (0)
; #define PG8_LDB(dst, b, h) do { _Pragma("unroll") for (int n = 0; n < 2; ++n) _Pragma("unroll") for (int k = 0; k < 2; ++k) dst[n][k] = *(const PG8_LAS bf16x8*)(lds + PG8_SB(b, h) + boff + n * 2048 + k * 1024); } while (0)
; #define PG8_MMA(ai, bj, At, Bt) do { __builtin_amdgcn_s_setprio(1); _Pragma("unroll") for (int m = 0; m < 4; ++m) _Pragma("unroll") for (int n = 0; n < 2; ++n) _Pragma("unroll") for (int k = 0; k < 2; ++k) \
;         acc[ai][bj][m][n] = __builtin_amdgcn_mfma_f32_16x16x32_bf16(Bt[n][k], At[m][k], acc[ai][bj][m][n], 0, 0, 0); __builtin_amdgcn_s_setprio(0); } while (0)
; #define PG8_WAIT_V(n) asm volatile("s_waitcnt vmcnt(" #n ")" ::: "memory")
; #define PG8_WAIT_L(n) asm volatile("s_waitcnt lgkmcnt(" #n ")" ::: "memory")
; #define PG8_BAR __builtin_amdgcn_s_barrier()
; #define PG8_SCHED __builtin_amdgcn_sched_barrier(0)
; template <class Epi, class Sched, bool ALIGN_EPI = false, bool SP2 = false>
; __device__ __forceinline__ void gemm_phase(PG8_LAS unsigned char* lds, const Gemm g, const Sched& S, const Epi& E) {
;     ...
;             PG8_LDB(B0, 1, 0); PG8_LDB(B1, 1, 1); PG8_SCHED; PG8_LDA(At, 1, 0); PG8_STAGE(PG8_SA(0, 1), a2 + hstep, voffA);
;             PG8_WAIT_V(8); PG8_WAIT_L(0); PG8_BAR; PG8_MMA(0, 0, At, B0); PG8_MMA(0, 1, At, B1); PG8_BAR; PG8_SCHED;
;             PG8_LDA(At, 1, 1); PG8_STAGE(PG8_SB(1, 0), b3, voffB); PG8_STAGE(PG8_SB(1, 1), b3 + hstep, voffB); PG8_STAGE(PG8_SA(1, 0), a3, voffA);
;             PG8_WAIT_V(8); PG8_WAIT_L(0); PG8_BAR; PG8_MMA(1, 0, At, B0); PG8_MMA(1, 1, At, B1); PG8_BAR; PG8_SCHED;
	s_add_i32 s33, 0, 0x18000
	s_add_i32 s42, 0, 0x1c000
	ds_read_b128 v[148:151], v241 offset:32768
	ds_read_b128 v[156:159], v241 offset:33792
	ds_read_b128 v[166:169], v241 offset:34816
	ds_read_b128 v[170:173], v241 offset:35840
	ds_read_b128 v[174:177], v241 offset:49152
	ds_read_b128 v[178:181], v241 offset:50176
	ds_read_b128 v[182:185], v241 offset:51200
	ds_read_b128 v[186:189], v241 offset:52224
	s_add_u32 s24, s24, 0x100000
	s_addc_u32 s25, s25, 0
	s_mov_b32 m0, s36
	ds_read_b128 v[190:193], v155 offset:32768
	ds_read_b128 v[194:197], v155 offset:33792
	ds_read_b128 v[198:201], v155 offset:34816
	ds_read_b128 v[202:205], v155 offset:35840
	ds_read_b128 v[206:209], v155 offset:36864
	ds_read_b128 v[210:213], v155 offset:37888
	ds_read_b128 v[214:217], v155 offset:38912
	global_load_lds_dwordx4 v130, s[24:25]
	s_mov_b32 m0, s37
	ds_read_b128 v[218:221], v155 offset:39936
	global_load_lds_dwordx4 v134, s[24:25]
	s_waitcnt vmcnt(8) lgkmcnt(0)
	s_barrier
	v_mfma_f32_16x16x32_bf16 v[118:121], v[148:151], v[190:193], v[118:121]
	v_mfma_f32_16x16x32_bf16 v[114:117], v[166:169], v[190:193], v[114:117]
	v_mfma_f32_16x16x32_bf16 v[102:105], v[148:151], v[198:201], v[102:105]
	v_mfma_f32_16x16x32_bf16 v[98:101], v[166:169], v[198:201], v[98:101]
	v_mfma_f32_16x16x32_bf16 v[86:89], v[148:151], v[206:209], v[86:89]
	v_mfma_f32_16x16x32_bf16 v[82:85], v[166:169], v[206:209], v[82:85]
	v_mfma_f32_16x16x32_bf16 v[70:73], v[148:151], v[214:217], v[70:73]
	v_mfma_f32_16x16x32_bf16 v[66:69], v[166:169], v[214:217], v[66:69]
	v_mfma_f32_16x16x32_bf16 v[118:121], v[156:159], v[194:197], v[118:121]
	v_mfma_f32_16x16x32_bf16 v[114:117], v[170:173], v[194:197], v[114:117]
	v_mfma_f32_16x16x32_bf16 v[102:105], v[156:159], v[202:205], v[102:105]
	v_mfma_f32_16x16x32_bf16 v[98:101], v[170:173], v[202:205], v[98:101]
	v_mfma_f32_16x16x32_bf16 v[86:89], v[156:159], v[210:213], v[86:89]
	v_mfma_f32_16x16x32_bf16 v[82:85], v[170:173], v[210:213], v[82:85]
	v_mfma_f32_16x16x32_bf16 v[70:73], v[156:159], v[218:221], v[70:73]
	v_mfma_f32_16x16x32_bf16 v[66:69], v[170:173], v[218:221], v[66:69]
	v_mfma_f32_16x16x32_bf16 v[126:129], v[174:177], v[190:193], v[126:129]
	v_mfma_f32_16x16x32_bf16 v[122:125], v[182:185], v[190:193], v[122:125]
	v_mfma_f32_16x16x32_bf16 v[110:113], v[174:177], v[198:201], v[110:113]
	v_mfma_f32_16x16x32_bf16 v[106:109], v[182:185], v[198:201], v[106:109]
	v_mfma_f32_16x16x32_bf16 v[94:97], v[174:177], v[206:209], v[94:97]
	v_mfma_f32_16x16x32_bf16 v[90:93], v[182:185], v[206:209], v[90:93]
	v_mfma_f32_16x16x32_bf16 v[78:81], v[174:177], v[214:217], v[78:81]
	v_mfma_f32_16x16x32_bf16 v[74:77], v[182:185], v[214:217], v[74:77]
	v_mfma_f32_16x16x32_bf16 v[126:129], v[178:181], v[194:197], v[126:129]
	v_mfma_f32_16x16x32_bf16 v[122:125], v[186:189], v[194:197], v[122:125]
	v_mfma_f32_16x16x32_bf16 v[110:113], v[178:181], v[202:205], v[110:113]
	v_mfma_f32_16x16x32_bf16 v[106:109], v[186:189], v[202:205], v[106:109]
	v_mfma_f32_16x16x32_bf16 v[94:97], v[178:181], v[210:213], v[94:97]
	v_mfma_f32_16x16x32_bf16 v[90:93], v[186:189], v[210:213], v[90:93]
	v_mfma_f32_16x16x32_bf16 v[78:81], v[178:181], v[218:221], v[78:81]
	v_mfma_f32_16x16x32_bf16 v[74:77], v[186:189], v[218:221], v[74:77]
	s_barrier
	s_add_i32 s24, s33, s28
	s_add_i32 m0, s24, 0xffffff80
	ds_read_b128 v[190:193], v155 offset:49152
	ds_read_b128 v[194:197], v155 offset:50176
	ds_read_b128 v[198:201], v155 offset:51200
	ds_read_b128 v[202:205], v155 offset:52224
	global_load_lds_dwordx4 v132, s[20:21] offset:128
	s_add_i32 m0, s24, 0x1f80
	s_add_i32 s24, s42, s28
	global_load_lds_dwordx4 v136, s[20:21] offset:128
	s_add_u32 s20, s20, 0x100080
	s_addc_u32 s21, s21, 0
	s_mov_b32 m0, s24
	ds_read_b128 v[218:221], v155 offset:56320
	global_load_lds_dwordx4 v132, s[20:21]
	s_add_i32 m0, s24, 0x2000
	ds_read_b128 v[214:217], v155 offset:55296
	global_load_lds_dwordx4 v136, s[20:21]
	s_mov_b32 m0, s43
	ds_read_b128 v[210:213], v155 offset:54272
	global_load_lds_dwordx4 v130, s[100:101]
	s_mov_b32 m0, s46
	ds_read_b128 v[206:209], v155 offset:53248
	global_load_lds_dwordx4 v134, s[100:101]
	s_waitcnt vmcnt(8) lgkmcnt(0)
	s_barrier
	v_mfma_f32_16x16x32_bf16 v[54:57], v[148:151], v[190:193], v[54:57]
	v_mfma_f32_16x16x32_bf16 v[50:53], v[166:169], v[190:193], v[50:53]
	v_mfma_f32_16x16x32_bf16 v[38:41], v[148:151], v[198:201], v[38:41]
	v_mfma_f32_16x16x32_bf16 v[34:37], v[166:169], v[198:201], v[34:37]
	v_mfma_f32_16x16x32_bf16 v[22:25], v[148:151], v[206:209], v[22:25]
	v_mfma_f32_16x16x32_bf16 v[18:21], v[166:169], v[206:209], v[18:21]
	v_mfma_f32_16x16x32_bf16 v[6:9], v[148:151], v[214:217], v[6:9]
	v_mfma_f32_16x16x32_bf16 v[2:5], v[166:169], v[214:217], v[2:5]
	v_mfma_f32_16x16x32_bf16 v[54:57], v[156:159], v[194:197], v[54:57]
	v_mfma_f32_16x16x32_bf16 v[50:53], v[170:173], v[194:197], v[50:53]
	v_mfma_f32_16x16x32_bf16 v[38:41], v[156:159], v[202:205], v[38:41]
	v_mfma_f32_16x16x32_bf16 v[34:37], v[170:173], v[202:205], v[34:37]
	v_mfma_f32_16x16x32_bf16 v[22:25], v[156:159], v[210:213], v[22:25]
	v_mfma_f32_16x16x32_bf16 v[18:21], v[170:173], v[210:213], v[18:21]
	v_mfma_f32_16x16x32_bf16 v[6:9], v[156:159], v[218:221], v[6:9]
	v_mfma_f32_16x16x32_bf16 v[2:5], v[170:173], v[218:221], v[2:5]
	v_mfma_f32_16x16x32_bf16 v[62:65], v[174:177], v[190:193], v[62:65]
	v_mfma_f32_16x16x32_bf16 v[58:61], v[182:185], v[190:193], v[58:61]
	v_mfma_f32_16x16x32_bf16 v[46:49], v[174:177], v[198:201], v[46:49]
	v_mfma_f32_16x16x32_bf16 v[42:45], v[182:185], v[198:201], v[42:45]
	v_mfma_f32_16x16x32_bf16 v[30:33], v[174:177], v[206:209], v[30:33]
	v_mfma_f32_16x16x32_bf16 v[26:29], v[182:185], v[206:209], v[26:29]
	v_mfma_f32_16x16x32_bf16 v[10:13], v[174:177], v[214:217], v[10:13]
	v_mfma_f32_16x16x32_bf16 v[14:17], v[182:185], v[214:217], v[14:17]
	v_mfma_f32_16x16x32_bf16 v[62:65], v[178:181], v[194:197], v[62:65]
	v_mfma_f32_16x16x32_bf16 v[58:61], v[186:189], v[194:197], v[58:61]
	v_mfma_f32_16x16x32_bf16 v[46:49], v[178:181], v[202:205], v[46:49]
	v_mfma_f32_16x16x32_bf16 v[42:45], v[186:189], v[202:205], v[42:45]
	v_mfma_f32_16x16x32_bf16 v[30:33], v[178:181], v[210:213], v[30:33]
	v_mfma_f32_16x16x32_bf16 v[26:29], v[186:189], v[210:213], v[26:29]
	v_mfma_f32_16x16x32_bf16 v[10:13], v[178:181], v[218:221], v[10:13]
	v_mfma_f32_16x16x32_bf16 v[14:17], v[186:189], v[218:221], v[14:17]
	s_barrier
	s_add_i32 s67, s67, 2
	s_add_u32 s22, s22, 0x100
	s_addc_u32 s23, s23, 0
	s_add_u32 s65, s65, 0x100
	s_addc_u32 s66, s66, 0
	s_cmp_gt_u32 s67, 61
	s_cbranch_scc0 .LBB0_1332


; #define PG8_BAR __builtin_amdgcn_s_barrier()
; template <class Epi, class Sched, bool ALIGN_EPI = false, bool SP2 = false>
; __device__ __forceinline__ void gemm_phase(PG8_LAS unsigned char* lds, const Gemm g, const Sched& S, const Epi& E) {
;     ...
;         if constexpr (ALIGN_EPI) { if (wr == 0) PG8_BAR; }
	s_and_b64 vcc, exec, s[8:9]
	s_cbranch_vccz .LBB0_1335
	s_barrier

; #define PG8_STAGE(bufoff, gbase, voff) do { _Pragma("unroll") for (int _i = 0; _i < 2; ++_i) \
;         __builtin_amdgcn_global_load_lds((const unsigned*)((const char*)(gbase) + (voff)[_i]), (PG8_LAS unsigned*)(lds + (bufoff) + ldsw + _i * 8192), 16, 0, 0); } while (0)
; #define PG8_LDA(dst, b, h) do { _Pragma("unroll") for (int m = 0; m < 4; ++m) _Pragma("unroll") for (int k = 0; k < 2; ++k) dst[m][k] = *(const PG8_LAS bf16x8*)(lds + PG8_SA(b, h) + aoff + m * 2048 + k * 1024); } while (0)
; #define PG8_LDB(dst, b, h) do { _Pragma("unroll") for (int n = 0; n < 2; ++n) _Pragma("unroll") for (int k = 0; k < 2; ++k) dst[n][k] = *(const PG8_LAS bf16x8*)(lds + PG8_SB(b, h) + boff + n * 2048 + k * 1024); } while (0)
; #define PG8_MMA(ai, bj, At, Bt) do { __builtin_amdgcn_s_setprio(1); _Pragma("unroll") for (int m = 0; m < 4; ++m) _Pragma("unroll") for (int n = 0; n < 2; ++n) _Pragma("unroll") for (int k = 0; k < 2; ++k) \
;         acc[ai][bj][m][n] = __builtin_amdgcn_mfma_f32_16x16x32_bf16(Bt[n][k], At[m][k], acc[ai][bj][m][n], 0, 0, 0); __builtin_amdgcn_s_setprio(0); } while (0)
; #define PG8_WAIT_V(n) asm volatile("s_waitcnt vmcnt(" #n ")" ::: "memory")
; #define PG8_WAIT_L(n) asm volatile("s_waitcnt lgkmcnt(" #n ")" ::: "memory")
; #define PG8_BAR __builtin_amdgcn_s_barrier()
; #define PG8_SCHED __builtin_amdgcn_sched_barrier(0)
; template <class Epi, class Sched, bool ALIGN_EPI = false, bool SP2 = false>
; __device__ __forceinline__ void gemm_phase(PG8_LAS unsigned char* lds, const Gemm g, const Sched& S, const Epi& E) {
;     ...
;             PG8_LDB(B0, 0, 0); PG8_LDB(B1, 0, 1); PG8_SCHED; PG8_LDA(At, 0, 0); PG8_STAGE(PG8_SA(1, 1), a1 + hstep, voffA);
;             PG8_WAIT_V(8); PG8_WAIT_L(0); PG8_BAR; PG8_MMA(0, 0, At, B0); PG8_MMA(0, 1, At, B1); PG8_BAR; PG8_SCHED;
;             PG8_LDA(At, 0, 1); PG8_STAGE(PG8_SB(0, 0), b2, voffB); PG8_STAGE(PG8_SB(0, 1), b2 + hstep, voffB); PG8_STAGE(PG8_SA(0, 0), a2, voffA);
;             PG8_WAIT_V(8); PG8_WAIT_L(0); PG8_BAR; PG8_MMA(1, 0, At, B0); PG8_MMA(1, 1, At, B1); PG8_BAR; PG8_SCHED;
.LBB0_1595:
	ds_read_b128 v[130:133], v241 offset:0
	ds_read_b128 v[134:137], v241 offset:1024
	ds_read_b128 v[138:141], v241 offset:2048
	ds_read_b128 v[142:145], v241 offset:3072
	ds_read_b128 v[146:149], v241 offset:16384
	ds_read_b128 v[150:153], v241 offset:17408
	ds_read_b128 v[172:175], v241 offset:18432
	ds_read_b128 v[176:179], v241 offset:19456
	s_add_u32 s24, s26, 0xfff00080
	s_addc_u32 s25, s27, -1
	s_cmp_eq_u32 s62, 60
	s_cselect_b32 s29, s15, s25
	s_cselect_b32 s28, s21, s24
	s_cselect_b32 s25, s13, s53
	s_cselect_b32 s24, s51, s52
	s_add_i32 m0, s23, 0xc000
	ds_read_b128 v[180:183], v185
	ds_read_b128 v[188:191], v185 offset:1024
	ds_read_b128 v[192:195], v185 offset:2048
	ds_read_b128 v[196:199], v185 offset:3072
	ds_read_b128 v[200:203], v185 offset:4096
	ds_read_b128 v[204:207], v185 offset:5120
	ds_read_b128 v[208:211], v185 offset:6144
	global_load_lds_dwordx4 v162, s[26:27]
	s_add_i32 m0, s23, 0xe000
	ds_read_b128 v[212:215], v185 offset:7168
	global_load_lds_dwordx4 v166, s[26:27]
	s_waitcnt vmcnt(8) lgkmcnt(0)
	s_barrier
	v_mfma_f32_16x16x32_bf16 v[114:117], v[130:133], v[180:183], v[114:117]
	v_mfma_f32_16x16x32_bf16 v[118:121], v[138:141], v[180:183], v[118:121]
	v_mfma_f32_16x16x32_bf16 v[106:109], v[130:133], v[192:195], v[106:109]
	v_mfma_f32_16x16x32_bf16 v[98:101], v[138:141], v[192:195], v[98:101]
	v_mfma_f32_16x16x32_bf16 v[90:93], v[130:133], v[200:203], v[90:93]
	v_mfma_f32_16x16x32_bf16 v[82:85], v[138:141], v[200:203], v[82:85]
	v_mfma_f32_16x16x32_bf16 v[74:77], v[130:133], v[208:211], v[74:77]
	v_mfma_f32_16x16x32_bf16 v[66:69], v[138:141], v[208:211], v[66:69]
	v_mfma_f32_16x16x32_bf16 v[114:117], v[134:137], v[188:191], v[114:117]
	v_mfma_f32_16x16x32_bf16 v[118:121], v[142:145], v[188:191], v[118:121]
	v_mfma_f32_16x16x32_bf16 v[106:109], v[134:137], v[196:199], v[106:109]
	v_mfma_f32_16x16x32_bf16 v[98:101], v[142:145], v[196:199], v[98:101]
	v_mfma_f32_16x16x32_bf16 v[90:93], v[134:137], v[204:207], v[90:93]
	v_mfma_f32_16x16x32_bf16 v[82:85], v[142:145], v[204:207], v[82:85]
	v_mfma_f32_16x16x32_bf16 v[74:77], v[134:137], v[212:215], v[74:77]
	v_mfma_f32_16x16x32_bf16 v[66:69], v[142:145], v[212:215], v[66:69]
	v_mfma_f32_16x16x32_bf16 v[122:125], v[146:149], v[180:183], v[122:125]
	v_mfma_f32_16x16x32_bf16 v[126:129], v[172:175], v[180:183], v[126:129]
	v_mfma_f32_16x16x32_bf16 v[110:113], v[146:149], v[192:195], v[110:113]
	v_mfma_f32_16x16x32_bf16 v[102:105], v[172:175], v[192:195], v[102:105]
	v_mfma_f32_16x16x32_bf16 v[94:97], v[146:149], v[200:203], v[94:97]
	v_mfma_f32_16x16x32_bf16 v[86:89], v[172:175], v[200:203], v[86:89]
	v_mfma_f32_16x16x32_bf16 v[78:81], v[146:149], v[208:211], v[78:81]
	v_mfma_f32_16x16x32_bf16 v[70:73], v[172:175], v[208:211], v[70:73]
	v_mfma_f32_16x16x32_bf16 v[122:125], v[150:153], v[188:191], v[122:125]
	v_mfma_f32_16x16x32_bf16 v[126:129], v[176:179], v[188:191], v[126:129]
	v_mfma_f32_16x16x32_bf16 v[110:113], v[150:153], v[196:199], v[110:113]
	v_mfma_f32_16x16x32_bf16 v[102:105], v[176:179], v[196:199], v[102:105]
	v_mfma_f32_16x16x32_bf16 v[94:97], v[150:153], v[204:207], v[94:97]
	v_mfma_f32_16x16x32_bf16 v[86:89], v[176:179], v[204:207], v[86:89]
	v_mfma_f32_16x16x32_bf16 v[78:81], v[150:153], v[212:215], v[78:81]
	v_mfma_f32_16x16x32_bf16 v[70:73], v[176:179], v[212:215], v[70:73]
	s_barrier
	s_add_i32 s33, s48, s36
	s_mov_b32 m0, s33
	ds_read_b128 v[180:183], v185 offset:16384
	ds_read_b128 v[188:191], v185 offset:17408
	ds_read_b128 v[192:195], v185 offset:18432
	ds_read_b128 v[196:199], v185 offset:19456
	ds_read_b128 v[200:203], v185 offset:20480
	global_load_lds_dwordx4 v156, s[24:25]
	s_add_i32 m0, s33, 0x2000
	s_add_u32 s64, s24, 0x100000
	s_addc_u32 s65, s25, 0
	s_add_i32 s33, s49, s36
	global_load_lds_dwordx4 v160, s[24:25]
	s_mov_b32 m0, s33
	s_add_u32 s100, s28, 0x80
	s_addc_u32 s101, s29, 0
	global_load_lds_dwordx4 v156, s[64:65]
	s_add_i32 m0, s33, 0x2000
	ds_read_b128 v[212:215], v185 offset:23552
	global_load_lds_dwordx4 v160, s[64:65]
	s_mov_b32 m0, s23
	ds_read_b128 v[208:211], v185 offset:22528
	global_load_lds_dwordx4 v154, s[28:29]
	s_mov_b32 m0, s37
	ds_read_b128 v[204:207], v185 offset:21504
	global_load_lds_dwordx4 v158, s[28:29]
	s_waitcnt vmcnt(8) lgkmcnt(0)
	s_barrier
	v_mfma_f32_16x16x32_bf16 v[58:61], v[130:133], v[180:183], v[58:61]
	v_mfma_f32_16x16x32_bf16 v[54:57], v[138:141], v[180:183], v[54:57]
	v_mfma_f32_16x16x32_bf16 v[42:45], v[130:133], v[192:195], v[42:45]
	v_mfma_f32_16x16x32_bf16 v[34:37], v[138:141], v[192:195], v[34:37]
	v_mfma_f32_16x16x32_bf16 v[26:29], v[130:133], v[200:203], v[26:29]
	v_mfma_f32_16x16x32_bf16 v[18:21], v[138:141], v[200:203], v[18:21]
	v_mfma_f32_16x16x32_bf16 v[6:9], v[130:133], v[208:211], v[6:9]
	v_mfma_f32_16x16x32_bf16 v[2:5], v[138:141], v[208:211], v[2:5]
	v_mfma_f32_16x16x32_bf16 v[58:61], v[134:137], v[188:191], v[58:61]
	v_mfma_f32_16x16x32_bf16 v[54:57], v[142:145], v[188:191], v[54:57]
	v_mfma_f32_16x16x32_bf16 v[42:45], v[134:137], v[196:199], v[42:45]
	v_mfma_f32_16x16x32_bf16 v[34:37], v[142:145], v[196:199], v[34:37]
	v_mfma_f32_16x16x32_bf16 v[26:29], v[134:137], v[204:207], v[26:29]
	v_mfma_f32_16x16x32_bf16 v[18:21], v[142:145], v[204:207], v[18:21]
	v_mfma_f32_16x16x32_bf16 v[6:9], v[134:137], v[212:215], v[6:9]
	v_mfma_f32_16x16x32_bf16 v[2:5], v[142:145], v[212:215], v[2:5]
	v_mfma_f32_16x16x32_bf16 v[62:65], v[146:149], v[180:183], v[62:65]
	v_mfma_f32_16x16x32_bf16 v[50:53], v[172:175], v[180:183], v[50:53]
	v_mfma_f32_16x16x32_bf16 v[46:49], v[146:149], v[192:195], v[46:49]
	v_mfma_f32_16x16x32_bf16 v[38:41], v[172:175], v[192:195], v[38:41]
	v_mfma_f32_16x16x32_bf16 v[30:33], v[146:149], v[200:203], v[30:33]
	v_mfma_f32_16x16x32_bf16 v[22:25], v[172:175], v[200:203], v[22:25]
	v_mfma_f32_16x16x32_bf16 v[10:13], v[146:149], v[208:211], v[10:13]
	v_mfma_f32_16x16x32_bf16 v[14:17], v[172:175], v[208:211], v[14:17]
	v_mfma_f32_16x16x32_bf16 v[62:65], v[150:153], v[188:191], v[62:65]
	v_mfma_f32_16x16x32_bf16 v[50:53], v[176:179], v[188:191], v[50:53]
	v_mfma_f32_16x16x32_bf16 v[46:49], v[150:153], v[196:199], v[46:49]
	v_mfma_f32_16x16x32_bf16 v[38:41], v[176:179], v[196:199], v[38:41]
	v_mfma_f32_16x16x32_bf16 v[30:33], v[150:153], v[204:207], v[30:33]
	v_mfma_f32_16x16x32_bf16 v[22:25], v[176:179], v[204:207], v[22:25]
	v_mfma_f32_16x16x32_bf16 v[10:13], v[150:153], v[212:215], v[10:13]
	v_mfma_f32_16x16x32_bf16 v[14:17], v[176:179], v[212:215], v[14:17]
	s_barrier
; #define PG8_STAGE(bufoff, gbase, voff) do { _Pragma("unroll") for (int _i = 0; _i < 2; ++_i) \
;         __builtin_amdgcn_global_load_lds((const unsigned*)((const char*)(gbase) + (voff)[_i]), (PG8_LAS unsigned*)(lds + (bufoff) + ldsw + _i * 8192), 16, 0, 0); } while (0)
; #define PG8_LDA(dst, b, h) do { _Pragma("unroll") for (int m = 0; m < 4; ++m) _Pragma("unroll") for (int k = 0; k < 2; ++k) dst[m][k] = *(const PG8_LAS bf16x8*)(lds + PG8_SA(b, h) + aoff + m * 2048 + k * 1024); } while (0)
; #define PG8_LDB(dst, b, h) do { _Pragma("unroll") for (int n = 0; n < 2; ++n) _Pragma("unroll") for (int k = 0; k < 2; ++k) dst[n][k] = *(const PG8_LAS bf16x8*)(lds + PG8_SB(b, h) + boff + n * 2048 + k * 1024); } while (0)
; #define PG8_MMA(ai, bj, At, Bt) do { __builtin_amdgcn_s_setprio(1); _Pragma("unroll") for (int m = 0; m < 4; ++m) _Pragma("unroll") for (int n = 0; n < 2; ++n) _Pragma("unroll") for (int k = 0; k < 2; ++k) \
;         acc[ai][bj][m][n] = __builtin_amdgcn_mfma_f32_16x16x32_bf16(Bt[n][k], At[m][k], acc[ai][bj][m][n], 0, 0, 0); __builtin_amdgcn_s_setprio(0); } while (0)
; #define PG8_WAIT_V(n) asm volatile("s_waitcnt vmcnt(" #n ")" ::: "memory")
; #define PG8_WAIT_L(n) asm volatile("s_waitcnt lgkmcnt(" #n ")" ::: "memory")
; #define PG8_BAR __builtin_amdgcn_s_barrier()
; #define PG8_SCHED __builtin_amdgcn_sched_barrier(0)
; template <class Epi, class Sched, bool ALIGN_EPI = false, bool SP2 = false>
; __device__ __forceinline__ void gemm_phase(PG8_LAS unsigned char* lds, const Gemm g, const Sched& S, const Epi& E) {
;     ...
;             PG8_LDB(B0, 1, 0); PG8_LDB(B1, 1, 1); PG8_SCHED; PG8_LDA(At, 1, 0); PG8_STAGE(PG8_SA(0, 1), a2 + hstep, voffA);
;             PG8_WAIT_V(8); PG8_WAIT_L(0); PG8_BAR; PG8_MMA(0, 0, At, B0); PG8_MMA(0, 1, At, B1); PG8_BAR; PG8_SCHED;
;             PG8_LDA(At, 1, 1); PG8_STAGE(PG8_SB(1, 0), b3, voffB); PG8_STAGE(PG8_SB(1, 1), b3 + hstep, voffB); PG8_STAGE(PG8_SA(1, 0), a3, voffA);
;             PG8_WAIT_V(8); PG8_WAIT_L(0); PG8_BAR; PG8_MMA(1, 0, At, B0); PG8_MMA(1, 1, At, B1); PG8_BAR; PG8_SCHED;
	s_add_i32 s33, 0, 0x18000
	s_add_i32 s42, 0, 0x1c000
	ds_read_b128 v[130:133], v241 offset:32768
	ds_read_b128 v[134:137], v241 offset:33792
	ds_read_b128 v[138:141], v241 offset:34816
	ds_read_b128 v[142:145], v241 offset:35840
	ds_read_b128 v[146:149], v241 offset:49152
	ds_read_b128 v[150:153], v241 offset:50176
	ds_read_b128 v[172:175], v241 offset:51200
	ds_read_b128 v[176:179], v241 offset:52224
	s_add_u32 s28, s28, 0x100000
	s_addc_u32 s29, s29, 0
	s_mov_b32 m0, s40
	ds_read_b128 v[180:183], v185 offset:32768
	ds_read_b128 v[188:191], v185 offset:33792
	ds_read_b128 v[192:195], v185 offset:34816
	ds_read_b128 v[196:199], v185 offset:35840
	ds_read_b128 v[200:203], v185 offset:36864
	ds_read_b128 v[204:207], v185 offset:37888
	ds_read_b128 v[208:211], v185 offset:38912
	global_load_lds_dwordx4 v154, s[28:29]
	s_mov_b32 m0, s41
	ds_read_b128 v[212:215], v185 offset:39936
	global_load_lds_dwordx4 v158, s[28:29]
	s_waitcnt vmcnt(8) lgkmcnt(0)
	s_barrier
	v_mfma_f32_16x16x32_bf16 v[114:117], v[130:133], v[180:183], v[114:117]
	v_mfma_f32_16x16x32_bf16 v[118:121], v[138:141], v[180:183], v[118:121]
	v_mfma_f32_16x16x32_bf16 v[106:109], v[130:133], v[192:195], v[106:109]
	v_mfma_f32_16x16x32_bf16 v[98:101], v[138:141], v[192:195], v[98:101]
	v_mfma_f32_16x16x32_bf16 v[90:93], v[130:133], v[200:203], v[90:93]
	v_mfma_f32_16x16x32_bf16 v[82:85], v[138:141], v[200:203], v[82:85]
	v_mfma_f32_16x16x32_bf16 v[74:77], v[130:133], v[208:211], v[74:77]
	v_mfma_f32_16x16x32_bf16 v[66:69], v[138:141], v[208:211], v[66:69]
	v_mfma_f32_16x16x32_bf16 v[114:117], v[134:137], v[188:191], v[114:117]
	v_mfma_f32_16x16x32_bf16 v[118:121], v[142:145], v[188:191], v[118:121]
	v_mfma_f32_16x16x32_bf16 v[106:109], v[134:137], v[196:199], v[106:109]
	v_mfma_f32_16x16x32_bf16 v[98:101], v[142:145], v[196:199], v[98:101]
	v_mfma_f32_16x16x32_bf16 v[90:93], v[134:137], v[204:207], v[90:93]
	v_mfma_f32_16x16x32_bf16 v[82:85], v[142:145], v[204:207], v[82:85]
	v_mfma_f32_16x16x32_bf16 v[74:77], v[134:137], v[212:215], v[74:77]
	v_mfma_f32_16x16x32_bf16 v[66:69], v[142:145], v[212:215], v[66:69]
	v_mfma_f32_16x16x32_bf16 v[122:125], v[146:149], v[180:183], v[122:125]
	v_mfma_f32_16x16x32_bf16 v[126:129], v[172:175], v[180:183], v[126:129]
	v_mfma_f32_16x16x32_bf16 v[110:113], v[146:149], v[192:195], v[110:113]
	v_mfma_f32_16x16x32_bf16 v[102:105], v[172:175], v[192:195], v[102:105]
	v_mfma_f32_16x16x32_bf16 v[94:97], v[146:149], v[200:203], v[94:97]
	v_mfma_f32_16x16x32_bf16 v[86:89], v[172:175], v[200:203], v[86:89]
	v_mfma_f32_16x16x32_bf16 v[78:81], v[146:149], v[208:211], v[78:81]
	v_mfma_f32_16x16x32_bf16 v[70:73], v[172:175], v[208:211], v[70:73]
	v_mfma_f32_16x16x32_bf16 v[122:125], v[150:153], v[188:191], v[122:125]
	v_mfma_f32_16x16x32_bf16 v[126:129], v[176:179], v[188:191], v[126:129]
	v_mfma_f32_16x16x32_bf16 v[110:113], v[150:153], v[196:199], v[110:113]
	v_mfma_f32_16x16x32_bf16 v[102:105], v[176:179], v[196:199], v[102:105]
	v_mfma_f32_16x16x32_bf16 v[94:97], v[150:153], v[204:207], v[94:97]
	v_mfma_f32_16x16x32_bf16 v[86:89], v[176:179], v[204:207], v[86:89]
	v_mfma_f32_16x16x32_bf16 v[78:81], v[150:153], v[212:215], v[78:81]
	v_mfma_f32_16x16x32_bf16 v[70:73], v[176:179], v[212:215], v[70:73]
	s_barrier
	s_add_i32 s28, s33, s36
	s_add_i32 m0, s28, 0xffffff80
	ds_read_b128 v[180:183], v185 offset:49152
	ds_read_b128 v[188:191], v185 offset:50176
	ds_read_b128 v[192:195], v185 offset:51200
	ds_read_b128 v[196:199], v185 offset:52224
	global_load_lds_dwordx4 v156, s[24:25] offset:128
	s_add_i32 m0, s28, 0x1f80
	s_add_i32 s28, s42, s36
	global_load_lds_dwordx4 v160, s[24:25] offset:128
	s_add_u32 s24, s24, 0x100080
	s_addc_u32 s25, s25, 0
	s_mov_b32 m0, s28
	ds_read_b128 v[212:215], v185 offset:56320
	global_load_lds_dwordx4 v156, s[24:25]
	s_add_i32 m0, s28, 0x2000
	ds_read_b128 v[208:211], v185 offset:55296
	global_load_lds_dwordx4 v160, s[24:25]
	s_mov_b32 m0, s44
	ds_read_b128 v[204:207], v185 offset:54272
	global_load_lds_dwordx4 v154, s[100:101]
	s_mov_b32 m0, s45
	ds_read_b128 v[200:203], v185 offset:53248
	global_load_lds_dwordx4 v158, s[100:101]
	s_waitcnt vmcnt(8) lgkmcnt(0)
	s_barrier
	v_mfma_f32_16x16x32_bf16 v[58:61], v[130:133], v[180:183], v[58:61]
	v_mfma_f32_16x16x32_bf16 v[54:57], v[138:141], v[180:183], v[54:57]
	v_mfma_f32_16x16x32_bf16 v[42:45], v[130:133], v[192:195], v[42:45]
	v_mfma_f32_16x16x32_bf16 v[34:37], v[138:141], v[192:195], v[34:37]
	v_mfma_f32_16x16x32_bf16 v[26:29], v[130:133], v[200:203], v[26:29]
	v_mfma_f32_16x16x32_bf16 v[18:21], v[138:141], v[200:203], v[18:21]
	v_mfma_f32_16x16x32_bf16 v[6:9], v[130:133], v[208:211], v[6:9]
	v_mfma_f32_16x16x32_bf16 v[2:5], v[138:141], v[208:211], v[2:5]
	v_mfma_f32_16x16x32_bf16 v[58:61], v[134:137], v[188:191], v[58:61]
	v_mfma_f32_16x16x32_bf16 v[54:57], v[142:145], v[188:191], v[54:57]
	v_mfma_f32_16x16x32_bf16 v[42:45], v[134:137], v[196:199], v[42:45]
	v_mfma_f32_16x16x32_bf16 v[34:37], v[142:145], v[196:199], v[34:37]
	v_mfma_f32_16x16x32_bf16 v[26:29], v[134:137], v[204:207], v[26:29]
	v_mfma_f32_16x16x32_bf16 v[18:21], v[142:145], v[204:207], v[18:21]
	v_mfma_f32_16x16x32_bf16 v[6:9], v[134:137], v[212:215], v[6:9]
	v_mfma_f32_16x16x32_bf16 v[2:5], v[142:145], v[212:215], v[2:5]
	v_mfma_f32_16x16x32_bf16 v[62:65], v[146:149], v[180:183], v[62:65]
	v_mfma_f32_16x16x32_bf16 v[50:53], v[172:175], v[180:183], v[50:53]
	v_mfma_f32_16x16x32_bf16 v[46:49], v[146:149], v[192:195], v[46:49]
	v_mfma_f32_16x16x32_bf16 v[38:41], v[172:175], v[192:195], v[38:41]
	v_mfma_f32_16x16x32_bf16 v[30:33], v[146:149], v[200:203], v[30:33]
	v_mfma_f32_16x16x32_bf16 v[22:25], v[172:175], v[200:203], v[22:25]
	v_mfma_f32_16x16x32_bf16 v[10:13], v[146:149], v[208:211], v[10:13]
	v_mfma_f32_16x16x32_bf16 v[14:17], v[172:175], v[208:211], v[14:17]
	v_mfma_f32_16x16x32_bf16 v[62:65], v[150:153], v[188:191], v[62:65]
	v_mfma_f32_16x16x32_bf16 v[50:53], v[176:179], v[188:191], v[50:53]
	v_mfma_f32_16x16x32_bf16 v[46:49], v[150:153], v[196:199], v[46:49]
	v_mfma_f32_16x16x32_bf16 v[38:41], v[176:179], v[196:199], v[38:41]
	v_mfma_f32_16x16x32_bf16 v[30:33], v[150:153], v[204:207], v[30:33]
	v_mfma_f32_16x16x32_bf16 v[22:25], v[176:179], v[204:207], v[22:25]
	v_mfma_f32_16x16x32_bf16 v[10:13], v[150:153], v[212:215], v[10:13]
	v_mfma_f32_16x16x32_bf16 v[14:17], v[176:179], v[212:215], v[14:17]
	s_barrier
	s_add_i32 s62, s62, 2
	s_add_u32 s26, s26, 0x100
	s_addc_u32 s27, s27, 0
	s_add_u32 s52, s52, 0x100
	s_addc_u32 s53, s53, 0
	s_cmp_gt_u32 s62, 61
	s_cbranch_scc0 .LBB0_1595


; #define PG8_BAR __builtin_amdgcn_s_barrier()
; template <class Epi, class Sched, bool ALIGN_EPI = false, bool SP2 = false>
; __device__ __forceinline__ void gemm_phase(PG8_LAS unsigned char* lds, const Gemm g, const Sched& S, const Epi& E) {
;     ...
;         if constexpr (ALIGN_EPI) { if (wr == 0) PG8_BAR; }
	s_and_b64 vcc, exec, s[10:11]
	s_cbranch_vccz .LBB0_1598
	s_barrier

; #define PG8_STAGE(bufoff, gbase, voff) do { _Pragma("unroll") for (int _i = 0; _i < 2; ++_i) \
;         __builtin_amdgcn_global_load_lds((const unsigned*)((const char*)(gbase) + (voff)[_i]), (PG8_LAS unsigned*)(lds + (bufoff) + ldsw + _i * 8192), 16, 0, 0); } while (0)
; #define PG8_LDA(dst, b, h) do { _Pragma("unroll") for (int m = 0; m < 4; ++m) _Pragma("unroll") for (int k = 0; k < 2; ++k) dst[m][k] = *(const PG8_LAS bf16x8*)(lds + PG8_SA(b, h) + aoff + m * 2048 + k * 1024); } while (0)
; #define PG8_LDB(dst, b, h) do { _Pragma("unroll") for (int n = 0; n < 2; ++n) _Pragma("unroll") for (int k = 0; k < 2; ++k) dst[n][k] = *(const PG8_LAS bf16x8*)(lds + PG8_SB(b, h) + boff + n * 2048 + k * 1024); } while (0)
; #define PG8_MMA(ai, bj, At, Bt) do { __builtin_amdgcn_s_setprio(1); _Pragma("unroll") for (int m = 0; m < 4; ++m) _Pragma("unroll") for (int n = 0; n < 2; ++n) _Pragma("unroll") for (int k = 0; k < 2; ++k) \
;         acc[ai][bj][m][n] = __builtin_amdgcn_mfma_f32_16x16x32_bf16(Bt[n][k], At[m][k], acc[ai][bj][m][n], 0, 0, 0); __builtin_amdgcn_s_setprio(0); } while (0)
; #define PG8_WAIT_V(n) asm volatile("s_waitcnt vmcnt(" #n ")" ::: "memory")
; #define PG8_WAIT_L(n) asm volatile("s_waitcnt lgkmcnt(" #n ")" ::: "memory")
; #define PG8_BAR __builtin_amdgcn_s_barrier()
; #define PG8_SCHED __builtin_amdgcn_sched_barrier(0)
; template <class Epi, class Sched, bool ALIGN_EPI = false, bool SP2 = false>
; __device__ __forceinline__ void gemm_phase(PG8_LAS unsigned char* lds, const Gemm g, const Sched& S, const Epi& E) {
;     ...
;             PG8_LDB(B0, 0, 0); PG8_LDB(B1, 0, 1); PG8_SCHED; PG8_LDA(At, 0, 0); PG8_STAGE(PG8_SA(1, 1), a1 + hstep, voffA);
;             PG8_WAIT_V(8); PG8_WAIT_L(0); PG8_BAR; PG8_MMA(0, 0, At, B0); PG8_MMA(0, 1, At, B1); PG8_BAR; PG8_SCHED;
;             PG8_LDA(At, 0, 1); PG8_STAGE(PG8_SB(0, 0), b2, voffB); PG8_STAGE(PG8_SB(0, 1), b2 + hstep, voffB); PG8_STAGE(PG8_SA(0, 0), a2, voffA);
;             PG8_WAIT_V(8); PG8_WAIT_L(0); PG8_BAR; PG8_MMA(1, 0, At, B0); PG8_MMA(1, 1, At, B1); PG8_BAR; PG8_SCHED;
.LBB0_1681:
	ds_read_b128 v[160:163], v241 offset:0
	ds_read_b128 v[166:169], v241 offset:1024
	ds_read_b128 v[170:173], v241 offset:2048
	ds_read_b128 v[174:177], v241 offset:3072
	ds_read_b128 v[178:181], v241 offset:16384
	ds_read_b128 v[182:185], v241 offset:17408
	ds_read_b128 v[186:189], v241 offset:18432
	ds_read_b128 v[190:193], v241 offset:19456
	s_add_u32 s22, s24, 0xfff00080
	s_addc_u32 s23, s25, -1
	s_cmp_eq_u32 s52, 60
	s_cselect_b32 s27, s15, s23
	s_cselect_b32 s26, s48, s22
	s_cselect_b32 s23, s13, s51
	s_cselect_b32 s22, s49, s50
	s_add_i32 m0, s21, 0xc000
	ds_read_b128 v[194:197], v155
	ds_read_b128 v[198:201], v155 offset:1024
	ds_read_b128 v[202:205], v155 offset:2048
	ds_read_b128 v[206:209], v155 offset:3072
	ds_read_b128 v[210:213], v155 offset:4096
	ds_read_b128 v[214:217], v155 offset:5120
	ds_read_b128 v[218:221], v155 offset:6144
	global_load_lds_dwordx4 v138, s[24:25]
	s_add_i32 m0, s21, 0xe000
	ds_read_b128 v[222:225], v155 offset:7168
	global_load_lds_dwordx4 v140, s[24:25]
	s_waitcnt vmcnt(8) lgkmcnt(0)
	s_barrier
	v_mfma_f32_16x16x32_bf16 v[122:125], v[160:163], v[194:197], v[122:125]
	v_mfma_f32_16x16x32_bf16 v[114:117], v[170:173], v[194:197], v[114:117]
	v_mfma_f32_16x16x32_bf16 v[106:109], v[160:163], v[202:205], v[106:109]
	v_mfma_f32_16x16x32_bf16 v[98:101], v[170:173], v[202:205], v[98:101]
	v_mfma_f32_16x16x32_bf16 v[90:93], v[160:163], v[210:213], v[90:93]
	v_mfma_f32_16x16x32_bf16 v[82:85], v[170:173], v[210:213], v[82:85]
	v_mfma_f32_16x16x32_bf16 v[74:77], v[160:163], v[218:221], v[74:77]
	v_mfma_f32_16x16x32_bf16 v[62:65], v[170:173], v[218:221], v[62:65]
	v_mfma_f32_16x16x32_bf16 v[122:125], v[166:169], v[198:201], v[122:125]
	v_mfma_f32_16x16x32_bf16 v[114:117], v[174:177], v[198:201], v[114:117]
	v_mfma_f32_16x16x32_bf16 v[106:109], v[166:169], v[206:209], v[106:109]
	v_mfma_f32_16x16x32_bf16 v[98:101], v[174:177], v[206:209], v[98:101]
	v_mfma_f32_16x16x32_bf16 v[90:93], v[166:169], v[214:217], v[90:93]
	v_mfma_f32_16x16x32_bf16 v[82:85], v[174:177], v[214:217], v[82:85]
	v_mfma_f32_16x16x32_bf16 v[74:77], v[166:169], v[222:225], v[74:77]
	v_mfma_f32_16x16x32_bf16 v[62:65], v[174:177], v[222:225], v[62:65]
	v_mfma_f32_16x16x32_bf16 v[126:129], v[178:181], v[194:197], v[126:129]
	v_mfma_f32_16x16x32_bf16 v[118:121], v[186:189], v[194:197], v[118:121]
	v_mfma_f32_16x16x32_bf16 v[110:113], v[178:181], v[202:205], v[110:113]
	v_mfma_f32_16x16x32_bf16 v[102:105], v[186:189], v[202:205], v[102:105]
	v_mfma_f32_16x16x32_bf16 v[94:97], v[178:181], v[210:213], v[94:97]
	v_mfma_f32_16x16x32_bf16 v[86:89], v[186:189], v[210:213], v[86:89]
	v_mfma_f32_16x16x32_bf16 v[78:81], v[178:181], v[218:221], v[78:81]
	v_mfma_f32_16x16x32_bf16 v[70:73], v[186:189], v[218:221], v[70:73]
	v_mfma_f32_16x16x32_bf16 v[126:129], v[182:185], v[198:201], v[126:129]
	v_mfma_f32_16x16x32_bf16 v[118:121], v[190:193], v[198:201], v[118:121]
	v_mfma_f32_16x16x32_bf16 v[110:113], v[182:185], v[206:209], v[110:113]
	v_mfma_f32_16x16x32_bf16 v[102:105], v[190:193], v[206:209], v[102:105]
	v_mfma_f32_16x16x32_bf16 v[94:97], v[182:185], v[214:217], v[94:97]
	v_mfma_f32_16x16x32_bf16 v[86:89], v[190:193], v[214:217], v[86:89]
	v_mfma_f32_16x16x32_bf16 v[78:81], v[182:185], v[222:225], v[78:81]
	v_mfma_f32_16x16x32_bf16 v[70:73], v[190:193], v[222:225], v[70:73]
	s_barrier
	s_add_i32 s33, s44, s29
	s_mov_b32 m0, s33
	ds_read_b128 v[194:197], v155 offset:16384
	ds_read_b128 v[198:201], v155 offset:17408
	ds_read_b128 v[202:205], v155 offset:18432
	ds_read_b128 v[206:209], v155 offset:19456
	ds_read_b128 v[210:213], v155 offset:20480
	global_load_lds_dwordx4 v132, s[22:23]
	s_add_i32 m0, s33, 0x2000
	s_add_u32 s62, s22, 0x100000
	s_addc_u32 s63, s23, 0
	s_add_i32 s33, s45, s29
	global_load_lds_dwordx4 v136, s[22:23]
	s_mov_b32 m0, s33
	s_add_u32 s100, s26, 0x80
	s_addc_u32 s101, s27, 0
	global_load_lds_dwordx4 v132, s[62:63]
	s_add_i32 m0, s33, 0x2000
	ds_read_b128 v[222:225], v155 offset:23552
	global_load_lds_dwordx4 v136, s[62:63]
	s_mov_b32 m0, s21
	ds_read_b128 v[218:221], v155 offset:22528
	global_load_lds_dwordx4 v130, s[26:27]
	s_mov_b32 m0, s34
	ds_read_b128 v[214:217], v155 offset:21504
	global_load_lds_dwordx4 v134, s[26:27]
	s_waitcnt vmcnt(8) lgkmcnt(0)
	s_barrier
	v_mfma_f32_16x16x32_bf16 v[58:61], v[160:163], v[194:197], v[58:61]
	v_mfma_f32_16x16x32_bf16 v[50:53], v[170:173], v[194:197], v[50:53]
	v_mfma_f32_16x16x32_bf16 v[42:45], v[160:163], v[202:205], v[42:45]
	v_mfma_f32_16x16x32_bf16 v[34:37], v[170:173], v[202:205], v[34:37]
	v_mfma_f32_16x16x32_bf16 v[26:29], v[160:163], v[210:213], v[26:29]
	v_mfma_f32_16x16x32_bf16 v[18:21], v[170:173], v[210:213], v[18:21]
	v_mfma_f32_16x16x32_bf16 v[10:13], v[160:163], v[218:221], v[10:13]
	v_mfma_f32_16x16x32_bf16 v[2:5], v[170:173], v[218:221], v[2:5]
	v_mfma_f32_16x16x32_bf16 v[58:61], v[166:169], v[198:201], v[58:61]
	v_mfma_f32_16x16x32_bf16 v[50:53], v[174:177], v[198:201], v[50:53]
	v_mfma_f32_16x16x32_bf16 v[42:45], v[166:169], v[206:209], v[42:45]
	v_mfma_f32_16x16x32_bf16 v[34:37], v[174:177], v[206:209], v[34:37]
	v_mfma_f32_16x16x32_bf16 v[26:29], v[166:169], v[214:217], v[26:29]
	v_mfma_f32_16x16x32_bf16 v[18:21], v[174:177], v[214:217], v[18:21]
	v_mfma_f32_16x16x32_bf16 v[10:13], v[166:169], v[222:225], v[10:13]
	v_mfma_f32_16x16x32_bf16 v[2:5], v[174:177], v[222:225], v[2:5]
	v_mfma_f32_16x16x32_bf16 v[66:69], v[178:181], v[194:197], v[66:69]
	v_mfma_f32_16x16x32_bf16 v[54:57], v[186:189], v[194:197], v[54:57]
	v_mfma_f32_16x16x32_bf16 v[46:49], v[178:181], v[202:205], v[46:49]
	v_mfma_f32_16x16x32_bf16 v[38:41], v[186:189], v[202:205], v[38:41]
	v_mfma_f32_16x16x32_bf16 v[30:33], v[178:181], v[210:213], v[30:33]
	v_mfma_f32_16x16x32_bf16 v[22:25], v[186:189], v[210:213], v[22:25]
	v_mfma_f32_16x16x32_bf16 v[14:17], v[178:181], v[218:221], v[14:17]
	v_mfma_f32_16x16x32_bf16 v[6:9], v[186:189], v[218:221], v[6:9]
	v_mfma_f32_16x16x32_bf16 v[66:69], v[182:185], v[198:201], v[66:69]
	v_mfma_f32_16x16x32_bf16 v[54:57], v[190:193], v[198:201], v[54:57]
	v_mfma_f32_16x16x32_bf16 v[46:49], v[182:185], v[206:209], v[46:49]
	v_mfma_f32_16x16x32_bf16 v[38:41], v[190:193], v[206:209], v[38:41]
	v_mfma_f32_16x16x32_bf16 v[30:33], v[182:185], v[214:217], v[30:33]
	v_mfma_f32_16x16x32_bf16 v[22:25], v[190:193], v[214:217], v[22:25]
	v_mfma_f32_16x16x32_bf16 v[14:17], v[182:185], v[222:225], v[14:17]
	v_mfma_f32_16x16x32_bf16 v[6:9], v[190:193], v[222:225], v[6:9]
	s_barrier
; #define PG8_STAGE(bufoff, gbase, voff) do { _Pragma("unroll") for (int _i = 0; _i < 2; ++_i) \
;         __builtin_amdgcn_global_load_lds((const unsigned*)((const char*)(gbase) + (voff)[_i]), (PG8_LAS unsigned*)(lds + (bufoff) + ldsw + _i * 8192), 16, 0, 0); } while (0)
; #define PG8_LDA(dst, b, h) do { _Pragma("unroll") for (int m = 0; m < 4; ++m) _Pragma("unroll") for (int k = 0; k < 2; ++k) dst[m][k] = *(const PG8_LAS bf16x8*)(lds + PG8_SA(b, h) + aoff + m * 2048 + k * 1024); } while (0)
; #define PG8_LDB(dst, b, h) do { _Pragma("unroll") for (int n = 0; n < 2; ++n) _Pragma("unroll") for (int k = 0; k < 2; ++k) dst[n][k] = *(const PG8_LAS bf16x8*)(lds + PG8_SB(b, h) + boff + n * 2048 + k * 1024); } while (0)
; #define PG8_MMA(ai, bj, At, Bt) do { __builtin_amdgcn_s_setprio(1); _Pragma("unroll") for (int m = 0; m < 4; ++m) _Pragma("unroll") for (int n = 0; n < 2; ++n) _Pragma("unroll") for (int k = 0; k < 2; ++k) \
;         acc[ai][bj][m][n] = __builtin_amdgcn_mfma_f32_16x16x32_bf16(Bt[n][k], At[m][k], acc[ai][bj][m][n], 0, 0, 0); __builtin_amdgcn_s_setprio(0); } while (0)
; #define PG8_WAIT_V(n) asm volatile("s_waitcnt vmcnt(" #n ")" ::: "memory")
; #define PG8_WAIT_L(n) asm volatile("s_waitcnt lgkmcnt(" #n ")" ::: "memory")
; #define PG8_BAR __builtin_amdgcn_s_barrier()
; #define PG8_SCHED __builtin_amdgcn_sched_barrier(0)
; template <class Epi, class Sched, bool ALIGN_EPI = false, bool SP2 = false>
; __device__ __forceinline__ void gemm_phase(PG8_LAS unsigned char* lds, const Gemm g, const Sched& S, const Epi& E) {
;     ...
;             PG8_LDB(B0, 1, 0); PG8_LDB(B1, 1, 1); PG8_SCHED; PG8_LDA(At, 1, 0); PG8_STAGE(PG8_SA(0, 1), a2 + hstep, voffA);
;             PG8_WAIT_V(8); PG8_WAIT_L(0); PG8_BAR; PG8_MMA(0, 0, At, B0); PG8_MMA(0, 1, At, B1); PG8_BAR; PG8_SCHED;
;             PG8_LDA(At, 1, 1); PG8_STAGE(PG8_SB(1, 0), b3, voffB); PG8_STAGE(PG8_SB(1, 1), b3 + hstep, voffB); PG8_STAGE(PG8_SA(1, 0), a3, voffA);
;             PG8_WAIT_V(8); PG8_WAIT_L(0); PG8_BAR; PG8_MMA(1, 0, At, B0); PG8_MMA(1, 1, At, B1); PG8_BAR; PG8_SCHED;
	s_add_i32 s33, 0, 0x18000
	s_add_i32 s42, 0, 0x1c000
	ds_read_b128 v[160:163], v241 offset:32768
	ds_read_b128 v[166:169], v241 offset:33792
	ds_read_b128 v[170:173], v241 offset:34816
	ds_read_b128 v[174:177], v241 offset:35840
	ds_read_b128 v[178:181], v241 offset:49152
	ds_read_b128 v[182:185], v241 offset:50176
	ds_read_b128 v[186:189], v241 offset:51200
	ds_read_b128 v[190:193], v241 offset:52224
	s_add_u32 s26, s26, 0x100000
	s_addc_u32 s27, s27, 0
	s_mov_b32 m0, s35
	ds_read_b128 v[194:197], v155 offset:32768
	ds_read_b128 v[198:201], v155 offset:33792
	ds_read_b128 v[202:205], v155 offset:34816
	ds_read_b128 v[206:209], v155 offset:35840
	ds_read_b128 v[210:213], v155 offset:36864
	ds_read_b128 v[214:217], v155 offset:37888
	ds_read_b128 v[218:221], v155 offset:38912
	global_load_lds_dwordx4 v130, s[26:27]
	s_mov_b32 m0, s36
	ds_read_b128 v[222:225], v155 offset:39936
	global_load_lds_dwordx4 v134, s[26:27]
	s_waitcnt vmcnt(8) lgkmcnt(0)
	s_barrier
	v_mfma_f32_16x16x32_bf16 v[122:125], v[160:163], v[194:197], v[122:125]
	v_mfma_f32_16x16x32_bf16 v[114:117], v[170:173], v[194:197], v[114:117]
	v_mfma_f32_16x16x32_bf16 v[106:109], v[160:163], v[202:205], v[106:109]
	v_mfma_f32_16x16x32_bf16 v[98:101], v[170:173], v[202:205], v[98:101]
	v_mfma_f32_16x16x32_bf16 v[90:93], v[160:163], v[210:213], v[90:93]
	v_mfma_f32_16x16x32_bf16 v[82:85], v[170:173], v[210:213], v[82:85]
	v_mfma_f32_16x16x32_bf16 v[74:77], v[160:163], v[218:221], v[74:77]
	v_mfma_f32_16x16x32_bf16 v[62:65], v[170:173], v[218:221], v[62:65]
	v_mfma_f32_16x16x32_bf16 v[122:125], v[166:169], v[198:201], v[122:125]
	v_mfma_f32_16x16x32_bf16 v[114:117], v[174:177], v[198:201], v[114:117]
	v_mfma_f32_16x16x32_bf16 v[106:109], v[166:169], v[206:209], v[106:109]
	v_mfma_f32_16x16x32_bf16 v[98:101], v[174:177], v[206:209], v[98:101]
	v_mfma_f32_16x16x32_bf16 v[90:93], v[166:169], v[214:217], v[90:93]
	v_mfma_f32_16x16x32_bf16 v[82:85], v[174:177], v[214:217], v[82:85]
	v_mfma_f32_16x16x32_bf16 v[74:77], v[166:169], v[222:225], v[74:77]
	v_mfma_f32_16x16x32_bf16 v[62:65], v[174:177], v[222:225], v[62:65]
	v_mfma_f32_16x16x32_bf16 v[126:129], v[178:181], v[194:197], v[126:129]
	v_mfma_f32_16x16x32_bf16 v[118:121], v[186:189], v[194:197], v[118:121]
	v_mfma_f32_16x16x32_bf16 v[110:113], v[178:181], v[202:205], v[110:113]
	v_mfma_f32_16x16x32_bf16 v[102:105], v[186:189], v[202:205], v[102:105]
	v_mfma_f32_16x16x32_bf16 v[94:97], v[178:181], v[210:213], v[94:97]
	v_mfma_f32_16x16x32_bf16 v[86:89], v[186:189], v[210:213], v[86:89]
	v_mfma_f32_16x16x32_bf16 v[78:81], v[178:181], v[218:221], v[78:81]
	v_mfma_f32_16x16x32_bf16 v[70:73], v[186:189], v[218:221], v[70:73]
	v_mfma_f32_16x16x32_bf16 v[126:129], v[182:185], v[198:201], v[126:129]
	v_mfma_f32_16x16x32_bf16 v[118:121], v[190:193], v[198:201], v[118:121]
	v_mfma_f32_16x16x32_bf16 v[110:113], v[182:185], v[206:209], v[110:113]
	v_mfma_f32_16x16x32_bf16 v[102:105], v[190:193], v[206:209], v[102:105]
	v_mfma_f32_16x16x32_bf16 v[94:97], v[182:185], v[214:217], v[94:97]
	v_mfma_f32_16x16x32_bf16 v[86:89], v[190:193], v[214:217], v[86:89]
	v_mfma_f32_16x16x32_bf16 v[78:81], v[182:185], v[222:225], v[78:81]
	v_mfma_f32_16x16x32_bf16 v[70:73], v[190:193], v[222:225], v[70:73]
	s_barrier
	s_add_i32 s26, s33, s29
	s_add_i32 m0, s26, 0xffffff80
	ds_read_b128 v[194:197], v155 offset:49152
	ds_read_b128 v[198:201], v155 offset:50176
	ds_read_b128 v[202:205], v155 offset:51200
	ds_read_b128 v[206:209], v155 offset:52224
	global_load_lds_dwordx4 v132, s[22:23] offset:128
	s_add_i32 m0, s26, 0x1f80
	s_add_i32 s26, s42, s29
	global_load_lds_dwordx4 v136, s[22:23] offset:128
	s_add_u32 s22, s22, 0x100080
	s_addc_u32 s23, s23, 0
	s_mov_b32 m0, s26
	ds_read_b128 v[222:225], v155 offset:56320
	global_load_lds_dwordx4 v132, s[22:23]
	s_add_i32 m0, s26, 0x2000
	ds_read_b128 v[218:221], v155 offset:55296
	global_load_lds_dwordx4 v136, s[22:23]
	s_mov_b32 m0, s41
	ds_read_b128 v[214:217], v155 offset:54272
	global_load_lds_dwordx4 v130, s[100:101]
	s_mov_b32 m0, s43
	ds_read_b128 v[210:213], v155 offset:53248
	global_load_lds_dwordx4 v134, s[100:101]
	s_waitcnt vmcnt(8) lgkmcnt(0)
	s_barrier
	v_mfma_f32_16x16x32_bf16 v[58:61], v[160:163], v[194:197], v[58:61]
	v_mfma_f32_16x16x32_bf16 v[50:53], v[170:173], v[194:197], v[50:53]
	v_mfma_f32_16x16x32_bf16 v[42:45], v[160:163], v[202:205], v[42:45]
	v_mfma_f32_16x16x32_bf16 v[34:37], v[170:173], v[202:205], v[34:37]
	v_mfma_f32_16x16x32_bf16 v[26:29], v[160:163], v[210:213], v[26:29]
	v_mfma_f32_16x16x32_bf16 v[18:21], v[170:173], v[210:213], v[18:21]
	v_mfma_f32_16x16x32_bf16 v[10:13], v[160:163], v[218:221], v[10:13]
	v_mfma_f32_16x16x32_bf16 v[2:5], v[170:173], v[218:221], v[2:5]
	v_mfma_f32_16x16x32_bf16 v[58:61], v[166:169], v[198:201], v[58:61]
	v_mfma_f32_16x16x32_bf16 v[50:53], v[174:177], v[198:201], v[50:53]
	v_mfma_f32_16x16x32_bf16 v[42:45], v[166:169], v[206:209], v[42:45]
	v_mfma_f32_16x16x32_bf16 v[34:37], v[174:177], v[206:209], v[34:37]
	v_mfma_f32_16x16x32_bf16 v[26:29], v[166:169], v[214:217], v[26:29]
	v_mfma_f32_16x16x32_bf16 v[18:21], v[174:177], v[214:217], v[18:21]
	v_mfma_f32_16x16x32_bf16 v[10:13], v[166:169], v[222:225], v[10:13]
	v_mfma_f32_16x16x32_bf16 v[2:5], v[174:177], v[222:225], v[2:5]
	v_mfma_f32_16x16x32_bf16 v[66:69], v[178:181], v[194:197], v[66:69]
	v_mfma_f32_16x16x32_bf16 v[54:57], v[186:189], v[194:197], v[54:57]
	v_mfma_f32_16x16x32_bf16 v[46:49], v[178:181], v[202:205], v[46:49]
	v_mfma_f32_16x16x32_bf16 v[38:41], v[186:189], v[202:205], v[38:41]
	v_mfma_f32_16x16x32_bf16 v[30:33], v[178:181], v[210:213], v[30:33]
	v_mfma_f32_16x16x32_bf16 v[22:25], v[186:189], v[210:213], v[22:25]
	v_mfma_f32_16x16x32_bf16 v[14:17], v[178:181], v[218:221], v[14:17]
	v_mfma_f32_16x16x32_bf16 v[6:9], v[186:189], v[218:221], v[6:9]
	v_mfma_f32_16x16x32_bf16 v[66:69], v[182:185], v[198:201], v[66:69]
	v_mfma_f32_16x16x32_bf16 v[54:57], v[190:193], v[198:201], v[54:57]
	v_mfma_f32_16x16x32_bf16 v[46:49], v[182:185], v[206:209], v[46:49]
	v_mfma_f32_16x16x32_bf16 v[38:41], v[190:193], v[206:209], v[38:41]
	v_mfma_f32_16x16x32_bf16 v[30:33], v[182:185], v[214:217], v[30:33]
	v_mfma_f32_16x16x32_bf16 v[22:25], v[190:193], v[214:217], v[22:25]
	v_mfma_f32_16x16x32_bf16 v[14:17], v[182:185], v[222:225], v[14:17]
	v_mfma_f32_16x16x32_bf16 v[6:9], v[190:193], v[222:225], v[6:9]
	s_barrier
	s_add_i32 s52, s52, 2
	s_add_u32 s24, s24, 0x100
	s_addc_u32 s25, s25, 0
	s_add_u32 s50, s50, 0x100
	s_addc_u32 s51, s51, 0
	s_cmp_gt_u32 s52, 61
	s_cbranch_scc0 .LBB0_1681


; #define PG8_BAR __builtin_amdgcn_s_barrier()
; template <class Epi, class Sched, bool ALIGN_EPI = false, bool SP2 = false>
; __device__ __forceinline__ void gemm_phase(PG8_LAS unsigned char* lds, const Gemm g, const Sched& S, const Epi& E) {
;     ...
;         if constexpr (ALIGN_EPI) { if (wr == 0) PG8_BAR; }
	s_and_b64 vcc, exec, s[8:9]
	s_cbranch_vccz .LBB0_1684
	s_barrier

; #define PG8_STAGE(bufoff, gbase, voff) do { _Pragma("unroll") for (int _i = 0; _i < 2; ++_i) \
;         __builtin_amdgcn_global_load_lds((const unsigned*)((const char*)(gbase) + (voff)[_i]), (PG8_LAS unsigned*)(lds + (bufoff) + ldsw + _i * 8192), 16, 0, 0); } while (0)
; #define PG8_LDA(dst, b, h) do { _Pragma("unroll") for (int m = 0; m < 4; ++m) _Pragma("unroll") for (int k = 0; k < 2; ++k) dst[m][k] = *(const PG8_LAS bf16x8*)(lds + PG8_SA(b, h) + aoff + m * 2048 + k * 1024); } while (0)
; #define PG8_LDB(dst, b, h) do { _Pragma("unroll") for (int n = 0; n < 2; ++n) _Pragma("unroll") for (int k = 0; k < 2; ++k) dst[n][k] = *(const PG8_LAS bf16x8*)(lds + PG8_SB(b, h) + boff + n * 2048 + k * 1024); } while (0)
; #define PG8_MMA(ai, bj, At, Bt) do { __builtin_amdgcn_s_setprio(1); _Pragma("unroll") for (int m = 0; m < 4; ++m) _Pragma("unroll") for (int n = 0; n < 2; ++n) _Pragma("unroll") for (int k = 0; k < 2; ++k) \
;         acc[ai][bj][m][n] = __builtin_amdgcn_mfma_f32_16x16x32_bf16(Bt[n][k], At[m][k], acc[ai][bj][m][n], 0, 0, 0); __builtin_amdgcn_s_setprio(0); } while (0)
; #define PG8_WAIT_V(n) asm volatile("s_waitcnt vmcnt(" #n ")" ::: "memory")
; #define PG8_WAIT_L(n) asm volatile("s_waitcnt lgkmcnt(" #n ")" ::: "memory")
; #define PG8_BAR __builtin_amdgcn_s_barrier()
; #define PG8_SCHED __builtin_amdgcn_sched_barrier(0)
; template <class Epi, class Sched, bool ALIGN_EPI = false, bool SP2 = false>
; __device__ __forceinline__ void gemm_phase(PG8_LAS unsigned char* lds, const Gemm g, const Sched& S, const Epi& E) {
;     ...
;             PG8_LDB(B0, 0, 0); PG8_LDB(B1, 0, 1); PG8_SCHED; PG8_LDA(At, 0, 0); PG8_STAGE(PG8_SA(1, 1), a1 + hstep, voffA);
;             PG8_WAIT_V(8); PG8_WAIT_L(0); PG8_BAR; PG8_MMA(0, 0, At, B0); PG8_MMA(0, 1, At, B1); PG8_BAR; PG8_SCHED;
;             PG8_LDA(At, 0, 1); PG8_STAGE(PG8_SB(0, 0), b2, voffB); PG8_STAGE(PG8_SB(0, 1), b2 + hstep, voffB); PG8_STAGE(PG8_SA(0, 0), a2, voffA);
;             PG8_WAIT_V(8); PG8_WAIT_L(0); PG8_BAR; PG8_MMA(1, 0, At, B0); PG8_MMA(1, 1, At, B1); PG8_BAR; PG8_SCHED;
.LBB0_1801:
	ds_read_b128 v[130:133], v241 offset:0
	ds_read_b128 v[134:137], v241 offset:1024
	ds_read_b128 v[138:141], v241 offset:2048
	ds_read_b128 v[142:145], v241 offset:3072
	ds_read_b128 v[146:149], v241 offset:16384
	ds_read_b128 v[150:153], v241 offset:17408
	ds_read_b128 v[170:173], v241 offset:18432
	ds_read_b128 v[174:177], v241 offset:19456
	s_add_u32 s16, s18, 0xffd50080
	s_addc_u32 s17, s19, -1
	s_cmpk_eq_i32 s48, 0xa8
	s_cselect_b32 s21, s5, s17
	s_cselect_b32 s20, s4, s16
	s_cselect_b32 s17, s15, s47
	s_cselect_b32 s16, s14, s46
	s_add_i32 m0, s25, 0xc000
	ds_read_b128 v[178:181], v184
	ds_read_b128 v[186:189], v184 offset:1024
	ds_read_b128 v[190:193], v184 offset:2048
	ds_read_b128 v[194:197], v184 offset:3072
	ds_read_b128 v[198:201], v184 offset:4096
	ds_read_b128 v[202:205], v184 offset:5120
	ds_read_b128 v[206:209], v184 offset:6144
	global_load_lds_dwordx4 v0, s[18:19]
	s_add_i32 m0, s25, 0xe000
	ds_read_b128 v[210:213], v184 offset:7168
	global_load_lds_dwordx4 v162, s[18:19]
	s_waitcnt vmcnt(8) lgkmcnt(0)
	s_barrier
	v_mfma_f32_16x16x32_bf16 v[114:117], v[130:133], v[178:181], v[114:117]
	v_mfma_f32_16x16x32_bf16 v[118:121], v[138:141], v[178:181], v[118:121]
	v_mfma_f32_16x16x32_bf16 v[106:109], v[130:133], v[190:193], v[106:109]
	v_mfma_f32_16x16x32_bf16 v[98:101], v[138:141], v[190:193], v[98:101]
	v_mfma_f32_16x16x32_bf16 v[90:93], v[130:133], v[198:201], v[90:93]
	v_mfma_f32_16x16x32_bf16 v[82:85], v[138:141], v[198:201], v[82:85]
	v_mfma_f32_16x16x32_bf16 v[74:77], v[130:133], v[206:209], v[74:77]
	v_mfma_f32_16x16x32_bf16 v[66:69], v[138:141], v[206:209], v[66:69]
	v_mfma_f32_16x16x32_bf16 v[114:117], v[134:137], v[186:189], v[114:117]
	v_mfma_f32_16x16x32_bf16 v[118:121], v[142:145], v[186:189], v[118:121]
	v_mfma_f32_16x16x32_bf16 v[106:109], v[134:137], v[194:197], v[106:109]
	v_mfma_f32_16x16x32_bf16 v[98:101], v[142:145], v[194:197], v[98:101]
	v_mfma_f32_16x16x32_bf16 v[90:93], v[134:137], v[202:205], v[90:93]
	v_mfma_f32_16x16x32_bf16 v[82:85], v[142:145], v[202:205], v[82:85]
	v_mfma_f32_16x16x32_bf16 v[74:77], v[134:137], v[210:213], v[74:77]
	v_mfma_f32_16x16x32_bf16 v[66:69], v[142:145], v[210:213], v[66:69]
	v_mfma_f32_16x16x32_bf16 v[122:125], v[146:149], v[178:181], v[122:125]
	v_mfma_f32_16x16x32_bf16 v[126:129], v[170:173], v[178:181], v[126:129]
	v_mfma_f32_16x16x32_bf16 v[110:113], v[146:149], v[190:193], v[110:113]
	v_mfma_f32_16x16x32_bf16 v[102:105], v[170:173], v[190:193], v[102:105]
	v_mfma_f32_16x16x32_bf16 v[94:97], v[146:149], v[198:201], v[94:97]
	v_mfma_f32_16x16x32_bf16 v[86:89], v[170:173], v[198:201], v[86:89]
	v_mfma_f32_16x16x32_bf16 v[78:81], v[146:149], v[206:209], v[78:81]
	v_mfma_f32_16x16x32_bf16 v[70:73], v[170:173], v[206:209], v[70:73]
	v_mfma_f32_16x16x32_bf16 v[122:125], v[150:153], v[186:189], v[122:125]
	v_mfma_f32_16x16x32_bf16 v[126:129], v[174:177], v[186:189], v[126:129]
	v_mfma_f32_16x16x32_bf16 v[110:113], v[150:153], v[194:197], v[110:113]
	v_mfma_f32_16x16x32_bf16 v[102:105], v[174:177], v[194:197], v[102:105]
	v_mfma_f32_16x16x32_bf16 v[94:97], v[150:153], v[202:205], v[94:97]
	v_mfma_f32_16x16x32_bf16 v[86:89], v[174:177], v[202:205], v[86:89]
	v_mfma_f32_16x16x32_bf16 v[78:81], v[150:153], v[210:213], v[78:81]
	v_mfma_f32_16x16x32_bf16 v[70:73], v[174:177], v[210:213], v[70:73]
	s_barrier
	s_add_i32 s33, s36, s24
	s_mov_b32 m0, s33
	ds_read_b128 v[178:181], v184 offset:16384
	ds_read_b128 v[186:189], v184 offset:17408
	ds_read_b128 v[190:193], v184 offset:18432
	ds_read_b128 v[194:197], v184 offset:19456
	ds_read_b128 v[198:201], v184 offset:20480
	global_load_lds_dwordx4 v156, s[16:17]
	s_add_i32 m0, s33, 0x2000
	s_add_u32 s50, s16, 0x2b0000
	s_addc_u32 s51, s17, 0
	s_add_i32 s33, s37, s24
	global_load_lds_dwordx4 v160, s[16:17]
	s_mov_b32 m0, s33
	s_add_u32 s100, s20, 0x80
	s_addc_u32 s101, s21, 0
	global_load_lds_dwordx4 v156, s[50:51]
	s_add_i32 m0, s33, 0x2000
	ds_read_b128 v[210:213], v184 offset:23552
	global_load_lds_dwordx4 v160, s[50:51]
	s_mov_b32 m0, s25
	ds_read_b128 v[206:209], v184 offset:22528
	global_load_lds_dwordx4 v154, s[20:21]
	s_mov_b32 m0, s26
	ds_read_b128 v[202:205], v184 offset:21504
	global_load_lds_dwordx4 v158, s[20:21]
	s_waitcnt vmcnt(8) lgkmcnt(0)
	s_barrier
	v_mfma_f32_16x16x32_bf16 v[58:61], v[130:133], v[178:181], v[58:61]
	v_mfma_f32_16x16x32_bf16 v[54:57], v[138:141], v[178:181], v[54:57]
	v_mfma_f32_16x16x32_bf16 v[42:45], v[130:133], v[190:193], v[42:45]
	v_mfma_f32_16x16x32_bf16 v[34:37], v[138:141], v[190:193], v[34:37]
	v_mfma_f32_16x16x32_bf16 v[26:29], v[130:133], v[198:201], v[26:29]
	v_mfma_f32_16x16x32_bf16 v[18:21], v[138:141], v[198:201], v[18:21]
	v_mfma_f32_16x16x32_bf16 v[6:9], v[130:133], v[206:209], v[6:9]
	v_mfma_f32_16x16x32_bf16 v[2:5], v[138:141], v[206:209], v[2:5]
	v_mfma_f32_16x16x32_bf16 v[58:61], v[134:137], v[186:189], v[58:61]
	v_mfma_f32_16x16x32_bf16 v[54:57], v[142:145], v[186:189], v[54:57]
	v_mfma_f32_16x16x32_bf16 v[42:45], v[134:137], v[194:197], v[42:45]
	v_mfma_f32_16x16x32_bf16 v[34:37], v[142:145], v[194:197], v[34:37]
	v_mfma_f32_16x16x32_bf16 v[26:29], v[134:137], v[202:205], v[26:29]
	v_mfma_f32_16x16x32_bf16 v[18:21], v[142:145], v[202:205], v[18:21]
	v_mfma_f32_16x16x32_bf16 v[6:9], v[134:137], v[210:213], v[6:9]
	v_mfma_f32_16x16x32_bf16 v[2:5], v[142:145], v[210:213], v[2:5]
	v_mfma_f32_16x16x32_bf16 v[62:65], v[146:149], v[178:181], v[62:65]
	v_mfma_f32_16x16x32_bf16 v[50:53], v[170:173], v[178:181], v[50:53]
	v_mfma_f32_16x16x32_bf16 v[46:49], v[146:149], v[190:193], v[46:49]
	v_mfma_f32_16x16x32_bf16 v[38:41], v[170:173], v[190:193], v[38:41]
	v_mfma_f32_16x16x32_bf16 v[30:33], v[146:149], v[198:201], v[30:33]
	v_mfma_f32_16x16x32_bf16 v[22:25], v[170:173], v[198:201], v[22:25]
	v_mfma_f32_16x16x32_bf16 v[10:13], v[146:149], v[206:209], v[10:13]
	v_mfma_f32_16x16x32_bf16 v[14:17], v[170:173], v[206:209], v[14:17]
	v_mfma_f32_16x16x32_bf16 v[62:65], v[150:153], v[186:189], v[62:65]
	v_mfma_f32_16x16x32_bf16 v[50:53], v[174:177], v[186:189], v[50:53]
	v_mfma_f32_16x16x32_bf16 v[46:49], v[150:153], v[194:197], v[46:49]
	v_mfma_f32_16x16x32_bf16 v[38:41], v[174:177], v[194:197], v[38:41]
	v_mfma_f32_16x16x32_bf16 v[30:33], v[150:153], v[202:205], v[30:33]
	v_mfma_f32_16x16x32_bf16 v[22:25], v[174:177], v[202:205], v[22:25]
	v_mfma_f32_16x16x32_bf16 v[10:13], v[150:153], v[210:213], v[10:13]
	v_mfma_f32_16x16x32_bf16 v[14:17], v[174:177], v[210:213], v[14:17]
	s_barrier
; #define PG8_STAGE(bufoff, gbase, voff) do { _Pragma("unroll") for (int _i = 0; _i < 2; ++_i) \
;         __builtin_amdgcn_global_load_lds((const unsigned*)((const char*)(gbase) + (voff)[_i]), (PG8_LAS unsigned*)(lds + (bufoff) + ldsw + _i * 8192), 16, 0, 0); } while (0)
; #define PG8_LDA(dst, b, h) do { _Pragma("unroll") for (int m = 0; m < 4; ++m) _Pragma("unroll") for (int k = 0; k < 2; ++k) dst[m][k] = *(const PG8_LAS bf16x8*)(lds + PG8_SA(b, h) + aoff + m * 2048 + k * 1024); } while (0)
; #define PG8_LDB(dst, b, h) do { _Pragma("unroll") for (int n = 0; n < 2; ++n) _Pragma("unroll") for (int k = 0; k < 2; ++k) dst[n][k] = *(const PG8_LAS bf16x8*)(lds + PG8_SB(b, h) + boff + n * 2048 + k * 1024); } while (0)
; #define PG8_MMA(ai, bj, At, Bt) do { __builtin_amdgcn_s_setprio(1); _Pragma("unroll") for (int m = 0; m < 4; ++m) _Pragma("unroll") for (int n = 0; n < 2; ++n) _Pragma("unroll") for (int k = 0; k < 2; ++k) \
;         acc[ai][bj][m][n] = __builtin_amdgcn_mfma_f32_16x16x32_bf16(Bt[n][k], At[m][k], acc[ai][bj][m][n], 0, 0, 0); __builtin_amdgcn_s_setprio(0); } while (0)
; #define PG8_WAIT_V(n) asm volatile("s_waitcnt vmcnt(" #n ")" ::: "memory")
; #define PG8_WAIT_L(n) asm volatile("s_waitcnt lgkmcnt(" #n ")" ::: "memory")
; #define PG8_BAR __builtin_amdgcn_s_barrier()
; #define PG8_SCHED __builtin_amdgcn_sched_barrier(0)
; template <class Epi, class Sched, bool ALIGN_EPI = false, bool SP2 = false>
; __device__ __forceinline__ void gemm_phase(PG8_LAS unsigned char* lds, const Gemm g, const Sched& S, const Epi& E) {
;     ...
;             PG8_LDB(B0, 1, 0); PG8_LDB(B1, 1, 1); PG8_SCHED; PG8_LDA(At, 1, 0); PG8_STAGE(PG8_SA(0, 1), a2 + hstep, voffA);
;             PG8_WAIT_V(8); PG8_WAIT_L(0); PG8_BAR; PG8_MMA(0, 0, At, B0); PG8_MMA(0, 1, At, B1); PG8_BAR; PG8_SCHED;
;             PG8_LDA(At, 1, 1); PG8_STAGE(PG8_SB(1, 0), b3, voffB); PG8_STAGE(PG8_SB(1, 1), b3 + hstep, voffB); PG8_STAGE(PG8_SA(1, 0), a3, voffA);
;             PG8_WAIT_V(8); PG8_WAIT_L(0); PG8_BAR; PG8_MMA(1, 0, At, B0); PG8_MMA(1, 1, At, B1); PG8_BAR; PG8_SCHED;
	s_add_i32 s33, 0, 0x18000
	s_add_i32 s42, 0, 0x1c000
	ds_read_b128 v[130:133], v241 offset:32768
	ds_read_b128 v[134:137], v241 offset:33792
	ds_read_b128 v[138:141], v241 offset:34816
	ds_read_b128 v[142:145], v241 offset:35840
	ds_read_b128 v[146:149], v241 offset:49152
	ds_read_b128 v[150:153], v241 offset:50176
	ds_read_b128 v[170:173], v241 offset:51200
	ds_read_b128 v[174:177], v241 offset:52224
	s_add_u32 s20, s20, 0x2b0000
	s_addc_u32 s21, s21, 0
	s_mov_b32 m0, s27
	ds_read_b128 v[178:181], v184 offset:32768
	ds_read_b128 v[186:189], v184 offset:33792
	ds_read_b128 v[190:193], v184 offset:34816
	ds_read_b128 v[194:197], v184 offset:35840
	ds_read_b128 v[198:201], v184 offset:36864
	ds_read_b128 v[202:205], v184 offset:37888
	ds_read_b128 v[206:209], v184 offset:38912
	global_load_lds_dwordx4 v154, s[20:21]
	s_mov_b32 m0, s28
	ds_read_b128 v[210:213], v184 offset:39936
	global_load_lds_dwordx4 v158, s[20:21]
	s_waitcnt vmcnt(8) lgkmcnt(0)
	s_barrier
	v_mfma_f32_16x16x32_bf16 v[114:117], v[130:133], v[178:181], v[114:117]
	v_mfma_f32_16x16x32_bf16 v[118:121], v[138:141], v[178:181], v[118:121]
	v_mfma_f32_16x16x32_bf16 v[106:109], v[130:133], v[190:193], v[106:109]
	v_mfma_f32_16x16x32_bf16 v[98:101], v[138:141], v[190:193], v[98:101]
	v_mfma_f32_16x16x32_bf16 v[90:93], v[130:133], v[198:201], v[90:93]
	v_mfma_f32_16x16x32_bf16 v[82:85], v[138:141], v[198:201], v[82:85]
	v_mfma_f32_16x16x32_bf16 v[74:77], v[130:133], v[206:209], v[74:77]
	v_mfma_f32_16x16x32_bf16 v[66:69], v[138:141], v[206:209], v[66:69]
	v_mfma_f32_16x16x32_bf16 v[114:117], v[134:137], v[186:189], v[114:117]
	v_mfma_f32_16x16x32_bf16 v[118:121], v[142:145], v[186:189], v[118:121]
	v_mfma_f32_16x16x32_bf16 v[106:109], v[134:137], v[194:197], v[106:109]
	v_mfma_f32_16x16x32_bf16 v[98:101], v[142:145], v[194:197], v[98:101]
	v_mfma_f32_16x16x32_bf16 v[90:93], v[134:137], v[202:205], v[90:93]
	v_mfma_f32_16x16x32_bf16 v[82:85], v[142:145], v[202:205], v[82:85]
	v_mfma_f32_16x16x32_bf16 v[74:77], v[134:137], v[210:213], v[74:77]
	v_mfma_f32_16x16x32_bf16 v[66:69], v[142:145], v[210:213], v[66:69]
	v_mfma_f32_16x16x32_bf16 v[122:125], v[146:149], v[178:181], v[122:125]
	v_mfma_f32_16x16x32_bf16 v[126:129], v[170:173], v[178:181], v[126:129]
	v_mfma_f32_16x16x32_bf16 v[110:113], v[146:149], v[190:193], v[110:113]
	v_mfma_f32_16x16x32_bf16 v[102:105], v[170:173], v[190:193], v[102:105]
	v_mfma_f32_16x16x32_bf16 v[94:97], v[146:149], v[198:201], v[94:97]
	v_mfma_f32_16x16x32_bf16 v[86:89], v[170:173], v[198:201], v[86:89]
	v_mfma_f32_16x16x32_bf16 v[78:81], v[146:149], v[206:209], v[78:81]
	v_mfma_f32_16x16x32_bf16 v[70:73], v[170:173], v[206:209], v[70:73]
	v_mfma_f32_16x16x32_bf16 v[122:125], v[150:153], v[186:189], v[122:125]
	v_mfma_f32_16x16x32_bf16 v[126:129], v[174:177], v[186:189], v[126:129]
	v_mfma_f32_16x16x32_bf16 v[110:113], v[150:153], v[194:197], v[110:113]
	v_mfma_f32_16x16x32_bf16 v[102:105], v[174:177], v[194:197], v[102:105]
	v_mfma_f32_16x16x32_bf16 v[94:97], v[150:153], v[202:205], v[94:97]
	v_mfma_f32_16x16x32_bf16 v[86:89], v[174:177], v[202:205], v[86:89]
	v_mfma_f32_16x16x32_bf16 v[78:81], v[150:153], v[210:213], v[78:81]
	v_mfma_f32_16x16x32_bf16 v[70:73], v[174:177], v[210:213], v[70:73]
	s_barrier
	s_add_i32 s20, s33, s24
	s_add_i32 m0, s20, 0xffffff80
	ds_read_b128 v[178:181], v184 offset:49152
	ds_read_b128 v[186:189], v184 offset:50176
	ds_read_b128 v[190:193], v184 offset:51200
	ds_read_b128 v[194:197], v184 offset:52224
	global_load_lds_dwordx4 v156, s[16:17] offset:128
	s_add_i32 m0, s20, 0x1f80
	s_add_i32 s20, s42, s24
	global_load_lds_dwordx4 v160, s[16:17] offset:128
	s_add_u32 s16, s16, 0x2b0080
	s_addc_u32 s17, s17, 0
	s_mov_b32 m0, s20
	ds_read_b128 v[210:213], v184 offset:56320
	global_load_lds_dwordx4 v156, s[16:17]
	s_add_i32 m0, s20, 0x2000
	ds_read_b128 v[206:209], v184 offset:55296
	global_load_lds_dwordx4 v160, s[16:17]
	s_mov_b32 m0, s30
	ds_read_b128 v[202:205], v184 offset:54272
	global_load_lds_dwordx4 v154, s[100:101]
	s_mov_b32 m0, s31
	ds_read_b128 v[198:201], v184 offset:53248
	global_load_lds_dwordx4 v158, s[100:101]
	s_waitcnt vmcnt(8) lgkmcnt(0)
	s_barrier
	v_mfma_f32_16x16x32_bf16 v[58:61], v[130:133], v[178:181], v[58:61]
	v_mfma_f32_16x16x32_bf16 v[54:57], v[138:141], v[178:181], v[54:57]
	v_mfma_f32_16x16x32_bf16 v[42:45], v[130:133], v[190:193], v[42:45]
	v_mfma_f32_16x16x32_bf16 v[34:37], v[138:141], v[190:193], v[34:37]
	v_mfma_f32_16x16x32_bf16 v[26:29], v[130:133], v[198:201], v[26:29]
	v_mfma_f32_16x16x32_bf16 v[18:21], v[138:141], v[198:201], v[18:21]
	v_mfma_f32_16x16x32_bf16 v[6:9], v[130:133], v[206:209], v[6:9]
	v_mfma_f32_16x16x32_bf16 v[2:5], v[138:141], v[206:209], v[2:5]
	v_mfma_f32_16x16x32_bf16 v[58:61], v[134:137], v[186:189], v[58:61]
	v_mfma_f32_16x16x32_bf16 v[54:57], v[142:145], v[186:189], v[54:57]
	v_mfma_f32_16x16x32_bf16 v[42:45], v[134:137], v[194:197], v[42:45]
	v_mfma_f32_16x16x32_bf16 v[34:37], v[142:145], v[194:197], v[34:37]
	v_mfma_f32_16x16x32_bf16 v[26:29], v[134:137], v[202:205], v[26:29]
	v_mfma_f32_16x16x32_bf16 v[18:21], v[142:145], v[202:205], v[18:21]
	v_mfma_f32_16x16x32_bf16 v[6:9], v[134:137], v[210:213], v[6:9]
	v_mfma_f32_16x16x32_bf16 v[2:5], v[142:145], v[210:213], v[2:5]
	v_mfma_f32_16x16x32_bf16 v[62:65], v[146:149], v[178:181], v[62:65]
	v_mfma_f32_16x16x32_bf16 v[50:53], v[170:173], v[178:181], v[50:53]
	v_mfma_f32_16x16x32_bf16 v[46:49], v[146:149], v[190:193], v[46:49]
	v_mfma_f32_16x16x32_bf16 v[38:41], v[170:173], v[190:193], v[38:41]
	v_mfma_f32_16x16x32_bf16 v[30:33], v[146:149], v[198:201], v[30:33]
	v_mfma_f32_16x16x32_bf16 v[22:25], v[170:173], v[198:201], v[22:25]
	v_mfma_f32_16x16x32_bf16 v[10:13], v[146:149], v[206:209], v[10:13]
	v_mfma_f32_16x16x32_bf16 v[14:17], v[170:173], v[206:209], v[14:17]
	v_mfma_f32_16x16x32_bf16 v[62:65], v[150:153], v[186:189], v[62:65]
	v_mfma_f32_16x16x32_bf16 v[50:53], v[174:177], v[186:189], v[50:53]
	v_mfma_f32_16x16x32_bf16 v[46:49], v[150:153], v[194:197], v[46:49]
	v_mfma_f32_16x16x32_bf16 v[38:41], v[174:177], v[194:197], v[38:41]
	v_mfma_f32_16x16x32_bf16 v[30:33], v[150:153], v[202:205], v[30:33]
	v_mfma_f32_16x16x32_bf16 v[22:25], v[174:177], v[202:205], v[22:25]
	v_mfma_f32_16x16x32_bf16 v[10:13], v[150:153], v[210:213], v[10:13]
	v_mfma_f32_16x16x32_bf16 v[14:17], v[174:177], v[210:213], v[14:17]
	s_barrier
	s_add_i32 s48, s48, 2
	s_add_u32 s18, s18, 0x100
	s_addc_u32 s19, s19, 0
	s_add_u32 s46, s46, 0x100
	s_addc_u32 s47, s47, 0
	s_cmpk_gt_u32 s48, 0xa9
	s_cbranch_scc0 .LBB0_1801


; #define PG8_BAR __builtin_amdgcn_s_barrier()
; template <class Epi, class Sched, bool ALIGN_EPI = false, bool SP2 = false>
; __device__ __forceinline__ void gemm_phase(PG8_LAS unsigned char* lds, const Gemm g, const Sched& S, const Epi& E) {
;     ...
;         if constexpr (ALIGN_EPI) { if (wr == 0) PG8_BAR; }
	s_and_b64 vcc, exec, s[12:13]
	s_cbranch_vccz .LBB0_1804
	s_barrier
